# hand-written NSA in-proj phase (P11) with light last-column tiles scheduled onto the 8-tile blocks
# baseline (speedup 1.0000x reference)
.LBB0_2401:
	s_cmp_gt_i32 s44, 11
	s_cselect_b64 s[2:3], -1, 0
	s_cmp_lt_i32 s45, 12
	s_cselect_b64 s[4:5], -1, 0
	s_or_b64 s[2:3], s[2:3], s[4:5]
	s_and_b64 vcc, exec, s[2:3]
	s_cbranch_vccnz .LBB0_3907
	s_mov_b32 s28, s22
	s_and_b32 s2, s42, 7
	s_cmp_lg_u32 s2, 0
	s_cbranch_scc1 .Lip11_vb
	s_and_b32 s2, s22, 7
	s_ashr_i32 s3, s42, 3
	s_mul_i32 s2, s3, s2
	s_ashr_i32 s3, s22, 3
	s_add_i32 s28, s2, s3
.Lip11_vb:
	s_load_dwordx2 s[4:5], s[0:1], 0x158
	s_load_dwordx2 s[6:7], s[0:1], 0x110
	v_mbcnt_hi_u32_b32 v234, -1, v210
	s_lshr_b32 s29, s70, 6
	s_lshl_b32 s27, s70, 4
	s_and_b32 s90, s70, 0x40
	v_and_b32_e32 v200, 48, v234
	v_or_b32_e32 v200, s90, v200
	v_and_b32_e32 v235, 31, v234
	v_lshrrev_b32_e32 v236, 5, v234
	v_bfe_u32 v237, v234, 1, 3
	v_lshlrev_b32_e32 v238, 7, v235
	s_lshr_b32 s91, s70, 7
	s_lshl_b32 s91, s91, 13
	s_and_b32 s31, s29, 1
	s_lshl_b32 s90, s90, 8
	s_add_u32 s90, s90, 0x8000
	v_xor_b32_e32 v239, v236, v237
	v_lshl_add_u32 v239, v239, 4, v238
	v_add_u32_e32 v184, s91, v239
	v_add_u32_e32 v188, s90, v239
	v_or_b32_e32 v239, 2, v236
	v_xor_b32_e32 v239, v239, v237
	v_lshl_add_u32 v239, v239, 4, v238
	v_add_u32_e32 v185, s91, v239
	v_add_u32_e32 v189, s90, v239
	v_or_b32_e32 v239, 4, v236
	v_xor_b32_e32 v239, v239, v237
	v_lshl_add_u32 v239, v239, 4, v238
	v_add_u32_e32 v186, s91, v239
	v_add_u32_e32 v190, s90, v239
	v_or_b32_e32 v239, 6, v236
	v_xor_b32_e32 v239, v239, v237
	v_lshl_add_u32 v239, v239, 4, v238
	v_add_u32_e32 v187, s91, v239
	v_add_u32_e32 v191, s90, v239
	v_lshrrev_b32_e32 v238, 3, v234
	s_lshl_b32 s96, s29, 3
	v_add_u32_e32 v238, s96, v238
	v_and_b32_e32 v239, 7, v234
	v_lshlrev_b32_e32 v239, 4, v239
	v_xor_b32_e32 v239, v200, v239
	v_lshl_add_u32 v192, v238, 11, v239
	v_mov_b32_e32 v193, 0
	v_add_u32_e32 v237, 64, v238
	v_lshl_add_u32 v194, v237, 11, v239
	v_mov_b32_e32 v195, 0
	v_add_u32_e32 v237, 128, v238
	v_lshl_add_u32 v196, v237, 11, v239
	v_mov_b32_e32 v197, 0
	v_add_u32_e32 v237, 192, v238
	v_lshl_add_u32 v198, v237, 11, v239
	v_mov_b32_e32 v199, 0
	s_mov_b32 s30, s28
	s_cmpk_ge_u32 s30, 0x780
	s_cbranch_scc1 .Lip11_done
	s_waitcnt lgkmcnt(0)
	s_mul_hi_u32 s35, s30, 0x92492493
	s_lshr_b32 s35, s35, 3
	s_mul_i32 s36, s35, 14
	s_sub_u32 s36, s30, s36
	s_sub_u32 s98, s30, 0x700
	s_cmpk_lt_u32 s30, 0x700
	s_cselect_b32 s36, s36, 14
	s_cselect_b32 s35, s35, s98
	s_lshl_b32 s98, s35, 19
	s_add_u32 s16, s4, s98
	s_addc_u32 s17, s5, 0
	s_lshl_b32 s98, s36, 19
	s_add_u32 s18, s6, s98
	s_addc_u32 s19, s7, 0
	s_add_u32 m0, s27, 0
	v_lshl_add_u64 v[152:153], v[192:193], 0, s[16:17]
	global_load_lds_dwordx4 v[152:153], off
	s_add_u32 m0, s27, 32768
	v_lshl_add_u64 v[154:155], v[192:193], 0, s[18:19]
	global_load_lds_dwordx4 v[154:155], off
	s_add_u32 m0, s27, 8192
	v_lshl_add_u64 v[156:157], v[194:195], 0, s[16:17]
	global_load_lds_dwordx4 v[156:157], off
	s_add_u32 m0, s27, 40960
	v_lshl_add_u64 v[152:153], v[194:195], 0, s[18:19]
	global_load_lds_dwordx4 v[152:153], off
	s_add_u32 m0, s27, 16384
	v_lshl_add_u64 v[154:155], v[196:197], 0, s[16:17]
	global_load_lds_dwordx4 v[154:155], off
	s_add_u32 m0, s27, 49152
	v_lshl_add_u64 v[156:157], v[196:197], 0, s[18:19]
	global_load_lds_dwordx4 v[156:157], off
	s_add_u32 m0, s27, 24576
	v_lshl_add_u64 v[152:153], v[198:199], 0, s[16:17]
	global_load_lds_dwordx4 v[152:153], off
	s_add_u32 m0, s27, 57344
	v_lshl_add_u64 v[154:155], v[198:199], 0, s[18:19]
	global_load_lds_dwordx4 v[154:155], off
.Lip11_tile:
	s_mul_hi_u32 s35, s30, 0x92492493
	s_lshr_b32 s35, s35, 3
	s_mul_i32 s36, s35, 14
	s_sub_u32 s36, s30, s36
	s_sub_u32 s98, s30, 0x700
	s_cmpk_lt_u32 s30, 0x700
	s_cselect_b32 s36, s36, 14
	s_cselect_b32 s35, s35, s98
	s_waitcnt vmcnt(0)
	s_barrier
	s_add_u32 s20, s16, 128
	s_addc_u32 s21, s17, 0
	s_add_u32 s24, s18, 128
	s_addc_u32 s25, s19, 0
	s_add_u32 m0, s27, 65536
	v_lshl_add_u64 v[152:153], v[192:193], 0, s[20:21]
	global_load_lds_dwordx4 v[152:153], off
	s_add_u32 m0, s27, 98304
	v_lshl_add_u64 v[154:155], v[192:193], 0, s[24:25]
	global_load_lds_dwordx4 v[154:155], off
	s_add_u32 m0, s27, 73728
	v_lshl_add_u64 v[156:157], v[194:195], 0, s[20:21]
	global_load_lds_dwordx4 v[156:157], off
	s_add_u32 m0, s27, 106496
	v_lshl_add_u64 v[152:153], v[194:195], 0, s[24:25]
	global_load_lds_dwordx4 v[152:153], off
	s_add_u32 m0, s27, 81920
	v_lshl_add_u64 v[154:155], v[196:197], 0, s[20:21]
	global_load_lds_dwordx4 v[154:155], off
	s_add_u32 m0, s27, 114688
	v_lshl_add_u64 v[156:157], v[196:197], 0, s[24:25]
	global_load_lds_dwordx4 v[156:157], off
	s_add_u32 m0, s27, 90112
	v_lshl_add_u64 v[152:153], v[198:199], 0, s[20:21]
	global_load_lds_dwordx4 v[152:153], off
	s_add_u32 m0, s27, 122880
	v_lshl_add_u64 v[154:155], v[198:199], 0, s[24:25]
	global_load_lds_dwordx4 v[154:155], off
	s_cmp_eq_u32 s36, 14
	s_cbranch_scc1 .Lip11_light
	ds_read_b128 v[160:163], v184
	ds_read_b128 v[168:171], v188
	ds_read_b128 v[164:167], v184 offset:4096
	ds_read_b128 v[172:175], v188 offset:4096
	ds_read_b128 v[176:179], v188 offset:8192
	ds_read_b128 v[180:183], v188 offset:12288
	ds_read_b128 v[128:131], v185
	ds_read_b128 v[136:139], v189
	ds_read_b128 v[132:135], v185 offset:4096
	ds_read_b128 v[140:143], v189 offset:4096
	ds_read_b128 v[144:147], v189 offset:8192
	ds_read_b128 v[148:151], v189 offset:12288
	s_waitcnt lgkmcnt(6)
	v_mfma_f32_32x32x16_bf16 v[112:127], v[160:163], v[168:171], 0
	v_mfma_f32_32x32x16_bf16 v[48:63], v[164:167], v[168:171], 0
	v_mfma_f32_32x32x16_bf16 v[96:111], v[160:163], v[172:175], 0
	v_mfma_f32_32x32x16_bf16 v[32:47], v[164:167], v[172:175], 0
	v_mfma_f32_32x32x16_bf16 v[80:95], v[160:163], v[176:179], 0
	v_mfma_f32_32x32x16_bf16 v[16:31], v[164:167], v[176:179], 0
	v_mfma_f32_32x32x16_bf16 v[64:79], v[160:163], v[180:183], 0
	v_mfma_f32_32x32x16_bf16 v[0:15], v[164:167], v[180:183], 0
	ds_read_b128 v[160:163], v186
	ds_read_b128 v[168:171], v190
	ds_read_b128 v[164:167], v186 offset:4096
	ds_read_b128 v[172:175], v190 offset:4096
	ds_read_b128 v[176:179], v190 offset:8192
	ds_read_b128 v[180:183], v190 offset:12288
	s_waitcnt lgkmcnt(6)
	v_mfma_f32_32x32x16_bf16 v[112:127], v[128:131], v[136:139], v[112:127]
	v_mfma_f32_32x32x16_bf16 v[48:63], v[132:135], v[136:139], v[48:63]
	v_mfma_f32_32x32x16_bf16 v[96:111], v[128:131], v[140:143], v[96:111]
	v_mfma_f32_32x32x16_bf16 v[32:47], v[132:135], v[140:143], v[32:47]
	v_mfma_f32_32x32x16_bf16 v[80:95], v[128:131], v[144:147], v[80:95]
	v_mfma_f32_32x32x16_bf16 v[16:31], v[132:135], v[144:147], v[16:31]
	v_mfma_f32_32x32x16_bf16 v[64:79], v[128:131], v[148:151], v[64:79]
	v_mfma_f32_32x32x16_bf16 v[0:15], v[132:135], v[148:151], v[0:15]
	ds_read_b128 v[128:131], v187
	ds_read_b128 v[136:139], v191
	ds_read_b128 v[132:135], v187 offset:4096
	ds_read_b128 v[140:143], v191 offset:4096
	ds_read_b128 v[144:147], v191 offset:8192
	ds_read_b128 v[148:151], v191 offset:12288
	s_waitcnt lgkmcnt(6)
	v_mfma_f32_32x32x16_bf16 v[112:127], v[160:163], v[168:171], v[112:127]
	v_mfma_f32_32x32x16_bf16 v[48:63], v[164:167], v[168:171], v[48:63]
	v_mfma_f32_32x32x16_bf16 v[96:111], v[160:163], v[172:175], v[96:111]
	v_mfma_f32_32x32x16_bf16 v[32:47], v[164:167], v[172:175], v[32:47]
	v_mfma_f32_32x32x16_bf16 v[80:95], v[160:163], v[176:179], v[80:95]
	v_mfma_f32_32x32x16_bf16 v[16:31], v[164:167], v[176:179], v[16:31]
	v_mfma_f32_32x32x16_bf16 v[64:79], v[160:163], v[180:183], v[64:79]
	v_mfma_f32_32x32x16_bf16 v[0:15], v[164:167], v[180:183], v[0:15]
	s_waitcnt vmcnt(0) lgkmcnt(0)
	s_barrier
	v_xor_b32_e32 v184, 0x10000, v184
	v_xor_b32_e32 v188, 0x10000, v188
	ds_read_b128 v[160:163], v184
	ds_read_b128 v[168:171], v188
	ds_read_b128 v[164:167], v184 offset:4096
	ds_read_b128 v[172:175], v188 offset:4096
	ds_read_b128 v[176:179], v188 offset:8192
	ds_read_b128 v[180:183], v188 offset:12288
	s_add_u32 s20, s16, 256
	s_addc_u32 s21, s17, 0
	s_add_u32 s24, s18, 256
	s_addc_u32 s25, s19, 0
	v_mfma_f32_32x32x16_bf16 v[112:127], v[128:131], v[136:139], v[112:127]
	v_xor_b32_e32 v185, 0x10000, v185
	v_xor_b32_e32 v189, 0x10000, v189
	s_add_u32 m0, s27, 0
	v_lshl_add_u64 v[152:153], v[192:193], 0, s[20:21]
	global_load_lds_dwordx4 v[152:153], off
	v_mfma_f32_32x32x16_bf16 v[48:63], v[132:135], v[136:139], v[48:63]
	v_xor_b32_e32 v186, 0x10000, v186
	v_xor_b32_e32 v190, 0x10000, v190
	s_add_u32 m0, s27, 32768
	v_lshl_add_u64 v[154:155], v[192:193], 0, s[24:25]
	global_load_lds_dwordx4 v[154:155], off
	v_mfma_f32_32x32x16_bf16 v[96:111], v[128:131], v[140:143], v[96:111]
	v_xor_b32_e32 v187, 0x10000, v187
	v_xor_b32_e32 v191, 0x10000, v191
	s_add_u32 m0, s27, 8192
	v_lshl_add_u64 v[156:157], v[194:195], 0, s[20:21]
	global_load_lds_dwordx4 v[156:157], off
	v_mfma_f32_32x32x16_bf16 v[32:47], v[132:135], v[140:143], v[32:47]
	s_add_u32 m0, s27, 40960
	v_lshl_add_u64 v[152:153], v[194:195], 0, s[24:25]
	global_load_lds_dwordx4 v[152:153], off
	v_mfma_f32_32x32x16_bf16 v[80:95], v[128:131], v[144:147], v[80:95]
	s_add_u32 m0, s27, 16384
	v_lshl_add_u64 v[154:155], v[196:197], 0, s[20:21]
	global_load_lds_dwordx4 v[154:155], off
	v_mfma_f32_32x32x16_bf16 v[16:31], v[132:135], v[144:147], v[16:31]
	s_add_u32 m0, s27, 49152
	v_lshl_add_u64 v[156:157], v[196:197], 0, s[24:25]
	global_load_lds_dwordx4 v[156:157], off
	v_mfma_f32_32x32x16_bf16 v[64:79], v[128:131], v[148:151], v[64:79]
	s_add_u32 m0, s27, 24576
	v_lshl_add_u64 v[152:153], v[198:199], 0, s[20:21]
	global_load_lds_dwordx4 v[152:153], off
	v_mfma_f32_32x32x16_bf16 v[0:15], v[132:135], v[148:151], v[0:15]
	s_add_u32 m0, s27, 57344
	v_lshl_add_u64 v[154:155], v[198:199], 0, s[24:25]
	global_load_lds_dwordx4 v[154:155], off
	ds_read_b128 v[128:131], v185
	ds_read_b128 v[136:139], v189
	ds_read_b128 v[132:135], v185 offset:4096
	ds_read_b128 v[140:143], v189 offset:4096
	ds_read_b128 v[144:147], v189 offset:8192
	ds_read_b128 v[148:151], v189 offset:12288
	s_waitcnt lgkmcnt(6)
	v_mfma_f32_32x32x16_bf16 v[112:127], v[160:163], v[168:171], v[112:127]
	v_mfma_f32_32x32x16_bf16 v[48:63], v[164:167], v[168:171], v[48:63]
	v_mfma_f32_32x32x16_bf16 v[96:111], v[160:163], v[172:175], v[96:111]
	v_mfma_f32_32x32x16_bf16 v[32:47], v[164:167], v[172:175], v[32:47]
	v_mfma_f32_32x32x16_bf16 v[80:95], v[160:163], v[176:179], v[80:95]
	v_mfma_f32_32x32x16_bf16 v[16:31], v[164:167], v[176:179], v[16:31]
	v_mfma_f32_32x32x16_bf16 v[64:79], v[160:163], v[180:183], v[64:79]
	v_mfma_f32_32x32x16_bf16 v[0:15], v[164:167], v[180:183], v[0:15]
	ds_read_b128 v[160:163], v186
	ds_read_b128 v[168:171], v190
	ds_read_b128 v[164:167], v186 offset:4096
	ds_read_b128 v[172:175], v190 offset:4096
	ds_read_b128 v[176:179], v190 offset:8192
	ds_read_b128 v[180:183], v190 offset:12288
	s_waitcnt lgkmcnt(6)
	v_mfma_f32_32x32x16_bf16 v[112:127], v[128:131], v[136:139], v[112:127]
	v_mfma_f32_32x32x16_bf16 v[48:63], v[132:135], v[136:139], v[48:63]
	v_mfma_f32_32x32x16_bf16 v[96:111], v[128:131], v[140:143], v[96:111]
	v_mfma_f32_32x32x16_bf16 v[32:47], v[132:135], v[140:143], v[32:47]
	v_mfma_f32_32x32x16_bf16 v[80:95], v[128:131], v[144:147], v[80:95]
	v_mfma_f32_32x32x16_bf16 v[16:31], v[132:135], v[144:147], v[16:31]
	v_mfma_f32_32x32x16_bf16 v[64:79], v[128:131], v[148:151], v[64:79]
	v_mfma_f32_32x32x16_bf16 v[0:15], v[132:135], v[148:151], v[0:15]
	ds_read_b128 v[128:131], v187
	ds_read_b128 v[136:139], v191
	ds_read_b128 v[132:135], v187 offset:4096
	ds_read_b128 v[140:143], v191 offset:4096
	ds_read_b128 v[144:147], v191 offset:8192
	ds_read_b128 v[148:151], v191 offset:12288
	s_waitcnt lgkmcnt(6)
	v_mfma_f32_32x32x16_bf16 v[112:127], v[160:163], v[168:171], v[112:127]
	v_mfma_f32_32x32x16_bf16 v[48:63], v[164:167], v[168:171], v[48:63]
	v_mfma_f32_32x32x16_bf16 v[96:111], v[160:163], v[172:175], v[96:111]
	v_mfma_f32_32x32x16_bf16 v[32:47], v[164:167], v[172:175], v[32:47]
	v_mfma_f32_32x32x16_bf16 v[80:95], v[160:163], v[176:179], v[80:95]
	v_mfma_f32_32x32x16_bf16 v[16:31], v[164:167], v[176:179], v[16:31]
	v_mfma_f32_32x32x16_bf16 v[64:79], v[160:163], v[180:183], v[64:79]
	v_mfma_f32_32x32x16_bf16 v[0:15], v[164:167], v[180:183], v[0:15]
	s_waitcnt vmcnt(0) lgkmcnt(0)
	s_barrier
	v_xor_b32_e32 v184, 0x10000, v184
	v_xor_b32_e32 v188, 0x10000, v188
	ds_read_b128 v[160:163], v184
	ds_read_b128 v[168:171], v188
	ds_read_b128 v[164:167], v184 offset:4096
	ds_read_b128 v[172:175], v188 offset:4096
	ds_read_b128 v[176:179], v188 offset:8192
	ds_read_b128 v[180:183], v188 offset:12288
	s_add_u32 s20, s16, 384
	s_addc_u32 s21, s17, 0
	s_add_u32 s24, s18, 384
	s_addc_u32 s25, s19, 0
	v_mfma_f32_32x32x16_bf16 v[112:127], v[128:131], v[136:139], v[112:127]
	v_xor_b32_e32 v185, 0x10000, v185
	v_xor_b32_e32 v189, 0x10000, v189
	s_add_u32 m0, s27, 65536
	v_lshl_add_u64 v[152:153], v[192:193], 0, s[20:21]
	global_load_lds_dwordx4 v[152:153], off
	v_mfma_f32_32x32x16_bf16 v[48:63], v[132:135], v[136:139], v[48:63]
	v_xor_b32_e32 v186, 0x10000, v186
	v_xor_b32_e32 v190, 0x10000, v190
	s_add_u32 m0, s27, 98304
	v_lshl_add_u64 v[154:155], v[192:193], 0, s[24:25]
	global_load_lds_dwordx4 v[154:155], off
	v_mfma_f32_32x32x16_bf16 v[96:111], v[128:131], v[140:143], v[96:111]
	v_xor_b32_e32 v187, 0x10000, v187
	v_xor_b32_e32 v191, 0x10000, v191
	s_add_u32 m0, s27, 73728
	v_lshl_add_u64 v[156:157], v[194:195], 0, s[20:21]
	global_load_lds_dwordx4 v[156:157], off
	v_mfma_f32_32x32x16_bf16 v[32:47], v[132:135], v[140:143], v[32:47]
	s_add_u32 m0, s27, 106496
	v_lshl_add_u64 v[152:153], v[194:195], 0, s[24:25]
	global_load_lds_dwordx4 v[152:153], off
	v_mfma_f32_32x32x16_bf16 v[80:95], v[128:131], v[144:147], v[80:95]
	s_add_u32 m0, s27, 81920
	v_lshl_add_u64 v[154:155], v[196:197], 0, s[20:21]
	global_load_lds_dwordx4 v[154:155], off
	v_mfma_f32_32x32x16_bf16 v[16:31], v[132:135], v[144:147], v[16:31]
	s_add_u32 m0, s27, 114688
	v_lshl_add_u64 v[156:157], v[196:197], 0, s[24:25]
	global_load_lds_dwordx4 v[156:157], off
	v_mfma_f32_32x32x16_bf16 v[64:79], v[128:131], v[148:151], v[64:79]
	s_add_u32 m0, s27, 90112
	v_lshl_add_u64 v[152:153], v[198:199], 0, s[20:21]
	global_load_lds_dwordx4 v[152:153], off
	v_mfma_f32_32x32x16_bf16 v[0:15], v[132:135], v[148:151], v[0:15]
	s_add_u32 m0, s27, 122880
	v_lshl_add_u64 v[154:155], v[198:199], 0, s[24:25]
	global_load_lds_dwordx4 v[154:155], off
	ds_read_b128 v[128:131], v185
	ds_read_b128 v[136:139], v189
	ds_read_b128 v[132:135], v185 offset:4096
	ds_read_b128 v[140:143], v189 offset:4096
	ds_read_b128 v[144:147], v189 offset:8192
	ds_read_b128 v[148:151], v189 offset:12288
	s_waitcnt lgkmcnt(6)
	v_mfma_f32_32x32x16_bf16 v[112:127], v[160:163], v[168:171], v[112:127]
	v_mfma_f32_32x32x16_bf16 v[48:63], v[164:167], v[168:171], v[48:63]
	v_mfma_f32_32x32x16_bf16 v[96:111], v[160:163], v[172:175], v[96:111]
	v_mfma_f32_32x32x16_bf16 v[32:47], v[164:167], v[172:175], v[32:47]
	v_mfma_f32_32x32x16_bf16 v[80:95], v[160:163], v[176:179], v[80:95]
	v_mfma_f32_32x32x16_bf16 v[16:31], v[164:167], v[176:179], v[16:31]
	v_mfma_f32_32x32x16_bf16 v[64:79], v[160:163], v[180:183], v[64:79]
	v_mfma_f32_32x32x16_bf16 v[0:15], v[164:167], v[180:183], v[0:15]
	ds_read_b128 v[160:163], v186
	ds_read_b128 v[168:171], v190
	ds_read_b128 v[164:167], v186 offset:4096
	ds_read_b128 v[172:175], v190 offset:4096
	ds_read_b128 v[176:179], v190 offset:8192
	ds_read_b128 v[180:183], v190 offset:12288
	s_waitcnt lgkmcnt(6)
	v_mfma_f32_32x32x16_bf16 v[112:127], v[128:131], v[136:139], v[112:127]
	v_mfma_f32_32x32x16_bf16 v[48:63], v[132:135], v[136:139], v[48:63]
	v_mfma_f32_32x32x16_bf16 v[96:111], v[128:131], v[140:143], v[96:111]
	v_mfma_f32_32x32x16_bf16 v[32:47], v[132:135], v[140:143], v[32:47]
	v_mfma_f32_32x32x16_bf16 v[80:95], v[128:131], v[144:147], v[80:95]
	v_mfma_f32_32x32x16_bf16 v[16:31], v[132:135], v[144:147], v[16:31]
	v_mfma_f32_32x32x16_bf16 v[64:79], v[128:131], v[148:151], v[64:79]
	v_mfma_f32_32x32x16_bf16 v[0:15], v[132:135], v[148:151], v[0:15]
	ds_read_b128 v[128:131], v187
	ds_read_b128 v[136:139], v191
	ds_read_b128 v[132:135], v187 offset:4096
	ds_read_b128 v[140:143], v191 offset:4096
	ds_read_b128 v[144:147], v191 offset:8192
	ds_read_b128 v[148:151], v191 offset:12288
	s_waitcnt lgkmcnt(6)
	v_mfma_f32_32x32x16_bf16 v[112:127], v[160:163], v[168:171], v[112:127]
	v_mfma_f32_32x32x16_bf16 v[48:63], v[164:167], v[168:171], v[48:63]
	v_mfma_f32_32x32x16_bf16 v[96:111], v[160:163], v[172:175], v[96:111]
	v_mfma_f32_32x32x16_bf16 v[32:47], v[164:167], v[172:175], v[32:47]
	v_mfma_f32_32x32x16_bf16 v[80:95], v[160:163], v[176:179], v[80:95]
	v_mfma_f32_32x32x16_bf16 v[16:31], v[164:167], v[176:179], v[16:31]
	v_mfma_f32_32x32x16_bf16 v[64:79], v[160:163], v[180:183], v[64:79]
	v_mfma_f32_32x32x16_bf16 v[0:15], v[164:167], v[180:183], v[0:15]
	s_waitcnt vmcnt(0) lgkmcnt(0)
	s_barrier
	v_xor_b32_e32 v184, 0x10000, v184
	v_xor_b32_e32 v188, 0x10000, v188
	ds_read_b128 v[160:163], v184
	ds_read_b128 v[168:171], v188
	ds_read_b128 v[164:167], v184 offset:4096
	ds_read_b128 v[172:175], v188 offset:4096
	ds_read_b128 v[176:179], v188 offset:8192
	ds_read_b128 v[180:183], v188 offset:12288
	s_add_u32 s20, s16, 512
	s_addc_u32 s21, s17, 0
	s_add_u32 s24, s18, 512
	s_addc_u32 s25, s19, 0
	v_mfma_f32_32x32x16_bf16 v[112:127], v[128:131], v[136:139], v[112:127]
	v_xor_b32_e32 v185, 0x10000, v185
	v_xor_b32_e32 v189, 0x10000, v189
	s_add_u32 m0, s27, 0
	v_lshl_add_u64 v[152:153], v[192:193], 0, s[20:21]
	global_load_lds_dwordx4 v[152:153], off
	v_mfma_f32_32x32x16_bf16 v[48:63], v[132:135], v[136:139], v[48:63]
	v_xor_b32_e32 v186, 0x10000, v186
	v_xor_b32_e32 v190, 0x10000, v190
	s_add_u32 m0, s27, 32768
	v_lshl_add_u64 v[154:155], v[192:193], 0, s[24:25]
	global_load_lds_dwordx4 v[154:155], off
	v_mfma_f32_32x32x16_bf16 v[96:111], v[128:131], v[140:143], v[96:111]
	v_xor_b32_e32 v187, 0x10000, v187
	v_xor_b32_e32 v191, 0x10000, v191
	s_add_u32 m0, s27, 8192
	v_lshl_add_u64 v[156:157], v[194:195], 0, s[20:21]
	global_load_lds_dwordx4 v[156:157], off
	v_mfma_f32_32x32x16_bf16 v[32:47], v[132:135], v[140:143], v[32:47]
	s_add_u32 m0, s27, 40960
	v_lshl_add_u64 v[152:153], v[194:195], 0, s[24:25]
	global_load_lds_dwordx4 v[152:153], off
	v_mfma_f32_32x32x16_bf16 v[80:95], v[128:131], v[144:147], v[80:95]
	s_add_u32 m0, s27, 16384
	v_lshl_add_u64 v[154:155], v[196:197], 0, s[20:21]
	global_load_lds_dwordx4 v[154:155], off
	v_mfma_f32_32x32x16_bf16 v[16:31], v[132:135], v[144:147], v[16:31]
	s_add_u32 m0, s27, 49152
	v_lshl_add_u64 v[156:157], v[196:197], 0, s[24:25]
	global_load_lds_dwordx4 v[156:157], off
	v_mfma_f32_32x32x16_bf16 v[64:79], v[128:131], v[148:151], v[64:79]
	s_add_u32 m0, s27, 24576
	v_lshl_add_u64 v[152:153], v[198:199], 0, s[20:21]
	global_load_lds_dwordx4 v[152:153], off
	v_mfma_f32_32x32x16_bf16 v[0:15], v[132:135], v[148:151], v[0:15]
	s_add_u32 m0, s27, 57344
	v_lshl_add_u64 v[154:155], v[198:199], 0, s[24:25]
	global_load_lds_dwordx4 v[154:155], off
	ds_read_b128 v[128:131], v185
	ds_read_b128 v[136:139], v189
	ds_read_b128 v[132:135], v185 offset:4096
	ds_read_b128 v[140:143], v189 offset:4096
	ds_read_b128 v[144:147], v189 offset:8192
	ds_read_b128 v[148:151], v189 offset:12288
	s_waitcnt lgkmcnt(6)
	v_mfma_f32_32x32x16_bf16 v[112:127], v[160:163], v[168:171], v[112:127]
	v_mfma_f32_32x32x16_bf16 v[48:63], v[164:167], v[168:171], v[48:63]
	v_mfma_f32_32x32x16_bf16 v[96:111], v[160:163], v[172:175], v[96:111]
	v_mfma_f32_32x32x16_bf16 v[32:47], v[164:167], v[172:175], v[32:47]
	v_mfma_f32_32x32x16_bf16 v[80:95], v[160:163], v[176:179], v[80:95]
	v_mfma_f32_32x32x16_bf16 v[16:31], v[164:167], v[176:179], v[16:31]
	v_mfma_f32_32x32x16_bf16 v[64:79], v[160:163], v[180:183], v[64:79]
	v_mfma_f32_32x32x16_bf16 v[0:15], v[164:167], v[180:183], v[0:15]
	ds_read_b128 v[160:163], v186
	ds_read_b128 v[168:171], v190
	ds_read_b128 v[164:167], v186 offset:4096
	ds_read_b128 v[172:175], v190 offset:4096
	ds_read_b128 v[176:179], v190 offset:8192
	ds_read_b128 v[180:183], v190 offset:12288
	s_waitcnt lgkmcnt(6)
	v_mfma_f32_32x32x16_bf16 v[112:127], v[128:131], v[136:139], v[112:127]
	v_mfma_f32_32x32x16_bf16 v[48:63], v[132:135], v[136:139], v[48:63]
	v_mfma_f32_32x32x16_bf16 v[96:111], v[128:131], v[140:143], v[96:111]
	v_mfma_f32_32x32x16_bf16 v[32:47], v[132:135], v[140:143], v[32:47]
	v_mfma_f32_32x32x16_bf16 v[80:95], v[128:131], v[144:147], v[80:95]
	v_mfma_f32_32x32x16_bf16 v[16:31], v[132:135], v[144:147], v[16:31]
	v_mfma_f32_32x32x16_bf16 v[64:79], v[128:131], v[148:151], v[64:79]
	v_mfma_f32_32x32x16_bf16 v[0:15], v[132:135], v[148:151], v[0:15]
	ds_read_b128 v[128:131], v187
	ds_read_b128 v[136:139], v191
	ds_read_b128 v[132:135], v187 offset:4096
	ds_read_b128 v[140:143], v191 offset:4096
	ds_read_b128 v[144:147], v191 offset:8192
	ds_read_b128 v[148:151], v191 offset:12288
	s_waitcnt lgkmcnt(6)
	v_mfma_f32_32x32x16_bf16 v[112:127], v[160:163], v[168:171], v[112:127]
	v_mfma_f32_32x32x16_bf16 v[48:63], v[164:167], v[168:171], v[48:63]
	v_mfma_f32_32x32x16_bf16 v[96:111], v[160:163], v[172:175], v[96:111]
	v_mfma_f32_32x32x16_bf16 v[32:47], v[164:167], v[172:175], v[32:47]
	v_mfma_f32_32x32x16_bf16 v[80:95], v[160:163], v[176:179], v[80:95]
	v_mfma_f32_32x32x16_bf16 v[16:31], v[164:167], v[176:179], v[16:31]
	v_mfma_f32_32x32x16_bf16 v[64:79], v[160:163], v[180:183], v[64:79]
	v_mfma_f32_32x32x16_bf16 v[0:15], v[164:167], v[180:183], v[0:15]
	s_waitcnt vmcnt(0) lgkmcnt(0)
	s_barrier
	v_xor_b32_e32 v184, 0x10000, v184
	v_xor_b32_e32 v188, 0x10000, v188
	ds_read_b128 v[160:163], v184
	ds_read_b128 v[168:171], v188
	ds_read_b128 v[164:167], v184 offset:4096
	ds_read_b128 v[172:175], v188 offset:4096
	ds_read_b128 v[176:179], v188 offset:8192
	ds_read_b128 v[180:183], v188 offset:12288
	s_add_u32 s20, s16, 640
	s_addc_u32 s21, s17, 0
	s_add_u32 s24, s18, 640
	s_addc_u32 s25, s19, 0
	v_mfma_f32_32x32x16_bf16 v[112:127], v[128:131], v[136:139], v[112:127]
	v_xor_b32_e32 v185, 0x10000, v185
	v_xor_b32_e32 v189, 0x10000, v189
	s_add_u32 m0, s27, 65536
	v_lshl_add_u64 v[152:153], v[192:193], 0, s[20:21]
	global_load_lds_dwordx4 v[152:153], off
	v_mfma_f32_32x32x16_bf16 v[48:63], v[132:135], v[136:139], v[48:63]
	v_xor_b32_e32 v186, 0x10000, v186
	v_xor_b32_e32 v190, 0x10000, v190
	s_add_u32 m0, s27, 98304
	v_lshl_add_u64 v[154:155], v[192:193], 0, s[24:25]
	global_load_lds_dwordx4 v[154:155], off
	v_mfma_f32_32x32x16_bf16 v[96:111], v[128:131], v[140:143], v[96:111]
	v_xor_b32_e32 v187, 0x10000, v187
	v_xor_b32_e32 v191, 0x10000, v191
	s_add_u32 m0, s27, 73728
	v_lshl_add_u64 v[156:157], v[194:195], 0, s[20:21]
	global_load_lds_dwordx4 v[156:157], off
	v_mfma_f32_32x32x16_bf16 v[32:47], v[132:135], v[140:143], v[32:47]
	s_add_u32 m0, s27, 106496
	v_lshl_add_u64 v[152:153], v[194:195], 0, s[24:25]
	global_load_lds_dwordx4 v[152:153], off
	v_mfma_f32_32x32x16_bf16 v[80:95], v[128:131], v[144:147], v[80:95]
	s_add_u32 m0, s27, 81920
	v_lshl_add_u64 v[154:155], v[196:197], 0, s[20:21]
	global_load_lds_dwordx4 v[154:155], off
	v_mfma_f32_32x32x16_bf16 v[16:31], v[132:135], v[144:147], v[16:31]
	s_add_u32 m0, s27, 114688
	v_lshl_add_u64 v[156:157], v[196:197], 0, s[24:25]
	global_load_lds_dwordx4 v[156:157], off
	v_mfma_f32_32x32x16_bf16 v[64:79], v[128:131], v[148:151], v[64:79]
	s_add_u32 m0, s27, 90112
	v_lshl_add_u64 v[152:153], v[198:199], 0, s[20:21]
	global_load_lds_dwordx4 v[152:153], off
	v_mfma_f32_32x32x16_bf16 v[0:15], v[132:135], v[148:151], v[0:15]
	s_add_u32 m0, s27, 122880
	v_lshl_add_u64 v[154:155], v[198:199], 0, s[24:25]
	global_load_lds_dwordx4 v[154:155], off
	ds_read_b128 v[128:131], v185
	ds_read_b128 v[136:139], v189
	ds_read_b128 v[132:135], v185 offset:4096
	ds_read_b128 v[140:143], v189 offset:4096
	ds_read_b128 v[144:147], v189 offset:8192
	ds_read_b128 v[148:151], v189 offset:12288
	s_waitcnt lgkmcnt(6)
	v_mfma_f32_32x32x16_bf16 v[112:127], v[160:163], v[168:171], v[112:127]
	v_mfma_f32_32x32x16_bf16 v[48:63], v[164:167], v[168:171], v[48:63]
	v_mfma_f32_32x32x16_bf16 v[96:111], v[160:163], v[172:175], v[96:111]
	v_mfma_f32_32x32x16_bf16 v[32:47], v[164:167], v[172:175], v[32:47]
	v_mfma_f32_32x32x16_bf16 v[80:95], v[160:163], v[176:179], v[80:95]
	v_mfma_f32_32x32x16_bf16 v[16:31], v[164:167], v[176:179], v[16:31]
	v_mfma_f32_32x32x16_bf16 v[64:79], v[160:163], v[180:183], v[64:79]
	v_mfma_f32_32x32x16_bf16 v[0:15], v[164:167], v[180:183], v[0:15]
	ds_read_b128 v[160:163], v186
	ds_read_b128 v[168:171], v190
	ds_read_b128 v[164:167], v186 offset:4096
	ds_read_b128 v[172:175], v190 offset:4096
	ds_read_b128 v[176:179], v190 offset:8192
	ds_read_b128 v[180:183], v190 offset:12288
	s_waitcnt lgkmcnt(6)
	v_mfma_f32_32x32x16_bf16 v[112:127], v[128:131], v[136:139], v[112:127]
	v_mfma_f32_32x32x16_bf16 v[48:63], v[132:135], v[136:139], v[48:63]
	v_mfma_f32_32x32x16_bf16 v[96:111], v[128:131], v[140:143], v[96:111]
	v_mfma_f32_32x32x16_bf16 v[32:47], v[132:135], v[140:143], v[32:47]
	v_mfma_f32_32x32x16_bf16 v[80:95], v[128:131], v[144:147], v[80:95]
	v_mfma_f32_32x32x16_bf16 v[16:31], v[132:135], v[144:147], v[16:31]
	v_mfma_f32_32x32x16_bf16 v[64:79], v[128:131], v[148:151], v[64:79]
	v_mfma_f32_32x32x16_bf16 v[0:15], v[132:135], v[148:151], v[0:15]
	ds_read_b128 v[128:131], v187
	ds_read_b128 v[136:139], v191
	ds_read_b128 v[132:135], v187 offset:4096
	ds_read_b128 v[140:143], v191 offset:4096
	ds_read_b128 v[144:147], v191 offset:8192
	ds_read_b128 v[148:151], v191 offset:12288
	s_waitcnt lgkmcnt(6)
	v_mfma_f32_32x32x16_bf16 v[112:127], v[160:163], v[168:171], v[112:127]
	v_mfma_f32_32x32x16_bf16 v[48:63], v[164:167], v[168:171], v[48:63]
	v_mfma_f32_32x32x16_bf16 v[96:111], v[160:163], v[172:175], v[96:111]
	v_mfma_f32_32x32x16_bf16 v[32:47], v[164:167], v[172:175], v[32:47]
	v_mfma_f32_32x32x16_bf16 v[80:95], v[160:163], v[176:179], v[80:95]
	v_mfma_f32_32x32x16_bf16 v[16:31], v[164:167], v[176:179], v[16:31]
	v_mfma_f32_32x32x16_bf16 v[64:79], v[160:163], v[180:183], v[64:79]
	v_mfma_f32_32x32x16_bf16 v[0:15], v[164:167], v[180:183], v[0:15]
	s_waitcnt vmcnt(0) lgkmcnt(0)
	s_barrier
	v_xor_b32_e32 v184, 0x10000, v184
	v_xor_b32_e32 v188, 0x10000, v188
	ds_read_b128 v[160:163], v184
	ds_read_b128 v[168:171], v188
	ds_read_b128 v[164:167], v184 offset:4096
	ds_read_b128 v[172:175], v188 offset:4096
	ds_read_b128 v[176:179], v188 offset:8192
	ds_read_b128 v[180:183], v188 offset:12288
	s_add_u32 s20, s16, 768
	s_addc_u32 s21, s17, 0
	s_add_u32 s24, s18, 768
	s_addc_u32 s25, s19, 0
	v_mfma_f32_32x32x16_bf16 v[112:127], v[128:131], v[136:139], v[112:127]
	v_xor_b32_e32 v185, 0x10000, v185
	v_xor_b32_e32 v189, 0x10000, v189
	s_add_u32 m0, s27, 0
	v_lshl_add_u64 v[152:153], v[192:193], 0, s[20:21]
	global_load_lds_dwordx4 v[152:153], off
	v_mfma_f32_32x32x16_bf16 v[48:63], v[132:135], v[136:139], v[48:63]
	v_xor_b32_e32 v186, 0x10000, v186
	v_xor_b32_e32 v190, 0x10000, v190
	s_add_u32 m0, s27, 32768
	v_lshl_add_u64 v[154:155], v[192:193], 0, s[24:25]
	global_load_lds_dwordx4 v[154:155], off
	v_mfma_f32_32x32x16_bf16 v[96:111], v[128:131], v[140:143], v[96:111]
	v_xor_b32_e32 v187, 0x10000, v187
	v_xor_b32_e32 v191, 0x10000, v191
	s_add_u32 m0, s27, 8192
	v_lshl_add_u64 v[156:157], v[194:195], 0, s[20:21]
	global_load_lds_dwordx4 v[156:157], off
	v_mfma_f32_32x32x16_bf16 v[32:47], v[132:135], v[140:143], v[32:47]
	s_add_u32 m0, s27, 40960
	v_lshl_add_u64 v[152:153], v[194:195], 0, s[24:25]
	global_load_lds_dwordx4 v[152:153], off
	v_mfma_f32_32x32x16_bf16 v[80:95], v[128:131], v[144:147], v[80:95]
	s_add_u32 m0, s27, 16384
	v_lshl_add_u64 v[154:155], v[196:197], 0, s[20:21]
	global_load_lds_dwordx4 v[154:155], off
	v_mfma_f32_32x32x16_bf16 v[16:31], v[132:135], v[144:147], v[16:31]
	s_add_u32 m0, s27, 49152
	v_lshl_add_u64 v[156:157], v[196:197], 0, s[24:25]
	global_load_lds_dwordx4 v[156:157], off
	v_mfma_f32_32x32x16_bf16 v[64:79], v[128:131], v[148:151], v[64:79]
	s_add_u32 m0, s27, 24576
	v_lshl_add_u64 v[152:153], v[198:199], 0, s[20:21]
	global_load_lds_dwordx4 v[152:153], off
	v_mfma_f32_32x32x16_bf16 v[0:15], v[132:135], v[148:151], v[0:15]
	s_add_u32 m0, s27, 57344
	v_lshl_add_u64 v[154:155], v[198:199], 0, s[24:25]
	global_load_lds_dwordx4 v[154:155], off
	ds_read_b128 v[128:131], v185
	ds_read_b128 v[136:139], v189
	ds_read_b128 v[132:135], v185 offset:4096
	ds_read_b128 v[140:143], v189 offset:4096
	ds_read_b128 v[144:147], v189 offset:8192
	ds_read_b128 v[148:151], v189 offset:12288
	s_waitcnt lgkmcnt(6)
	v_mfma_f32_32x32x16_bf16 v[112:127], v[160:163], v[168:171], v[112:127]
	v_mfma_f32_32x32x16_bf16 v[48:63], v[164:167], v[168:171], v[48:63]
	v_mfma_f32_32x32x16_bf16 v[96:111], v[160:163], v[172:175], v[96:111]
	v_mfma_f32_32x32x16_bf16 v[32:47], v[164:167], v[172:175], v[32:47]
	v_mfma_f32_32x32x16_bf16 v[80:95], v[160:163], v[176:179], v[80:95]
	v_mfma_f32_32x32x16_bf16 v[16:31], v[164:167], v[176:179], v[16:31]
	v_mfma_f32_32x32x16_bf16 v[64:79], v[160:163], v[180:183], v[64:79]
	v_mfma_f32_32x32x16_bf16 v[0:15], v[164:167], v[180:183], v[0:15]
	ds_read_b128 v[160:163], v186
	ds_read_b128 v[168:171], v190
	ds_read_b128 v[164:167], v186 offset:4096
	ds_read_b128 v[172:175], v190 offset:4096
	ds_read_b128 v[176:179], v190 offset:8192
	ds_read_b128 v[180:183], v190 offset:12288
	s_waitcnt lgkmcnt(6)
	v_mfma_f32_32x32x16_bf16 v[112:127], v[128:131], v[136:139], v[112:127]
	v_mfma_f32_32x32x16_bf16 v[48:63], v[132:135], v[136:139], v[48:63]
	v_mfma_f32_32x32x16_bf16 v[96:111], v[128:131], v[140:143], v[96:111]
	v_mfma_f32_32x32x16_bf16 v[32:47], v[132:135], v[140:143], v[32:47]
	v_mfma_f32_32x32x16_bf16 v[80:95], v[128:131], v[144:147], v[80:95]
	v_mfma_f32_32x32x16_bf16 v[16:31], v[132:135], v[144:147], v[16:31]
	v_mfma_f32_32x32x16_bf16 v[64:79], v[128:131], v[148:151], v[64:79]
	v_mfma_f32_32x32x16_bf16 v[0:15], v[132:135], v[148:151], v[0:15]
	ds_read_b128 v[128:131], v187
	ds_read_b128 v[136:139], v191
	ds_read_b128 v[132:135], v187 offset:4096
	ds_read_b128 v[140:143], v191 offset:4096
	ds_read_b128 v[144:147], v191 offset:8192
	ds_read_b128 v[148:151], v191 offset:12288
	s_waitcnt lgkmcnt(6)
	v_mfma_f32_32x32x16_bf16 v[112:127], v[160:163], v[168:171], v[112:127]
	v_mfma_f32_32x32x16_bf16 v[48:63], v[164:167], v[168:171], v[48:63]
	v_mfma_f32_32x32x16_bf16 v[96:111], v[160:163], v[172:175], v[96:111]
	v_mfma_f32_32x32x16_bf16 v[32:47], v[164:167], v[172:175], v[32:47]
	v_mfma_f32_32x32x16_bf16 v[80:95], v[160:163], v[176:179], v[80:95]
	v_mfma_f32_32x32x16_bf16 v[16:31], v[164:167], v[176:179], v[16:31]
	v_mfma_f32_32x32x16_bf16 v[64:79], v[160:163], v[180:183], v[64:79]
	v_mfma_f32_32x32x16_bf16 v[0:15], v[164:167], v[180:183], v[0:15]
	s_waitcnt vmcnt(0) lgkmcnt(0)
	s_barrier
	v_xor_b32_e32 v184, 0x10000, v184
	v_xor_b32_e32 v188, 0x10000, v188
	ds_read_b128 v[160:163], v184
	ds_read_b128 v[168:171], v188
	ds_read_b128 v[164:167], v184 offset:4096
	ds_read_b128 v[172:175], v188 offset:4096
	ds_read_b128 v[176:179], v188 offset:8192
	ds_read_b128 v[180:183], v188 offset:12288
	s_add_u32 s20, s16, 896
	s_addc_u32 s21, s17, 0
	s_add_u32 s24, s18, 896
	s_addc_u32 s25, s19, 0
	v_mfma_f32_32x32x16_bf16 v[112:127], v[128:131], v[136:139], v[112:127]
	v_xor_b32_e32 v185, 0x10000, v185
	v_xor_b32_e32 v189, 0x10000, v189
	s_add_u32 m0, s27, 65536
	v_lshl_add_u64 v[152:153], v[192:193], 0, s[20:21]
	global_load_lds_dwordx4 v[152:153], off
	v_mfma_f32_32x32x16_bf16 v[48:63], v[132:135], v[136:139], v[48:63]
	v_xor_b32_e32 v186, 0x10000, v186
	v_xor_b32_e32 v190, 0x10000, v190
	s_add_u32 m0, s27, 98304
	v_lshl_add_u64 v[154:155], v[192:193], 0, s[24:25]
	global_load_lds_dwordx4 v[154:155], off
	v_mfma_f32_32x32x16_bf16 v[96:111], v[128:131], v[140:143], v[96:111]
	v_xor_b32_e32 v187, 0x10000, v187
	v_xor_b32_e32 v191, 0x10000, v191
	s_add_u32 m0, s27, 73728
	v_lshl_add_u64 v[156:157], v[194:195], 0, s[20:21]
	global_load_lds_dwordx4 v[156:157], off
	v_mfma_f32_32x32x16_bf16 v[32:47], v[132:135], v[140:143], v[32:47]
	s_add_u32 m0, s27, 106496
	v_lshl_add_u64 v[152:153], v[194:195], 0, s[24:25]
	global_load_lds_dwordx4 v[152:153], off
	v_mfma_f32_32x32x16_bf16 v[80:95], v[128:131], v[144:147], v[80:95]
	s_add_u32 m0, s27, 81920
	v_lshl_add_u64 v[154:155], v[196:197], 0, s[20:21]
	global_load_lds_dwordx4 v[154:155], off
	v_mfma_f32_32x32x16_bf16 v[16:31], v[132:135], v[144:147], v[16:31]
	s_add_u32 m0, s27, 114688
	v_lshl_add_u64 v[156:157], v[196:197], 0, s[24:25]
	global_load_lds_dwordx4 v[156:157], off
	v_mfma_f32_32x32x16_bf16 v[64:79], v[128:131], v[148:151], v[64:79]
	s_add_u32 m0, s27, 90112
	v_lshl_add_u64 v[152:153], v[198:199], 0, s[20:21]
	global_load_lds_dwordx4 v[152:153], off
	v_mfma_f32_32x32x16_bf16 v[0:15], v[132:135], v[148:151], v[0:15]
	s_add_u32 m0, s27, 122880
	v_lshl_add_u64 v[154:155], v[198:199], 0, s[24:25]
	global_load_lds_dwordx4 v[154:155], off
	ds_read_b128 v[128:131], v185
	ds_read_b128 v[136:139], v189
	ds_read_b128 v[132:135], v185 offset:4096
	ds_read_b128 v[140:143], v189 offset:4096
	ds_read_b128 v[144:147], v189 offset:8192
	ds_read_b128 v[148:151], v189 offset:12288
	s_waitcnt lgkmcnt(6)
	v_mfma_f32_32x32x16_bf16 v[112:127], v[160:163], v[168:171], v[112:127]
	v_mfma_f32_32x32x16_bf16 v[48:63], v[164:167], v[168:171], v[48:63]
	v_mfma_f32_32x32x16_bf16 v[96:111], v[160:163], v[172:175], v[96:111]
	v_mfma_f32_32x32x16_bf16 v[32:47], v[164:167], v[172:175], v[32:47]
	v_mfma_f32_32x32x16_bf16 v[80:95], v[160:163], v[176:179], v[80:95]
	v_mfma_f32_32x32x16_bf16 v[16:31], v[164:167], v[176:179], v[16:31]
	v_mfma_f32_32x32x16_bf16 v[64:79], v[160:163], v[180:183], v[64:79]
	v_mfma_f32_32x32x16_bf16 v[0:15], v[164:167], v[180:183], v[0:15]
	ds_read_b128 v[160:163], v186
	ds_read_b128 v[168:171], v190
	ds_read_b128 v[164:167], v186 offset:4096
	ds_read_b128 v[172:175], v190 offset:4096
	ds_read_b128 v[176:179], v190 offset:8192
	ds_read_b128 v[180:183], v190 offset:12288
	s_waitcnt lgkmcnt(6)
	v_mfma_f32_32x32x16_bf16 v[112:127], v[128:131], v[136:139], v[112:127]
	v_mfma_f32_32x32x16_bf16 v[48:63], v[132:135], v[136:139], v[48:63]
	v_mfma_f32_32x32x16_bf16 v[96:111], v[128:131], v[140:143], v[96:111]
	v_mfma_f32_32x32x16_bf16 v[32:47], v[132:135], v[140:143], v[32:47]
	v_mfma_f32_32x32x16_bf16 v[80:95], v[128:131], v[144:147], v[80:95]
	v_mfma_f32_32x32x16_bf16 v[16:31], v[132:135], v[144:147], v[16:31]
	v_mfma_f32_32x32x16_bf16 v[64:79], v[128:131], v[148:151], v[64:79]
	v_mfma_f32_32x32x16_bf16 v[0:15], v[132:135], v[148:151], v[0:15]
	ds_read_b128 v[128:131], v187
	ds_read_b128 v[136:139], v191
	ds_read_b128 v[132:135], v187 offset:4096
	ds_read_b128 v[140:143], v191 offset:4096
	ds_read_b128 v[144:147], v191 offset:8192
	ds_read_b128 v[148:151], v191 offset:12288
	s_waitcnt lgkmcnt(6)
	v_mfma_f32_32x32x16_bf16 v[112:127], v[160:163], v[168:171], v[112:127]
	v_mfma_f32_32x32x16_bf16 v[48:63], v[164:167], v[168:171], v[48:63]
	v_mfma_f32_32x32x16_bf16 v[96:111], v[160:163], v[172:175], v[96:111]
	v_mfma_f32_32x32x16_bf16 v[32:47], v[164:167], v[172:175], v[32:47]
	v_mfma_f32_32x32x16_bf16 v[80:95], v[160:163], v[176:179], v[80:95]
	v_mfma_f32_32x32x16_bf16 v[16:31], v[164:167], v[176:179], v[16:31]
	v_mfma_f32_32x32x16_bf16 v[64:79], v[160:163], v[180:183], v[64:79]
	v_mfma_f32_32x32x16_bf16 v[0:15], v[164:167], v[180:183], v[0:15]
	s_waitcnt vmcnt(0) lgkmcnt(0)
	s_barrier
	v_xor_b32_e32 v184, 0x10000, v184
	v_xor_b32_e32 v188, 0x10000, v188
	ds_read_b128 v[160:163], v184
	ds_read_b128 v[168:171], v188
	ds_read_b128 v[164:167], v184 offset:4096
	ds_read_b128 v[172:175], v188 offset:4096
	ds_read_b128 v[176:179], v188 offset:8192
	ds_read_b128 v[180:183], v188 offset:12288
	s_add_u32 s20, s16, 1024
	s_addc_u32 s21, s17, 0
	s_add_u32 s24, s18, 1024
	s_addc_u32 s25, s19, 0
	v_mfma_f32_32x32x16_bf16 v[112:127], v[128:131], v[136:139], v[112:127]
	v_xor_b32_e32 v185, 0x10000, v185
	v_xor_b32_e32 v189, 0x10000, v189
	s_add_u32 m0, s27, 0
	v_lshl_add_u64 v[152:153], v[192:193], 0, s[20:21]
	global_load_lds_dwordx4 v[152:153], off
	v_mfma_f32_32x32x16_bf16 v[48:63], v[132:135], v[136:139], v[48:63]
	v_xor_b32_e32 v186, 0x10000, v186
	v_xor_b32_e32 v190, 0x10000, v190
	s_add_u32 m0, s27, 32768
	v_lshl_add_u64 v[154:155], v[192:193], 0, s[24:25]
	global_load_lds_dwordx4 v[154:155], off
	v_mfma_f32_32x32x16_bf16 v[96:111], v[128:131], v[140:143], v[96:111]
	v_xor_b32_e32 v187, 0x10000, v187
	v_xor_b32_e32 v191, 0x10000, v191
	s_add_u32 m0, s27, 8192
	v_lshl_add_u64 v[156:157], v[194:195], 0, s[20:21]
	global_load_lds_dwordx4 v[156:157], off
	v_mfma_f32_32x32x16_bf16 v[32:47], v[132:135], v[140:143], v[32:47]
	s_add_u32 m0, s27, 40960
	v_lshl_add_u64 v[152:153], v[194:195], 0, s[24:25]
	global_load_lds_dwordx4 v[152:153], off
	v_mfma_f32_32x32x16_bf16 v[80:95], v[128:131], v[144:147], v[80:95]
	s_add_u32 m0, s27, 16384
	v_lshl_add_u64 v[154:155], v[196:197], 0, s[20:21]
	global_load_lds_dwordx4 v[154:155], off
	v_mfma_f32_32x32x16_bf16 v[16:31], v[132:135], v[144:147], v[16:31]
	s_add_u32 m0, s27, 49152
	v_lshl_add_u64 v[156:157], v[196:197], 0, s[24:25]
	global_load_lds_dwordx4 v[156:157], off
	v_mfma_f32_32x32x16_bf16 v[64:79], v[128:131], v[148:151], v[64:79]
	s_add_u32 m0, s27, 24576
	v_lshl_add_u64 v[152:153], v[198:199], 0, s[20:21]
	global_load_lds_dwordx4 v[152:153], off
	v_mfma_f32_32x32x16_bf16 v[0:15], v[132:135], v[148:151], v[0:15]
	s_add_u32 m0, s27, 57344
	v_lshl_add_u64 v[154:155], v[198:199], 0, s[24:25]
	global_load_lds_dwordx4 v[154:155], off
	ds_read_b128 v[128:131], v185
	ds_read_b128 v[136:139], v189
	ds_read_b128 v[132:135], v185 offset:4096
	ds_read_b128 v[140:143], v189 offset:4096
	ds_read_b128 v[144:147], v189 offset:8192
	ds_read_b128 v[148:151], v189 offset:12288
	s_waitcnt lgkmcnt(6)
	v_mfma_f32_32x32x16_bf16 v[112:127], v[160:163], v[168:171], v[112:127]
	v_mfma_f32_32x32x16_bf16 v[48:63], v[164:167], v[168:171], v[48:63]
	v_mfma_f32_32x32x16_bf16 v[96:111], v[160:163], v[172:175], v[96:111]
	v_mfma_f32_32x32x16_bf16 v[32:47], v[164:167], v[172:175], v[32:47]
	v_mfma_f32_32x32x16_bf16 v[80:95], v[160:163], v[176:179], v[80:95]
	v_mfma_f32_32x32x16_bf16 v[16:31], v[164:167], v[176:179], v[16:31]
	v_mfma_f32_32x32x16_bf16 v[64:79], v[160:163], v[180:183], v[64:79]
	v_mfma_f32_32x32x16_bf16 v[0:15], v[164:167], v[180:183], v[0:15]
	ds_read_b128 v[160:163], v186
	ds_read_b128 v[168:171], v190
	ds_read_b128 v[164:167], v186 offset:4096
	ds_read_b128 v[172:175], v190 offset:4096
	ds_read_b128 v[176:179], v190 offset:8192
	ds_read_b128 v[180:183], v190 offset:12288
	s_waitcnt lgkmcnt(6)
	v_mfma_f32_32x32x16_bf16 v[112:127], v[128:131], v[136:139], v[112:127]
	v_mfma_f32_32x32x16_bf16 v[48:63], v[132:135], v[136:139], v[48:63]
	v_mfma_f32_32x32x16_bf16 v[96:111], v[128:131], v[140:143], v[96:111]
	v_mfma_f32_32x32x16_bf16 v[32:47], v[132:135], v[140:143], v[32:47]
	v_mfma_f32_32x32x16_bf16 v[80:95], v[128:131], v[144:147], v[80:95]
	v_mfma_f32_32x32x16_bf16 v[16:31], v[132:135], v[144:147], v[16:31]
	v_mfma_f32_32x32x16_bf16 v[64:79], v[128:131], v[148:151], v[64:79]
	v_mfma_f32_32x32x16_bf16 v[0:15], v[132:135], v[148:151], v[0:15]
	ds_read_b128 v[128:131], v187
	ds_read_b128 v[136:139], v191
	ds_read_b128 v[132:135], v187 offset:4096
	ds_read_b128 v[140:143], v191 offset:4096
	ds_read_b128 v[144:147], v191 offset:8192
	ds_read_b128 v[148:151], v191 offset:12288
	s_waitcnt lgkmcnt(6)
	v_mfma_f32_32x32x16_bf16 v[112:127], v[160:163], v[168:171], v[112:127]
	v_mfma_f32_32x32x16_bf16 v[48:63], v[164:167], v[168:171], v[48:63]
	v_mfma_f32_32x32x16_bf16 v[96:111], v[160:163], v[172:175], v[96:111]
	v_mfma_f32_32x32x16_bf16 v[32:47], v[164:167], v[172:175], v[32:47]
	v_mfma_f32_32x32x16_bf16 v[80:95], v[160:163], v[176:179], v[80:95]
	v_mfma_f32_32x32x16_bf16 v[16:31], v[164:167], v[176:179], v[16:31]
	v_mfma_f32_32x32x16_bf16 v[64:79], v[160:163], v[180:183], v[64:79]
	v_mfma_f32_32x32x16_bf16 v[0:15], v[164:167], v[180:183], v[0:15]
	s_waitcnt vmcnt(0) lgkmcnt(0)
	s_barrier
	v_xor_b32_e32 v184, 0x10000, v184
	v_xor_b32_e32 v188, 0x10000, v188
	ds_read_b128 v[160:163], v184
	ds_read_b128 v[168:171], v188
	ds_read_b128 v[164:167], v184 offset:4096
	ds_read_b128 v[172:175], v188 offset:4096
	ds_read_b128 v[176:179], v188 offset:8192
	ds_read_b128 v[180:183], v188 offset:12288
	s_add_u32 s20, s16, 1152
	s_addc_u32 s21, s17, 0
	s_add_u32 s24, s18, 1152
	s_addc_u32 s25, s19, 0
	v_mfma_f32_32x32x16_bf16 v[112:127], v[128:131], v[136:139], v[112:127]
	v_xor_b32_e32 v185, 0x10000, v185
	v_xor_b32_e32 v189, 0x10000, v189
	s_add_u32 m0, s27, 65536
	v_lshl_add_u64 v[152:153], v[192:193], 0, s[20:21]
	global_load_lds_dwordx4 v[152:153], off
	v_mfma_f32_32x32x16_bf16 v[48:63], v[132:135], v[136:139], v[48:63]
	v_xor_b32_e32 v186, 0x10000, v186
	v_xor_b32_e32 v190, 0x10000, v190
	s_add_u32 m0, s27, 98304
	v_lshl_add_u64 v[154:155], v[192:193], 0, s[24:25]
	global_load_lds_dwordx4 v[154:155], off
	v_mfma_f32_32x32x16_bf16 v[96:111], v[128:131], v[140:143], v[96:111]
	v_xor_b32_e32 v187, 0x10000, v187
	v_xor_b32_e32 v191, 0x10000, v191
	s_add_u32 m0, s27, 73728
	v_lshl_add_u64 v[156:157], v[194:195], 0, s[20:21]
	global_load_lds_dwordx4 v[156:157], off
	v_mfma_f32_32x32x16_bf16 v[32:47], v[132:135], v[140:143], v[32:47]
	s_add_u32 m0, s27, 106496
	v_lshl_add_u64 v[152:153], v[194:195], 0, s[24:25]
	global_load_lds_dwordx4 v[152:153], off
	v_mfma_f32_32x32x16_bf16 v[80:95], v[128:131], v[144:147], v[80:95]
	s_add_u32 m0, s27, 81920
	v_lshl_add_u64 v[154:155], v[196:197], 0, s[20:21]
	global_load_lds_dwordx4 v[154:155], off
	v_mfma_f32_32x32x16_bf16 v[16:31], v[132:135], v[144:147], v[16:31]
	s_add_u32 m0, s27, 114688
	v_lshl_add_u64 v[156:157], v[196:197], 0, s[24:25]
	global_load_lds_dwordx4 v[156:157], off
	v_mfma_f32_32x32x16_bf16 v[64:79], v[128:131], v[148:151], v[64:79]
	s_add_u32 m0, s27, 90112
	v_lshl_add_u64 v[152:153], v[198:199], 0, s[20:21]
	global_load_lds_dwordx4 v[152:153], off
	v_mfma_f32_32x32x16_bf16 v[0:15], v[132:135], v[148:151], v[0:15]
	s_add_u32 m0, s27, 122880
	v_lshl_add_u64 v[154:155], v[198:199], 0, s[24:25]
	global_load_lds_dwordx4 v[154:155], off
	ds_read_b128 v[128:131], v185
	ds_read_b128 v[136:139], v189
	ds_read_b128 v[132:135], v185 offset:4096
	ds_read_b128 v[140:143], v189 offset:4096
	ds_read_b128 v[144:147], v189 offset:8192
	ds_read_b128 v[148:151], v189 offset:12288
	s_waitcnt lgkmcnt(6)
	v_mfma_f32_32x32x16_bf16 v[112:127], v[160:163], v[168:171], v[112:127]
	v_mfma_f32_32x32x16_bf16 v[48:63], v[164:167], v[168:171], v[48:63]
	v_mfma_f32_32x32x16_bf16 v[96:111], v[160:163], v[172:175], v[96:111]
	v_mfma_f32_32x32x16_bf16 v[32:47], v[164:167], v[172:175], v[32:47]
	v_mfma_f32_32x32x16_bf16 v[80:95], v[160:163], v[176:179], v[80:95]
	v_mfma_f32_32x32x16_bf16 v[16:31], v[164:167], v[176:179], v[16:31]
	v_mfma_f32_32x32x16_bf16 v[64:79], v[160:163], v[180:183], v[64:79]
	v_mfma_f32_32x32x16_bf16 v[0:15], v[164:167], v[180:183], v[0:15]
	ds_read_b128 v[160:163], v186
	ds_read_b128 v[168:171], v190
	ds_read_b128 v[164:167], v186 offset:4096
	ds_read_b128 v[172:175], v190 offset:4096
	ds_read_b128 v[176:179], v190 offset:8192
	ds_read_b128 v[180:183], v190 offset:12288
	s_waitcnt lgkmcnt(6)
	v_mfma_f32_32x32x16_bf16 v[112:127], v[128:131], v[136:139], v[112:127]
	v_mfma_f32_32x32x16_bf16 v[48:63], v[132:135], v[136:139], v[48:63]
	v_mfma_f32_32x32x16_bf16 v[96:111], v[128:131], v[140:143], v[96:111]
	v_mfma_f32_32x32x16_bf16 v[32:47], v[132:135], v[140:143], v[32:47]
	v_mfma_f32_32x32x16_bf16 v[80:95], v[128:131], v[144:147], v[80:95]
	v_mfma_f32_32x32x16_bf16 v[16:31], v[132:135], v[144:147], v[16:31]
	v_mfma_f32_32x32x16_bf16 v[64:79], v[128:131], v[148:151], v[64:79]
	v_mfma_f32_32x32x16_bf16 v[0:15], v[132:135], v[148:151], v[0:15]
	ds_read_b128 v[128:131], v187
	ds_read_b128 v[136:139], v191
	ds_read_b128 v[132:135], v187 offset:4096
	ds_read_b128 v[140:143], v191 offset:4096
	ds_read_b128 v[144:147], v191 offset:8192
	ds_read_b128 v[148:151], v191 offset:12288
	s_waitcnt lgkmcnt(6)
	v_mfma_f32_32x32x16_bf16 v[112:127], v[160:163], v[168:171], v[112:127]
	v_mfma_f32_32x32x16_bf16 v[48:63], v[164:167], v[168:171], v[48:63]
	v_mfma_f32_32x32x16_bf16 v[96:111], v[160:163], v[172:175], v[96:111]
	v_mfma_f32_32x32x16_bf16 v[32:47], v[164:167], v[172:175], v[32:47]
	v_mfma_f32_32x32x16_bf16 v[80:95], v[160:163], v[176:179], v[80:95]
	v_mfma_f32_32x32x16_bf16 v[16:31], v[164:167], v[176:179], v[16:31]
	v_mfma_f32_32x32x16_bf16 v[64:79], v[160:163], v[180:183], v[64:79]
	v_mfma_f32_32x32x16_bf16 v[0:15], v[164:167], v[180:183], v[0:15]
	s_waitcnt vmcnt(0) lgkmcnt(0)
	s_barrier
	v_xor_b32_e32 v184, 0x10000, v184
	v_xor_b32_e32 v188, 0x10000, v188
	ds_read_b128 v[160:163], v184
	ds_read_b128 v[168:171], v188
	ds_read_b128 v[164:167], v184 offset:4096
	ds_read_b128 v[172:175], v188 offset:4096
	ds_read_b128 v[176:179], v188 offset:8192
	ds_read_b128 v[180:183], v188 offset:12288
	s_add_u32 s20, s16, 1280
	s_addc_u32 s21, s17, 0
	s_add_u32 s24, s18, 1280
	s_addc_u32 s25, s19, 0
	v_mfma_f32_32x32x16_bf16 v[112:127], v[128:131], v[136:139], v[112:127]
	v_xor_b32_e32 v185, 0x10000, v185
	v_xor_b32_e32 v189, 0x10000, v189
	s_add_u32 m0, s27, 0
	v_lshl_add_u64 v[152:153], v[192:193], 0, s[20:21]
	global_load_lds_dwordx4 v[152:153], off
	v_mfma_f32_32x32x16_bf16 v[48:63], v[132:135], v[136:139], v[48:63]
	v_xor_b32_e32 v186, 0x10000, v186
	v_xor_b32_e32 v190, 0x10000, v190
	s_add_u32 m0, s27, 32768
	v_lshl_add_u64 v[154:155], v[192:193], 0, s[24:25]
	global_load_lds_dwordx4 v[154:155], off
	v_mfma_f32_32x32x16_bf16 v[96:111], v[128:131], v[140:143], v[96:111]
	v_xor_b32_e32 v187, 0x10000, v187
	v_xor_b32_e32 v191, 0x10000, v191
	s_add_u32 m0, s27, 8192
	v_lshl_add_u64 v[156:157], v[194:195], 0, s[20:21]
	global_load_lds_dwordx4 v[156:157], off
	v_mfma_f32_32x32x16_bf16 v[32:47], v[132:135], v[140:143], v[32:47]
	s_add_u32 m0, s27, 40960
	v_lshl_add_u64 v[152:153], v[194:195], 0, s[24:25]
	global_load_lds_dwordx4 v[152:153], off
	v_mfma_f32_32x32x16_bf16 v[80:95], v[128:131], v[144:147], v[80:95]
	s_add_u32 m0, s27, 16384
	v_lshl_add_u64 v[154:155], v[196:197], 0, s[20:21]
	global_load_lds_dwordx4 v[154:155], off
	v_mfma_f32_32x32x16_bf16 v[16:31], v[132:135], v[144:147], v[16:31]
	s_add_u32 m0, s27, 49152
	v_lshl_add_u64 v[156:157], v[196:197], 0, s[24:25]
	global_load_lds_dwordx4 v[156:157], off
	v_mfma_f32_32x32x16_bf16 v[64:79], v[128:131], v[148:151], v[64:79]
	s_add_u32 m0, s27, 24576
	v_lshl_add_u64 v[152:153], v[198:199], 0, s[20:21]
	global_load_lds_dwordx4 v[152:153], off
	v_mfma_f32_32x32x16_bf16 v[0:15], v[132:135], v[148:151], v[0:15]
	s_add_u32 m0, s27, 57344
	v_lshl_add_u64 v[154:155], v[198:199], 0, s[24:25]
	global_load_lds_dwordx4 v[154:155], off
	ds_read_b128 v[128:131], v185
	ds_read_b128 v[136:139], v189
	ds_read_b128 v[132:135], v185 offset:4096
	ds_read_b128 v[140:143], v189 offset:4096
	ds_read_b128 v[144:147], v189 offset:8192
	ds_read_b128 v[148:151], v189 offset:12288
	s_waitcnt lgkmcnt(6)
	v_mfma_f32_32x32x16_bf16 v[112:127], v[160:163], v[168:171], v[112:127]
	v_mfma_f32_32x32x16_bf16 v[48:63], v[164:167], v[168:171], v[48:63]
	v_mfma_f32_32x32x16_bf16 v[96:111], v[160:163], v[172:175], v[96:111]
	v_mfma_f32_32x32x16_bf16 v[32:47], v[164:167], v[172:175], v[32:47]
	v_mfma_f32_32x32x16_bf16 v[80:95], v[160:163], v[176:179], v[80:95]
	v_mfma_f32_32x32x16_bf16 v[16:31], v[164:167], v[176:179], v[16:31]
	v_mfma_f32_32x32x16_bf16 v[64:79], v[160:163], v[180:183], v[64:79]
	v_mfma_f32_32x32x16_bf16 v[0:15], v[164:167], v[180:183], v[0:15]
	ds_read_b128 v[160:163], v186
	ds_read_b128 v[168:171], v190
	ds_read_b128 v[164:167], v186 offset:4096
	ds_read_b128 v[172:175], v190 offset:4096
	ds_read_b128 v[176:179], v190 offset:8192
	ds_read_b128 v[180:183], v190 offset:12288
	s_waitcnt lgkmcnt(6)
	v_mfma_f32_32x32x16_bf16 v[112:127], v[128:131], v[136:139], v[112:127]
	v_mfma_f32_32x32x16_bf16 v[48:63], v[132:135], v[136:139], v[48:63]
	v_mfma_f32_32x32x16_bf16 v[96:111], v[128:131], v[140:143], v[96:111]
	v_mfma_f32_32x32x16_bf16 v[32:47], v[132:135], v[140:143], v[32:47]
	v_mfma_f32_32x32x16_bf16 v[80:95], v[128:131], v[144:147], v[80:95]
	v_mfma_f32_32x32x16_bf16 v[16:31], v[132:135], v[144:147], v[16:31]
	v_mfma_f32_32x32x16_bf16 v[64:79], v[128:131], v[148:151], v[64:79]
	v_mfma_f32_32x32x16_bf16 v[0:15], v[132:135], v[148:151], v[0:15]
	ds_read_b128 v[128:131], v187
	ds_read_b128 v[136:139], v191
	ds_read_b128 v[132:135], v187 offset:4096
	ds_read_b128 v[140:143], v191 offset:4096
	ds_read_b128 v[144:147], v191 offset:8192
	ds_read_b128 v[148:151], v191 offset:12288
	s_waitcnt lgkmcnt(6)
	v_mfma_f32_32x32x16_bf16 v[112:127], v[160:163], v[168:171], v[112:127]
	v_mfma_f32_32x32x16_bf16 v[48:63], v[164:167], v[168:171], v[48:63]
	v_mfma_f32_32x32x16_bf16 v[96:111], v[160:163], v[172:175], v[96:111]
	v_mfma_f32_32x32x16_bf16 v[32:47], v[164:167], v[172:175], v[32:47]
	v_mfma_f32_32x32x16_bf16 v[80:95], v[160:163], v[176:179], v[80:95]
	v_mfma_f32_32x32x16_bf16 v[16:31], v[164:167], v[176:179], v[16:31]
	v_mfma_f32_32x32x16_bf16 v[64:79], v[160:163], v[180:183], v[64:79]
	v_mfma_f32_32x32x16_bf16 v[0:15], v[164:167], v[180:183], v[0:15]
	s_waitcnt vmcnt(0) lgkmcnt(0)
	s_barrier
	v_xor_b32_e32 v184, 0x10000, v184
	v_xor_b32_e32 v188, 0x10000, v188
	ds_read_b128 v[160:163], v184
	ds_read_b128 v[168:171], v188
	ds_read_b128 v[164:167], v184 offset:4096
	ds_read_b128 v[172:175], v188 offset:4096
	ds_read_b128 v[176:179], v188 offset:8192
	ds_read_b128 v[180:183], v188 offset:12288
	s_add_u32 s20, s16, 1408
	s_addc_u32 s21, s17, 0
	s_add_u32 s24, s18, 1408
	s_addc_u32 s25, s19, 0
	v_mfma_f32_32x32x16_bf16 v[112:127], v[128:131], v[136:139], v[112:127]
	v_xor_b32_e32 v185, 0x10000, v185
	v_xor_b32_e32 v189, 0x10000, v189
	s_add_u32 m0, s27, 65536
	v_lshl_add_u64 v[152:153], v[192:193], 0, s[20:21]
	global_load_lds_dwordx4 v[152:153], off
	v_mfma_f32_32x32x16_bf16 v[48:63], v[132:135], v[136:139], v[48:63]
	v_xor_b32_e32 v186, 0x10000, v186
	v_xor_b32_e32 v190, 0x10000, v190
	s_add_u32 m0, s27, 98304
	v_lshl_add_u64 v[154:155], v[192:193], 0, s[24:25]
	global_load_lds_dwordx4 v[154:155], off
	v_mfma_f32_32x32x16_bf16 v[96:111], v[128:131], v[140:143], v[96:111]
	v_xor_b32_e32 v187, 0x10000, v187
	v_xor_b32_e32 v191, 0x10000, v191
	s_add_u32 m0, s27, 73728
	v_lshl_add_u64 v[156:157], v[194:195], 0, s[20:21]
	global_load_lds_dwordx4 v[156:157], off
	v_mfma_f32_32x32x16_bf16 v[32:47], v[132:135], v[140:143], v[32:47]
	s_add_u32 m0, s27, 106496
	v_lshl_add_u64 v[152:153], v[194:195], 0, s[24:25]
	global_load_lds_dwordx4 v[152:153], off
	v_mfma_f32_32x32x16_bf16 v[80:95], v[128:131], v[144:147], v[80:95]
	s_add_u32 m0, s27, 81920
	v_lshl_add_u64 v[154:155], v[196:197], 0, s[20:21]
	global_load_lds_dwordx4 v[154:155], off
	v_mfma_f32_32x32x16_bf16 v[16:31], v[132:135], v[144:147], v[16:31]
	s_add_u32 m0, s27, 114688
	v_lshl_add_u64 v[156:157], v[196:197], 0, s[24:25]
	global_load_lds_dwordx4 v[156:157], off
	v_mfma_f32_32x32x16_bf16 v[64:79], v[128:131], v[148:151], v[64:79]
	s_add_u32 m0, s27, 90112
	v_lshl_add_u64 v[152:153], v[198:199], 0, s[20:21]
	global_load_lds_dwordx4 v[152:153], off
	v_mfma_f32_32x32x16_bf16 v[0:15], v[132:135], v[148:151], v[0:15]
	s_add_u32 m0, s27, 122880
	v_lshl_add_u64 v[154:155], v[198:199], 0, s[24:25]
	global_load_lds_dwordx4 v[154:155], off
	ds_read_b128 v[128:131], v185
	ds_read_b128 v[136:139], v189
	ds_read_b128 v[132:135], v185 offset:4096
	ds_read_b128 v[140:143], v189 offset:4096
	ds_read_b128 v[144:147], v189 offset:8192
	ds_read_b128 v[148:151], v189 offset:12288
	s_waitcnt lgkmcnt(6)
	v_mfma_f32_32x32x16_bf16 v[112:127], v[160:163], v[168:171], v[112:127]
	v_mfma_f32_32x32x16_bf16 v[48:63], v[164:167], v[168:171], v[48:63]
	v_mfma_f32_32x32x16_bf16 v[96:111], v[160:163], v[172:175], v[96:111]
	v_mfma_f32_32x32x16_bf16 v[32:47], v[164:167], v[172:175], v[32:47]
	v_mfma_f32_32x32x16_bf16 v[80:95], v[160:163], v[176:179], v[80:95]
	v_mfma_f32_32x32x16_bf16 v[16:31], v[164:167], v[176:179], v[16:31]
	v_mfma_f32_32x32x16_bf16 v[64:79], v[160:163], v[180:183], v[64:79]
	v_mfma_f32_32x32x16_bf16 v[0:15], v[164:167], v[180:183], v[0:15]
	ds_read_b128 v[160:163], v186
	ds_read_b128 v[168:171], v190
	ds_read_b128 v[164:167], v186 offset:4096
	ds_read_b128 v[172:175], v190 offset:4096
	ds_read_b128 v[176:179], v190 offset:8192
	ds_read_b128 v[180:183], v190 offset:12288
	s_waitcnt lgkmcnt(6)
	v_mfma_f32_32x32x16_bf16 v[112:127], v[128:131], v[136:139], v[112:127]
	v_mfma_f32_32x32x16_bf16 v[48:63], v[132:135], v[136:139], v[48:63]
	v_mfma_f32_32x32x16_bf16 v[96:111], v[128:131], v[140:143], v[96:111]
	v_mfma_f32_32x32x16_bf16 v[32:47], v[132:135], v[140:143], v[32:47]
	v_mfma_f32_32x32x16_bf16 v[80:95], v[128:131], v[144:147], v[80:95]
	v_mfma_f32_32x32x16_bf16 v[16:31], v[132:135], v[144:147], v[16:31]
	v_mfma_f32_32x32x16_bf16 v[64:79], v[128:131], v[148:151], v[64:79]
	v_mfma_f32_32x32x16_bf16 v[0:15], v[132:135], v[148:151], v[0:15]
	ds_read_b128 v[128:131], v187
	ds_read_b128 v[136:139], v191
	ds_read_b128 v[132:135], v187 offset:4096
	ds_read_b128 v[140:143], v191 offset:4096
	ds_read_b128 v[144:147], v191 offset:8192
	ds_read_b128 v[148:151], v191 offset:12288
	s_waitcnt lgkmcnt(6)
	v_mfma_f32_32x32x16_bf16 v[112:127], v[160:163], v[168:171], v[112:127]
	v_mfma_f32_32x32x16_bf16 v[48:63], v[164:167], v[168:171], v[48:63]
	v_mfma_f32_32x32x16_bf16 v[96:111], v[160:163], v[172:175], v[96:111]
	v_mfma_f32_32x32x16_bf16 v[32:47], v[164:167], v[172:175], v[32:47]
	v_mfma_f32_32x32x16_bf16 v[80:95], v[160:163], v[176:179], v[80:95]
	v_mfma_f32_32x32x16_bf16 v[16:31], v[164:167], v[176:179], v[16:31]
	v_mfma_f32_32x32x16_bf16 v[64:79], v[160:163], v[180:183], v[64:79]
	v_mfma_f32_32x32x16_bf16 v[0:15], v[164:167], v[180:183], v[0:15]
	s_waitcnt vmcnt(0) lgkmcnt(0)
	s_barrier
	v_xor_b32_e32 v184, 0x10000, v184
	v_xor_b32_e32 v188, 0x10000, v188
	ds_read_b128 v[160:163], v184
	ds_read_b128 v[168:171], v188
	ds_read_b128 v[164:167], v184 offset:4096
	ds_read_b128 v[172:175], v188 offset:4096
	ds_read_b128 v[176:179], v188 offset:8192
	ds_read_b128 v[180:183], v188 offset:12288
	s_add_u32 s20, s16, 1536
	s_addc_u32 s21, s17, 0
	s_add_u32 s24, s18, 1536
	s_addc_u32 s25, s19, 0
	v_mfma_f32_32x32x16_bf16 v[112:127], v[128:131], v[136:139], v[112:127]
	v_xor_b32_e32 v185, 0x10000, v185
	v_xor_b32_e32 v189, 0x10000, v189
	s_add_u32 m0, s27, 0
	v_lshl_add_u64 v[152:153], v[192:193], 0, s[20:21]
	global_load_lds_dwordx4 v[152:153], off
	v_mfma_f32_32x32x16_bf16 v[48:63], v[132:135], v[136:139], v[48:63]
	v_xor_b32_e32 v186, 0x10000, v186
	v_xor_b32_e32 v190, 0x10000, v190
	s_add_u32 m0, s27, 32768
	v_lshl_add_u64 v[154:155], v[192:193], 0, s[24:25]
	global_load_lds_dwordx4 v[154:155], off
	v_mfma_f32_32x32x16_bf16 v[96:111], v[128:131], v[140:143], v[96:111]
	v_xor_b32_e32 v187, 0x10000, v187
	v_xor_b32_e32 v191, 0x10000, v191
	s_add_u32 m0, s27, 8192
	v_lshl_add_u64 v[156:157], v[194:195], 0, s[20:21]
	global_load_lds_dwordx4 v[156:157], off
	v_mfma_f32_32x32x16_bf16 v[32:47], v[132:135], v[140:143], v[32:47]
	s_add_u32 m0, s27, 40960
	v_lshl_add_u64 v[152:153], v[194:195], 0, s[24:25]
	global_load_lds_dwordx4 v[152:153], off
	v_mfma_f32_32x32x16_bf16 v[80:95], v[128:131], v[144:147], v[80:95]
	s_add_u32 m0, s27, 16384
	v_lshl_add_u64 v[154:155], v[196:197], 0, s[20:21]
	global_load_lds_dwordx4 v[154:155], off
	v_mfma_f32_32x32x16_bf16 v[16:31], v[132:135], v[144:147], v[16:31]
	s_add_u32 m0, s27, 49152
	v_lshl_add_u64 v[156:157], v[196:197], 0, s[24:25]
	global_load_lds_dwordx4 v[156:157], off
	v_mfma_f32_32x32x16_bf16 v[64:79], v[128:131], v[148:151], v[64:79]
	s_add_u32 m0, s27, 24576
	v_lshl_add_u64 v[152:153], v[198:199], 0, s[20:21]
	global_load_lds_dwordx4 v[152:153], off
	v_mfma_f32_32x32x16_bf16 v[0:15], v[132:135], v[148:151], v[0:15]
	s_add_u32 m0, s27, 57344
	v_lshl_add_u64 v[154:155], v[198:199], 0, s[24:25]
	global_load_lds_dwordx4 v[154:155], off
	ds_read_b128 v[128:131], v185
	ds_read_b128 v[136:139], v189
	ds_read_b128 v[132:135], v185 offset:4096
	ds_read_b128 v[140:143], v189 offset:4096
	ds_read_b128 v[144:147], v189 offset:8192
	ds_read_b128 v[148:151], v189 offset:12288
	s_waitcnt lgkmcnt(6)
	v_mfma_f32_32x32x16_bf16 v[112:127], v[160:163], v[168:171], v[112:127]
	v_mfma_f32_32x32x16_bf16 v[48:63], v[164:167], v[168:171], v[48:63]
	v_mfma_f32_32x32x16_bf16 v[96:111], v[160:163], v[172:175], v[96:111]
	v_mfma_f32_32x32x16_bf16 v[32:47], v[164:167], v[172:175], v[32:47]
	v_mfma_f32_32x32x16_bf16 v[80:95], v[160:163], v[176:179], v[80:95]
	v_mfma_f32_32x32x16_bf16 v[16:31], v[164:167], v[176:179], v[16:31]
	v_mfma_f32_32x32x16_bf16 v[64:79], v[160:163], v[180:183], v[64:79]
	v_mfma_f32_32x32x16_bf16 v[0:15], v[164:167], v[180:183], v[0:15]
	ds_read_b128 v[160:163], v186
	ds_read_b128 v[168:171], v190
	ds_read_b128 v[164:167], v186 offset:4096
	ds_read_b128 v[172:175], v190 offset:4096
	ds_read_b128 v[176:179], v190 offset:8192
	ds_read_b128 v[180:183], v190 offset:12288
	s_waitcnt lgkmcnt(6)
	v_mfma_f32_32x32x16_bf16 v[112:127], v[128:131], v[136:139], v[112:127]
	v_mfma_f32_32x32x16_bf16 v[48:63], v[132:135], v[136:139], v[48:63]
	v_mfma_f32_32x32x16_bf16 v[96:111], v[128:131], v[140:143], v[96:111]
	v_mfma_f32_32x32x16_bf16 v[32:47], v[132:135], v[140:143], v[32:47]
	v_mfma_f32_32x32x16_bf16 v[80:95], v[128:131], v[144:147], v[80:95]
	v_mfma_f32_32x32x16_bf16 v[16:31], v[132:135], v[144:147], v[16:31]
	v_mfma_f32_32x32x16_bf16 v[64:79], v[128:131], v[148:151], v[64:79]
	v_mfma_f32_32x32x16_bf16 v[0:15], v[132:135], v[148:151], v[0:15]
	ds_read_b128 v[128:131], v187
	ds_read_b128 v[136:139], v191
	ds_read_b128 v[132:135], v187 offset:4096
	ds_read_b128 v[140:143], v191 offset:4096
	ds_read_b128 v[144:147], v191 offset:8192
	ds_read_b128 v[148:151], v191 offset:12288
	s_waitcnt lgkmcnt(6)
	v_mfma_f32_32x32x16_bf16 v[112:127], v[160:163], v[168:171], v[112:127]
	v_mfma_f32_32x32x16_bf16 v[48:63], v[164:167], v[168:171], v[48:63]
	v_mfma_f32_32x32x16_bf16 v[96:111], v[160:163], v[172:175], v[96:111]
	v_mfma_f32_32x32x16_bf16 v[32:47], v[164:167], v[172:175], v[32:47]
	v_mfma_f32_32x32x16_bf16 v[80:95], v[160:163], v[176:179], v[80:95]
	v_mfma_f32_32x32x16_bf16 v[16:31], v[164:167], v[176:179], v[16:31]
	v_mfma_f32_32x32x16_bf16 v[64:79], v[160:163], v[180:183], v[64:79]
	v_mfma_f32_32x32x16_bf16 v[0:15], v[164:167], v[180:183], v[0:15]
	s_waitcnt vmcnt(0) lgkmcnt(0)
	s_barrier
	v_xor_b32_e32 v184, 0x10000, v184
	v_xor_b32_e32 v188, 0x10000, v188
	ds_read_b128 v[160:163], v184
	ds_read_b128 v[168:171], v188
	ds_read_b128 v[164:167], v184 offset:4096
	ds_read_b128 v[172:175], v188 offset:4096
	ds_read_b128 v[176:179], v188 offset:8192
	ds_read_b128 v[180:183], v188 offset:12288
	s_add_u32 s20, s16, 1664
	s_addc_u32 s21, s17, 0
	s_add_u32 s24, s18, 1664
	s_addc_u32 s25, s19, 0
	v_mfma_f32_32x32x16_bf16 v[112:127], v[128:131], v[136:139], v[112:127]
	v_xor_b32_e32 v185, 0x10000, v185
	v_xor_b32_e32 v189, 0x10000, v189
	s_add_u32 m0, s27, 65536
	v_lshl_add_u64 v[152:153], v[192:193], 0, s[20:21]
	global_load_lds_dwordx4 v[152:153], off
	v_mfma_f32_32x32x16_bf16 v[48:63], v[132:135], v[136:139], v[48:63]
	v_xor_b32_e32 v186, 0x10000, v186
	v_xor_b32_e32 v190, 0x10000, v190
	s_add_u32 m0, s27, 98304
	v_lshl_add_u64 v[154:155], v[192:193], 0, s[24:25]
	global_load_lds_dwordx4 v[154:155], off
	v_mfma_f32_32x32x16_bf16 v[96:111], v[128:131], v[140:143], v[96:111]
	v_xor_b32_e32 v187, 0x10000, v187
	v_xor_b32_e32 v191, 0x10000, v191
	s_add_u32 m0, s27, 73728
	v_lshl_add_u64 v[156:157], v[194:195], 0, s[20:21]
	global_load_lds_dwordx4 v[156:157], off
	v_mfma_f32_32x32x16_bf16 v[32:47], v[132:135], v[140:143], v[32:47]
	s_add_u32 m0, s27, 106496
	v_lshl_add_u64 v[152:153], v[194:195], 0, s[24:25]
	global_load_lds_dwordx4 v[152:153], off
	v_mfma_f32_32x32x16_bf16 v[80:95], v[128:131], v[144:147], v[80:95]
	s_add_u32 m0, s27, 81920
	v_lshl_add_u64 v[154:155], v[196:197], 0, s[20:21]
	global_load_lds_dwordx4 v[154:155], off
	v_mfma_f32_32x32x16_bf16 v[16:31], v[132:135], v[144:147], v[16:31]
	s_add_u32 m0, s27, 114688
	v_lshl_add_u64 v[156:157], v[196:197], 0, s[24:25]
	global_load_lds_dwordx4 v[156:157], off
	v_mfma_f32_32x32x16_bf16 v[64:79], v[128:131], v[148:151], v[64:79]
	s_add_u32 m0, s27, 90112
	v_lshl_add_u64 v[152:153], v[198:199], 0, s[20:21]
	global_load_lds_dwordx4 v[152:153], off
	v_mfma_f32_32x32x16_bf16 v[0:15], v[132:135], v[148:151], v[0:15]
	s_add_u32 m0, s27, 122880
	v_lshl_add_u64 v[154:155], v[198:199], 0, s[24:25]
	global_load_lds_dwordx4 v[154:155], off
	ds_read_b128 v[128:131], v185
	ds_read_b128 v[136:139], v189
	ds_read_b128 v[132:135], v185 offset:4096
	ds_read_b128 v[140:143], v189 offset:4096
	ds_read_b128 v[144:147], v189 offset:8192
	ds_read_b128 v[148:151], v189 offset:12288
	s_waitcnt lgkmcnt(6)
	v_mfma_f32_32x32x16_bf16 v[112:127], v[160:163], v[168:171], v[112:127]
	v_mfma_f32_32x32x16_bf16 v[48:63], v[164:167], v[168:171], v[48:63]
	v_mfma_f32_32x32x16_bf16 v[96:111], v[160:163], v[172:175], v[96:111]
	v_mfma_f32_32x32x16_bf16 v[32:47], v[164:167], v[172:175], v[32:47]
	v_mfma_f32_32x32x16_bf16 v[80:95], v[160:163], v[176:179], v[80:95]
	v_mfma_f32_32x32x16_bf16 v[16:31], v[164:167], v[176:179], v[16:31]
	v_mfma_f32_32x32x16_bf16 v[64:79], v[160:163], v[180:183], v[64:79]
	v_mfma_f32_32x32x16_bf16 v[0:15], v[164:167], v[180:183], v[0:15]
	ds_read_b128 v[160:163], v186
	ds_read_b128 v[168:171], v190
	ds_read_b128 v[164:167], v186 offset:4096
	ds_read_b128 v[172:175], v190 offset:4096
	ds_read_b128 v[176:179], v190 offset:8192
	ds_read_b128 v[180:183], v190 offset:12288
	s_waitcnt lgkmcnt(6)
	v_mfma_f32_32x32x16_bf16 v[112:127], v[128:131], v[136:139], v[112:127]
	v_mfma_f32_32x32x16_bf16 v[48:63], v[132:135], v[136:139], v[48:63]
	v_mfma_f32_32x32x16_bf16 v[96:111], v[128:131], v[140:143], v[96:111]
	v_mfma_f32_32x32x16_bf16 v[32:47], v[132:135], v[140:143], v[32:47]
	v_mfma_f32_32x32x16_bf16 v[80:95], v[128:131], v[144:147], v[80:95]
	v_mfma_f32_32x32x16_bf16 v[16:31], v[132:135], v[144:147], v[16:31]
	v_mfma_f32_32x32x16_bf16 v[64:79], v[128:131], v[148:151], v[64:79]
	v_mfma_f32_32x32x16_bf16 v[0:15], v[132:135], v[148:151], v[0:15]
	ds_read_b128 v[128:131], v187
	ds_read_b128 v[136:139], v191
	ds_read_b128 v[132:135], v187 offset:4096
	ds_read_b128 v[140:143], v191 offset:4096
	ds_read_b128 v[144:147], v191 offset:8192
	ds_read_b128 v[148:151], v191 offset:12288
	s_waitcnt lgkmcnt(6)
	v_mfma_f32_32x32x16_bf16 v[112:127], v[160:163], v[168:171], v[112:127]
	v_mfma_f32_32x32x16_bf16 v[48:63], v[164:167], v[168:171], v[48:63]
	v_mfma_f32_32x32x16_bf16 v[96:111], v[160:163], v[172:175], v[96:111]
	v_mfma_f32_32x32x16_bf16 v[32:47], v[164:167], v[172:175], v[32:47]
	v_mfma_f32_32x32x16_bf16 v[80:95], v[160:163], v[176:179], v[80:95]
	v_mfma_f32_32x32x16_bf16 v[16:31], v[164:167], v[176:179], v[16:31]
	v_mfma_f32_32x32x16_bf16 v[64:79], v[160:163], v[180:183], v[64:79]
	v_mfma_f32_32x32x16_bf16 v[0:15], v[164:167], v[180:183], v[0:15]
	s_waitcnt vmcnt(0) lgkmcnt(0)
	s_barrier
	v_xor_b32_e32 v184, 0x10000, v184
	v_xor_b32_e32 v188, 0x10000, v188
	ds_read_b128 v[160:163], v184
	ds_read_b128 v[168:171], v188
	ds_read_b128 v[164:167], v184 offset:4096
	ds_read_b128 v[172:175], v188 offset:4096
	ds_read_b128 v[176:179], v188 offset:8192
	ds_read_b128 v[180:183], v188 offset:12288
	s_add_u32 s20, s16, 1792
	s_addc_u32 s21, s17, 0
	s_add_u32 s24, s18, 1792
	s_addc_u32 s25, s19, 0
	v_mfma_f32_32x32x16_bf16 v[112:127], v[128:131], v[136:139], v[112:127]
	v_xor_b32_e32 v185, 0x10000, v185
	v_xor_b32_e32 v189, 0x10000, v189
	s_add_u32 m0, s27, 0
	v_lshl_add_u64 v[152:153], v[192:193], 0, s[20:21]
	global_load_lds_dwordx4 v[152:153], off
	v_mfma_f32_32x32x16_bf16 v[48:63], v[132:135], v[136:139], v[48:63]
	v_xor_b32_e32 v186, 0x10000, v186
	v_xor_b32_e32 v190, 0x10000, v190
	s_add_u32 m0, s27, 32768
	v_lshl_add_u64 v[154:155], v[192:193], 0, s[24:25]
	global_load_lds_dwordx4 v[154:155], off
	v_mfma_f32_32x32x16_bf16 v[96:111], v[128:131], v[140:143], v[96:111]
	v_xor_b32_e32 v187, 0x10000, v187
	v_xor_b32_e32 v191, 0x10000, v191
	s_add_u32 m0, s27, 8192
	v_lshl_add_u64 v[156:157], v[194:195], 0, s[20:21]
	global_load_lds_dwordx4 v[156:157], off
	v_mfma_f32_32x32x16_bf16 v[32:47], v[132:135], v[140:143], v[32:47]
	s_add_u32 m0, s27, 40960
	v_lshl_add_u64 v[152:153], v[194:195], 0, s[24:25]
	global_load_lds_dwordx4 v[152:153], off
	v_mfma_f32_32x32x16_bf16 v[80:95], v[128:131], v[144:147], v[80:95]
	s_add_u32 m0, s27, 16384
	v_lshl_add_u64 v[154:155], v[196:197], 0, s[20:21]
	global_load_lds_dwordx4 v[154:155], off
	v_mfma_f32_32x32x16_bf16 v[16:31], v[132:135], v[144:147], v[16:31]
	s_add_u32 m0, s27, 49152
	v_lshl_add_u64 v[156:157], v[196:197], 0, s[24:25]
	global_load_lds_dwordx4 v[156:157], off
	v_mfma_f32_32x32x16_bf16 v[64:79], v[128:131], v[148:151], v[64:79]
	s_add_u32 m0, s27, 24576
	v_lshl_add_u64 v[152:153], v[198:199], 0, s[20:21]
	global_load_lds_dwordx4 v[152:153], off
	v_mfma_f32_32x32x16_bf16 v[0:15], v[132:135], v[148:151], v[0:15]
	s_add_u32 m0, s27, 57344
	v_lshl_add_u64 v[154:155], v[198:199], 0, s[24:25]
	global_load_lds_dwordx4 v[154:155], off
	ds_read_b128 v[128:131], v185
	ds_read_b128 v[136:139], v189
	ds_read_b128 v[132:135], v185 offset:4096
	ds_read_b128 v[140:143], v189 offset:4096
	ds_read_b128 v[144:147], v189 offset:8192
	ds_read_b128 v[148:151], v189 offset:12288
	s_waitcnt lgkmcnt(6)
	v_mfma_f32_32x32x16_bf16 v[112:127], v[160:163], v[168:171], v[112:127]
	v_mfma_f32_32x32x16_bf16 v[48:63], v[164:167], v[168:171], v[48:63]
	v_mfma_f32_32x32x16_bf16 v[96:111], v[160:163], v[172:175], v[96:111]
	v_mfma_f32_32x32x16_bf16 v[32:47], v[164:167], v[172:175], v[32:47]
	v_mfma_f32_32x32x16_bf16 v[80:95], v[160:163], v[176:179], v[80:95]
	v_mfma_f32_32x32x16_bf16 v[16:31], v[164:167], v[176:179], v[16:31]
	v_mfma_f32_32x32x16_bf16 v[64:79], v[160:163], v[180:183], v[64:79]
	v_mfma_f32_32x32x16_bf16 v[0:15], v[164:167], v[180:183], v[0:15]
	ds_read_b128 v[160:163], v186
	ds_read_b128 v[168:171], v190
	ds_read_b128 v[164:167], v186 offset:4096
	ds_read_b128 v[172:175], v190 offset:4096
	ds_read_b128 v[176:179], v190 offset:8192
	ds_read_b128 v[180:183], v190 offset:12288
	s_waitcnt lgkmcnt(6)
	v_mfma_f32_32x32x16_bf16 v[112:127], v[128:131], v[136:139], v[112:127]
	v_mfma_f32_32x32x16_bf16 v[48:63], v[132:135], v[136:139], v[48:63]
	v_mfma_f32_32x32x16_bf16 v[96:111], v[128:131], v[140:143], v[96:111]
	v_mfma_f32_32x32x16_bf16 v[32:47], v[132:135], v[140:143], v[32:47]
	v_mfma_f32_32x32x16_bf16 v[80:95], v[128:131], v[144:147], v[80:95]
	v_mfma_f32_32x32x16_bf16 v[16:31], v[132:135], v[144:147], v[16:31]
	v_mfma_f32_32x32x16_bf16 v[64:79], v[128:131], v[148:151], v[64:79]
	v_mfma_f32_32x32x16_bf16 v[0:15], v[132:135], v[148:151], v[0:15]
	ds_read_b128 v[128:131], v187
	ds_read_b128 v[136:139], v191
	ds_read_b128 v[132:135], v187 offset:4096
	ds_read_b128 v[140:143], v191 offset:4096
	ds_read_b128 v[144:147], v191 offset:8192
	ds_read_b128 v[148:151], v191 offset:12288
	s_waitcnt lgkmcnt(6)
	v_mfma_f32_32x32x16_bf16 v[112:127], v[160:163], v[168:171], v[112:127]
	v_mfma_f32_32x32x16_bf16 v[48:63], v[164:167], v[168:171], v[48:63]
	v_mfma_f32_32x32x16_bf16 v[96:111], v[160:163], v[172:175], v[96:111]
	v_mfma_f32_32x32x16_bf16 v[32:47], v[164:167], v[172:175], v[32:47]
	v_mfma_f32_32x32x16_bf16 v[80:95], v[160:163], v[176:179], v[80:95]
	v_mfma_f32_32x32x16_bf16 v[16:31], v[164:167], v[176:179], v[16:31]
	v_mfma_f32_32x32x16_bf16 v[64:79], v[160:163], v[180:183], v[64:79]
	v_mfma_f32_32x32x16_bf16 v[0:15], v[164:167], v[180:183], v[0:15]
	s_waitcnt vmcnt(0) lgkmcnt(0)
	s_barrier
	v_xor_b32_e32 v184, 0x10000, v184
	v_xor_b32_e32 v188, 0x10000, v188
	ds_read_b128 v[160:163], v184
	ds_read_b128 v[168:171], v188
	ds_read_b128 v[164:167], v184 offset:4096
	ds_read_b128 v[172:175], v188 offset:4096
	ds_read_b128 v[176:179], v188 offset:8192
	ds_read_b128 v[180:183], v188 offset:12288
	s_add_u32 s20, s16, 1920
	s_addc_u32 s21, s17, 0
	s_add_u32 s24, s18, 1920
	s_addc_u32 s25, s19, 0
	v_mfma_f32_32x32x16_bf16 v[112:127], v[128:131], v[136:139], v[112:127]
	v_xor_b32_e32 v185, 0x10000, v185
	v_xor_b32_e32 v189, 0x10000, v189
	s_add_u32 m0, s27, 65536
	v_lshl_add_u64 v[152:153], v[192:193], 0, s[20:21]
	global_load_lds_dwordx4 v[152:153], off
	v_mfma_f32_32x32x16_bf16 v[48:63], v[132:135], v[136:139], v[48:63]
	v_xor_b32_e32 v186, 0x10000, v186
	v_xor_b32_e32 v190, 0x10000, v190
	s_add_u32 m0, s27, 98304
	v_lshl_add_u64 v[154:155], v[192:193], 0, s[24:25]
	global_load_lds_dwordx4 v[154:155], off
	v_mfma_f32_32x32x16_bf16 v[96:111], v[128:131], v[140:143], v[96:111]
	v_xor_b32_e32 v187, 0x10000, v187
	v_xor_b32_e32 v191, 0x10000, v191
	s_add_u32 m0, s27, 73728
	v_lshl_add_u64 v[156:157], v[194:195], 0, s[20:21]
	global_load_lds_dwordx4 v[156:157], off
	v_mfma_f32_32x32x16_bf16 v[32:47], v[132:135], v[140:143], v[32:47]
	s_add_u32 m0, s27, 106496
	v_lshl_add_u64 v[152:153], v[194:195], 0, s[24:25]
	global_load_lds_dwordx4 v[152:153], off
	v_mfma_f32_32x32x16_bf16 v[80:95], v[128:131], v[144:147], v[80:95]
	s_add_u32 m0, s27, 81920
	v_lshl_add_u64 v[154:155], v[196:197], 0, s[20:21]
	global_load_lds_dwordx4 v[154:155], off
	v_mfma_f32_32x32x16_bf16 v[16:31], v[132:135], v[144:147], v[16:31]
	s_add_u32 m0, s27, 114688
	v_lshl_add_u64 v[156:157], v[196:197], 0, s[24:25]
	global_load_lds_dwordx4 v[156:157], off
	v_mfma_f32_32x32x16_bf16 v[64:79], v[128:131], v[148:151], v[64:79]
	s_add_u32 m0, s27, 90112
	v_lshl_add_u64 v[152:153], v[198:199], 0, s[20:21]
	global_load_lds_dwordx4 v[152:153], off
	v_mfma_f32_32x32x16_bf16 v[0:15], v[132:135], v[148:151], v[0:15]
	s_add_u32 m0, s27, 122880
	v_lshl_add_u64 v[154:155], v[198:199], 0, s[24:25]
	global_load_lds_dwordx4 v[154:155], off
	ds_read_b128 v[128:131], v185
	ds_read_b128 v[136:139], v189
	ds_read_b128 v[132:135], v185 offset:4096
	ds_read_b128 v[140:143], v189 offset:4096
	ds_read_b128 v[144:147], v189 offset:8192
	ds_read_b128 v[148:151], v189 offset:12288
	s_waitcnt lgkmcnt(6)
	v_mfma_f32_32x32x16_bf16 v[112:127], v[160:163], v[168:171], v[112:127]
	v_mfma_f32_32x32x16_bf16 v[48:63], v[164:167], v[168:171], v[48:63]
	v_mfma_f32_32x32x16_bf16 v[96:111], v[160:163], v[172:175], v[96:111]
	v_mfma_f32_32x32x16_bf16 v[32:47], v[164:167], v[172:175], v[32:47]
	v_mfma_f32_32x32x16_bf16 v[80:95], v[160:163], v[176:179], v[80:95]
	v_mfma_f32_32x32x16_bf16 v[16:31], v[164:167], v[176:179], v[16:31]
	v_mfma_f32_32x32x16_bf16 v[64:79], v[160:163], v[180:183], v[64:79]
	v_mfma_f32_32x32x16_bf16 v[0:15], v[164:167], v[180:183], v[0:15]
	ds_read_b128 v[160:163], v186
	ds_read_b128 v[168:171], v190
	ds_read_b128 v[164:167], v186 offset:4096
	ds_read_b128 v[172:175], v190 offset:4096
	ds_read_b128 v[176:179], v190 offset:8192
	ds_read_b128 v[180:183], v190 offset:12288
	s_waitcnt lgkmcnt(6)
	v_mfma_f32_32x32x16_bf16 v[112:127], v[128:131], v[136:139], v[112:127]
	v_mfma_f32_32x32x16_bf16 v[48:63], v[132:135], v[136:139], v[48:63]
	v_mfma_f32_32x32x16_bf16 v[96:111], v[128:131], v[140:143], v[96:111]
	v_mfma_f32_32x32x16_bf16 v[32:47], v[132:135], v[140:143], v[32:47]
	v_mfma_f32_32x32x16_bf16 v[80:95], v[128:131], v[144:147], v[80:95]
	v_mfma_f32_32x32x16_bf16 v[16:31], v[132:135], v[144:147], v[16:31]
	v_mfma_f32_32x32x16_bf16 v[64:79], v[128:131], v[148:151], v[64:79]
	v_mfma_f32_32x32x16_bf16 v[0:15], v[132:135], v[148:151], v[0:15]
	ds_read_b128 v[128:131], v187
	ds_read_b128 v[136:139], v191
	ds_read_b128 v[132:135], v187 offset:4096
	ds_read_b128 v[140:143], v191 offset:4096
	ds_read_b128 v[144:147], v191 offset:8192
	ds_read_b128 v[148:151], v191 offset:12288
	s_waitcnt lgkmcnt(6)
	v_mfma_f32_32x32x16_bf16 v[112:127], v[160:163], v[168:171], v[112:127]
	v_mfma_f32_32x32x16_bf16 v[48:63], v[164:167], v[168:171], v[48:63]
	v_mfma_f32_32x32x16_bf16 v[96:111], v[160:163], v[172:175], v[96:111]
	v_mfma_f32_32x32x16_bf16 v[32:47], v[164:167], v[172:175], v[32:47]
	v_mfma_f32_32x32x16_bf16 v[80:95], v[160:163], v[176:179], v[80:95]
	v_mfma_f32_32x32x16_bf16 v[16:31], v[164:167], v[176:179], v[16:31]
	v_mfma_f32_32x32x16_bf16 v[64:79], v[160:163], v[180:183], v[64:79]
	v_mfma_f32_32x32x16_bf16 v[0:15], v[164:167], v[180:183], v[0:15]
	s_waitcnt vmcnt(0) lgkmcnt(0)
	s_barrier
	v_xor_b32_e32 v184, 0x10000, v184
	v_xor_b32_e32 v188, 0x10000, v188
	ds_read_b128 v[160:163], v184
	ds_read_b128 v[168:171], v188
	ds_read_b128 v[164:167], v184 offset:4096
	ds_read_b128 v[172:175], v188 offset:4096
	ds_read_b128 v[176:179], v188 offset:8192
	ds_read_b128 v[180:183], v188 offset:12288
	s_add_u32 s37, s30, s42
	s_cmpk_ge_u32 s37, 0x780
	s_cbranch_scc1 .Lip11_full_nonext
	s_mul_hi_u32 s38, s37, 0x92492493
	s_lshr_b32 s38, s38, 3
	s_mul_i32 s39, s38, 14
	s_sub_u32 s39, s37, s39
	s_sub_u32 s98, s37, 0x700
	s_cmpk_lt_u32 s37, 0x700
	s_cselect_b32 s39, s39, 14
	s_cselect_b32 s38, s38, s98
	s_lshl_b32 s98, s38, 19
	s_add_u32 s16, s4, s98
	s_addc_u32 s17, s5, 0
	s_lshl_b32 s98, s39, 19
	s_add_u32 s18, s6, s98
	s_addc_u32 s19, s7, 0
	v_mfma_f32_32x32x16_bf16 v[112:127], v[128:131], v[136:139], v[112:127]
	v_xor_b32_e32 v185, 0x10000, v185
	v_xor_b32_e32 v189, 0x10000, v189
	s_add_u32 m0, s27, 0
	v_lshl_add_u64 v[152:153], v[192:193], 0, s[16:17]
	global_load_lds_dwordx4 v[152:153], off
	v_mfma_f32_32x32x16_bf16 v[48:63], v[132:135], v[136:139], v[48:63]
	v_xor_b32_e32 v186, 0x10000, v186
	v_xor_b32_e32 v190, 0x10000, v190
	s_add_u32 m0, s27, 32768
	v_lshl_add_u64 v[154:155], v[192:193], 0, s[18:19]
	global_load_lds_dwordx4 v[154:155], off
	v_mfma_f32_32x32x16_bf16 v[96:111], v[128:131], v[140:143], v[96:111]
	v_xor_b32_e32 v187, 0x10000, v187
	v_xor_b32_e32 v191, 0x10000, v191
	s_add_u32 m0, s27, 8192
	v_lshl_add_u64 v[156:157], v[194:195], 0, s[16:17]
	global_load_lds_dwordx4 v[156:157], off
	v_mfma_f32_32x32x16_bf16 v[32:47], v[132:135], v[140:143], v[32:47]
	s_add_u32 m0, s27, 40960
	v_lshl_add_u64 v[152:153], v[194:195], 0, s[18:19]
	global_load_lds_dwordx4 v[152:153], off
	v_mfma_f32_32x32x16_bf16 v[80:95], v[128:131], v[144:147], v[80:95]
	s_add_u32 m0, s27, 16384
	v_lshl_add_u64 v[154:155], v[196:197], 0, s[16:17]
	global_load_lds_dwordx4 v[154:155], off
	v_mfma_f32_32x32x16_bf16 v[16:31], v[132:135], v[144:147], v[16:31]
	s_add_u32 m0, s27, 49152
	v_lshl_add_u64 v[156:157], v[196:197], 0, s[18:19]
	global_load_lds_dwordx4 v[156:157], off
	v_mfma_f32_32x32x16_bf16 v[64:79], v[128:131], v[148:151], v[64:79]
	s_add_u32 m0, s27, 24576
	v_lshl_add_u64 v[152:153], v[198:199], 0, s[16:17]
	global_load_lds_dwordx4 v[152:153], off
	v_mfma_f32_32x32x16_bf16 v[0:15], v[132:135], v[148:151], v[0:15]
	s_add_u32 m0, s27, 57344
	v_lshl_add_u64 v[154:155], v[198:199], 0, s[18:19]
	global_load_lds_dwordx4 v[154:155], off
	s_branch .Lip11_full_join

.Lip11_full_join:
	ds_read_b128 v[128:131], v185
	ds_read_b128 v[136:139], v189
	ds_read_b128 v[132:135], v185 offset:4096
	ds_read_b128 v[140:143], v189 offset:4096
	ds_read_b128 v[144:147], v189 offset:8192
	ds_read_b128 v[148:151], v189 offset:12288
	s_waitcnt lgkmcnt(6)
	v_mfma_f32_32x32x16_bf16 v[112:127], v[160:163], v[168:171], v[112:127]
	v_mfma_f32_32x32x16_bf16 v[48:63], v[164:167], v[168:171], v[48:63]
	v_mfma_f32_32x32x16_bf16 v[96:111], v[160:163], v[172:175], v[96:111]
	v_mfma_f32_32x32x16_bf16 v[32:47], v[164:167], v[172:175], v[32:47]
	v_mfma_f32_32x32x16_bf16 v[80:95], v[160:163], v[176:179], v[80:95]
	v_mfma_f32_32x32x16_bf16 v[16:31], v[164:167], v[176:179], v[16:31]
	v_mfma_f32_32x32x16_bf16 v[64:79], v[160:163], v[180:183], v[64:79]
	v_mfma_f32_32x32x16_bf16 v[0:15], v[164:167], v[180:183], v[0:15]
	ds_read_b128 v[160:163], v186
	ds_read_b128 v[168:171], v190
	ds_read_b128 v[164:167], v186 offset:4096
	ds_read_b128 v[172:175], v190 offset:4096
	ds_read_b128 v[176:179], v190 offset:8192
	ds_read_b128 v[180:183], v190 offset:12288
	s_waitcnt lgkmcnt(6)
	v_mfma_f32_32x32x16_bf16 v[112:127], v[128:131], v[136:139], v[112:127]
	v_mfma_f32_32x32x16_bf16 v[48:63], v[132:135], v[136:139], v[48:63]
	v_mfma_f32_32x32x16_bf16 v[96:111], v[128:131], v[140:143], v[96:111]
	v_mfma_f32_32x32x16_bf16 v[32:47], v[132:135], v[140:143], v[32:47]
	v_mfma_f32_32x32x16_bf16 v[80:95], v[128:131], v[144:147], v[80:95]
	v_mfma_f32_32x32x16_bf16 v[16:31], v[132:135], v[144:147], v[16:31]
	v_mfma_f32_32x32x16_bf16 v[64:79], v[128:131], v[148:151], v[64:79]
	v_mfma_f32_32x32x16_bf16 v[0:15], v[132:135], v[148:151], v[0:15]
	ds_read_b128 v[128:131], v187
	ds_read_b128 v[136:139], v191
	ds_read_b128 v[132:135], v187 offset:4096
	ds_read_b128 v[140:143], v191 offset:4096
	ds_read_b128 v[144:147], v191 offset:8192
	ds_read_b128 v[148:151], v191 offset:12288
	s_waitcnt lgkmcnt(6)
	v_mfma_f32_32x32x16_bf16 v[112:127], v[160:163], v[168:171], v[112:127]
	v_mfma_f32_32x32x16_bf16 v[48:63], v[164:167], v[168:171], v[48:63]
	v_mfma_f32_32x32x16_bf16 v[96:111], v[160:163], v[172:175], v[96:111]
	v_mfma_f32_32x32x16_bf16 v[32:47], v[164:167], v[172:175], v[32:47]
	v_mfma_f32_32x32x16_bf16 v[80:95], v[160:163], v[176:179], v[80:95]
	v_mfma_f32_32x32x16_bf16 v[16:31], v[164:167], v[176:179], v[16:31]
	v_mfma_f32_32x32x16_bf16 v[64:79], v[160:163], v[180:183], v[64:79]
	v_mfma_f32_32x32x16_bf16 v[0:15], v[164:167], v[180:183], v[0:15]
	s_waitcnt vmcnt(0) lgkmcnt(0)
	s_barrier
	v_xor_b32_e32 v184, 0x10000, v184
	v_xor_b32_e32 v188, 0x10000, v188
	v_mfma_f32_32x32x16_bf16 v[112:127], v[128:131], v[136:139], v[112:127]
	v_xor_b32_e32 v185, 0x10000, v185
	v_xor_b32_e32 v189, 0x10000, v189
	v_mfma_f32_32x32x16_bf16 v[48:63], v[132:135], v[136:139], v[48:63]
	v_xor_b32_e32 v186, 0x10000, v186
	v_xor_b32_e32 v190, 0x10000, v190
	v_mfma_f32_32x32x16_bf16 v[96:111], v[128:131], v[140:143], v[96:111]
	v_xor_b32_e32 v187, 0x10000, v187
	v_xor_b32_e32 v191, 0x10000, v191
	v_mfma_f32_32x32x16_bf16 v[32:47], v[132:135], v[140:143], v[32:47]
	v_mfma_f32_32x32x16_bf16 v[80:95], v[128:131], v[144:147], v[80:95]
	v_mfma_f32_32x32x16_bf16 v[16:31], v[132:135], v[144:147], v[16:31]
	v_mfma_f32_32x32x16_bf16 v[64:79], v[128:131], v[148:151], v[64:79]
	v_mfma_f32_32x32x16_bf16 v[0:15], v[132:135], v[148:151], v[0:15]
	s_branch .Lip11_epi
.Lip11_light:
	s_cmp_eq_u32 s31, 0
	s_cbranch_scc0 .Lip11_lload
	ds_read_b128 v[160:163], v184
	ds_read_b128 v[168:171], v188
	ds_read_b128 v[164:167], v184 offset:4096
	ds_read_b128 v[172:175], v188 offset:4096
	ds_read_b128 v[128:131], v185
	ds_read_b128 v[136:139], v189
	ds_read_b128 v[132:135], v185 offset:4096
	ds_read_b128 v[140:143], v189 offset:4096
	s_waitcnt lgkmcnt(4)
	v_mfma_f32_32x32x16_bf16 v[112:127], v[160:163], v[168:171], 0
	v_mfma_f32_32x32x16_bf16 v[48:63], v[164:167], v[168:171], 0
	v_mfma_f32_32x32x16_bf16 v[96:111], v[160:163], v[172:175], 0
	v_mfma_f32_32x32x16_bf16 v[32:47], v[164:167], v[172:175], 0
	ds_read_b128 v[160:163], v186
	ds_read_b128 v[168:171], v190
	ds_read_b128 v[164:167], v186 offset:4096
	ds_read_b128 v[172:175], v190 offset:4096
	s_waitcnt lgkmcnt(4)
	v_mfma_f32_32x32x16_bf16 v[112:127], v[128:131], v[136:139], v[112:127]
	v_mfma_f32_32x32x16_bf16 v[48:63], v[132:135], v[136:139], v[48:63]
	v_mfma_f32_32x32x16_bf16 v[96:111], v[128:131], v[140:143], v[96:111]
	v_mfma_f32_32x32x16_bf16 v[32:47], v[132:135], v[140:143], v[32:47]
	ds_read_b128 v[128:131], v187
	ds_read_b128 v[136:139], v191
	ds_read_b128 v[132:135], v187 offset:4096
	ds_read_b128 v[140:143], v191 offset:4096
	s_waitcnt lgkmcnt(4)
	v_mfma_f32_32x32x16_bf16 v[112:127], v[160:163], v[168:171], v[112:127]
	v_mfma_f32_32x32x16_bf16 v[48:63], v[164:167], v[168:171], v[48:63]
	v_mfma_f32_32x32x16_bf16 v[96:111], v[160:163], v[172:175], v[96:111]
	v_mfma_f32_32x32x16_bf16 v[32:47], v[164:167], v[172:175], v[32:47]
	s_waitcnt vmcnt(0) lgkmcnt(0)
	s_barrier
	v_xor_b32_e32 v184, 0x10000, v184
	v_xor_b32_e32 v188, 0x10000, v188
	ds_read_b128 v[160:163], v184
	ds_read_b128 v[168:171], v188
	ds_read_b128 v[164:167], v184 offset:4096
	ds_read_b128 v[172:175], v188 offset:4096
	s_add_u32 s20, s16, 256
	s_addc_u32 s21, s17, 0
	s_add_u32 s24, s18, 256
	s_addc_u32 s25, s19, 0
	v_mfma_f32_32x32x16_bf16 v[112:127], v[128:131], v[136:139], v[112:127]
	v_xor_b32_e32 v185, 0x10000, v185
	v_xor_b32_e32 v189, 0x10000, v189
	s_add_u32 m0, s27, 0
	v_lshl_add_u64 v[152:153], v[192:193], 0, s[20:21]
	global_load_lds_dwordx4 v[152:153], off
	v_mfma_f32_32x32x16_bf16 v[48:63], v[132:135], v[136:139], v[48:63]
	v_xor_b32_e32 v186, 0x10000, v186
	v_xor_b32_e32 v190, 0x10000, v190
	s_add_u32 m0, s27, 32768
	v_lshl_add_u64 v[154:155], v[192:193], 0, s[24:25]
	global_load_lds_dwordx4 v[154:155], off
	v_mfma_f32_32x32x16_bf16 v[96:111], v[128:131], v[140:143], v[96:111]
	v_xor_b32_e32 v187, 0x10000, v187
	v_xor_b32_e32 v191, 0x10000, v191
	s_add_u32 m0, s27, 8192
	v_lshl_add_u64 v[156:157], v[194:195], 0, s[20:21]
	global_load_lds_dwordx4 v[156:157], off
	v_mfma_f32_32x32x16_bf16 v[32:47], v[132:135], v[140:143], v[32:47]
	s_add_u32 m0, s27, 40960
	v_lshl_add_u64 v[152:153], v[194:195], 0, s[24:25]
	global_load_lds_dwordx4 v[152:153], off
	s_add_u32 m0, s27, 16384
	v_lshl_add_u64 v[154:155], v[196:197], 0, s[20:21]
	global_load_lds_dwordx4 v[154:155], off
	s_add_u32 m0, s27, 49152
	v_lshl_add_u64 v[156:157], v[196:197], 0, s[24:25]
	global_load_lds_dwordx4 v[156:157], off
	s_add_u32 m0, s27, 24576
	v_lshl_add_u64 v[152:153], v[198:199], 0, s[20:21]
	global_load_lds_dwordx4 v[152:153], off
	s_add_u32 m0, s27, 57344
	v_lshl_add_u64 v[154:155], v[198:199], 0, s[24:25]
	global_load_lds_dwordx4 v[154:155], off
	ds_read_b128 v[128:131], v185
	ds_read_b128 v[136:139], v189
	ds_read_b128 v[132:135], v185 offset:4096
	ds_read_b128 v[140:143], v189 offset:4096
	s_waitcnt lgkmcnt(4)
	v_mfma_f32_32x32x16_bf16 v[112:127], v[160:163], v[168:171], v[112:127]
	v_mfma_f32_32x32x16_bf16 v[48:63], v[164:167], v[168:171], v[48:63]
	v_mfma_f32_32x32x16_bf16 v[96:111], v[160:163], v[172:175], v[96:111]
	v_mfma_f32_32x32x16_bf16 v[32:47], v[164:167], v[172:175], v[32:47]
	ds_read_b128 v[160:163], v186
	ds_read_b128 v[168:171], v190
	ds_read_b128 v[164:167], v186 offset:4096
	ds_read_b128 v[172:175], v190 offset:4096
	s_waitcnt lgkmcnt(4)
	v_mfma_f32_32x32x16_bf16 v[112:127], v[128:131], v[136:139], v[112:127]
	v_mfma_f32_32x32x16_bf16 v[48:63], v[132:135], v[136:139], v[48:63]
	v_mfma_f32_32x32x16_bf16 v[96:111], v[128:131], v[140:143], v[96:111]
	v_mfma_f32_32x32x16_bf16 v[32:47], v[132:135], v[140:143], v[32:47]
	ds_read_b128 v[128:131], v187
	ds_read_b128 v[136:139], v191
	ds_read_b128 v[132:135], v187 offset:4096
	ds_read_b128 v[140:143], v191 offset:4096
	s_waitcnt lgkmcnt(4)
	v_mfma_f32_32x32x16_bf16 v[112:127], v[160:163], v[168:171], v[112:127]
	v_mfma_f32_32x32x16_bf16 v[48:63], v[164:167], v[168:171], v[48:63]
	v_mfma_f32_32x32x16_bf16 v[96:111], v[160:163], v[172:175], v[96:111]
	v_mfma_f32_32x32x16_bf16 v[32:47], v[164:167], v[172:175], v[32:47]
	s_waitcnt vmcnt(0) lgkmcnt(0)
	s_barrier
	v_xor_b32_e32 v184, 0x10000, v184
	v_xor_b32_e32 v188, 0x10000, v188
	ds_read_b128 v[160:163], v184
	ds_read_b128 v[168:171], v188
	ds_read_b128 v[164:167], v184 offset:4096
	ds_read_b128 v[172:175], v188 offset:4096
	s_add_u32 s20, s16, 384
	s_addc_u32 s21, s17, 0
	s_add_u32 s24, s18, 384
	s_addc_u32 s25, s19, 0
	v_mfma_f32_32x32x16_bf16 v[112:127], v[128:131], v[136:139], v[112:127]
	v_xor_b32_e32 v185, 0x10000, v185
	v_xor_b32_e32 v189, 0x10000, v189
	s_add_u32 m0, s27, 65536
	v_lshl_add_u64 v[152:153], v[192:193], 0, s[20:21]
	global_load_lds_dwordx4 v[152:153], off
	v_mfma_f32_32x32x16_bf16 v[48:63], v[132:135], v[136:139], v[48:63]
	v_xor_b32_e32 v186, 0x10000, v186
	v_xor_b32_e32 v190, 0x10000, v190
	s_add_u32 m0, s27, 98304
	v_lshl_add_u64 v[154:155], v[192:193], 0, s[24:25]
	global_load_lds_dwordx4 v[154:155], off
	v_mfma_f32_32x32x16_bf16 v[96:111], v[128:131], v[140:143], v[96:111]
	v_xor_b32_e32 v187, 0x10000, v187
	v_xor_b32_e32 v191, 0x10000, v191
	s_add_u32 m0, s27, 73728
	v_lshl_add_u64 v[156:157], v[194:195], 0, s[20:21]
	global_load_lds_dwordx4 v[156:157], off
	v_mfma_f32_32x32x16_bf16 v[32:47], v[132:135], v[140:143], v[32:47]
	s_add_u32 m0, s27, 106496
	v_lshl_add_u64 v[152:153], v[194:195], 0, s[24:25]
	global_load_lds_dwordx4 v[152:153], off
	s_add_u32 m0, s27, 81920
	v_lshl_add_u64 v[154:155], v[196:197], 0, s[20:21]
	global_load_lds_dwordx4 v[154:155], off
	s_add_u32 m0, s27, 114688
	v_lshl_add_u64 v[156:157], v[196:197], 0, s[24:25]
	global_load_lds_dwordx4 v[156:157], off
	s_add_u32 m0, s27, 90112
	v_lshl_add_u64 v[152:153], v[198:199], 0, s[20:21]
	global_load_lds_dwordx4 v[152:153], off
	s_add_u32 m0, s27, 122880
	v_lshl_add_u64 v[154:155], v[198:199], 0, s[24:25]
	global_load_lds_dwordx4 v[154:155], off
	ds_read_b128 v[128:131], v185
	ds_read_b128 v[136:139], v189
	ds_read_b128 v[132:135], v185 offset:4096
	ds_read_b128 v[140:143], v189 offset:4096
	s_waitcnt lgkmcnt(4)
	v_mfma_f32_32x32x16_bf16 v[112:127], v[160:163], v[168:171], v[112:127]
	v_mfma_f32_32x32x16_bf16 v[48:63], v[164:167], v[168:171], v[48:63]
	v_mfma_f32_32x32x16_bf16 v[96:111], v[160:163], v[172:175], v[96:111]
	v_mfma_f32_32x32x16_bf16 v[32:47], v[164:167], v[172:175], v[32:47]
	ds_read_b128 v[160:163], v186
	ds_read_b128 v[168:171], v190
	ds_read_b128 v[164:167], v186 offset:4096
	ds_read_b128 v[172:175], v190 offset:4096
	s_waitcnt lgkmcnt(4)
	v_mfma_f32_32x32x16_bf16 v[112:127], v[128:131], v[136:139], v[112:127]
	v_mfma_f32_32x32x16_bf16 v[48:63], v[132:135], v[136:139], v[48:63]
	v_mfma_f32_32x32x16_bf16 v[96:111], v[128:131], v[140:143], v[96:111]
	v_mfma_f32_32x32x16_bf16 v[32:47], v[132:135], v[140:143], v[32:47]
	ds_read_b128 v[128:131], v187
	ds_read_b128 v[136:139], v191
	ds_read_b128 v[132:135], v187 offset:4096
	ds_read_b128 v[140:143], v191 offset:4096
	s_waitcnt lgkmcnt(4)
	v_mfma_f32_32x32x16_bf16 v[112:127], v[160:163], v[168:171], v[112:127]
	v_mfma_f32_32x32x16_bf16 v[48:63], v[164:167], v[168:171], v[48:63]
	v_mfma_f32_32x32x16_bf16 v[96:111], v[160:163], v[172:175], v[96:111]
	v_mfma_f32_32x32x16_bf16 v[32:47], v[164:167], v[172:175], v[32:47]
	s_waitcnt vmcnt(0) lgkmcnt(0)
	s_barrier
	v_xor_b32_e32 v184, 0x10000, v184
	v_xor_b32_e32 v188, 0x10000, v188
	ds_read_b128 v[160:163], v184
	ds_read_b128 v[168:171], v188
	ds_read_b128 v[164:167], v184 offset:4096
	ds_read_b128 v[172:175], v188 offset:4096
	s_add_u32 s20, s16, 512
	s_addc_u32 s21, s17, 0
	s_add_u32 s24, s18, 512
	s_addc_u32 s25, s19, 0
	v_mfma_f32_32x32x16_bf16 v[112:127], v[128:131], v[136:139], v[112:127]
	v_xor_b32_e32 v185, 0x10000, v185
	v_xor_b32_e32 v189, 0x10000, v189
	s_add_u32 m0, s27, 0
	v_lshl_add_u64 v[152:153], v[192:193], 0, s[20:21]
	global_load_lds_dwordx4 v[152:153], off
	v_mfma_f32_32x32x16_bf16 v[48:63], v[132:135], v[136:139], v[48:63]
	v_xor_b32_e32 v186, 0x10000, v186
	v_xor_b32_e32 v190, 0x10000, v190
	s_add_u32 m0, s27, 32768
	v_lshl_add_u64 v[154:155], v[192:193], 0, s[24:25]
	global_load_lds_dwordx4 v[154:155], off
	v_mfma_f32_32x32x16_bf16 v[96:111], v[128:131], v[140:143], v[96:111]
	v_xor_b32_e32 v187, 0x10000, v187
	v_xor_b32_e32 v191, 0x10000, v191
	s_add_u32 m0, s27, 8192
	v_lshl_add_u64 v[156:157], v[194:195], 0, s[20:21]
	global_load_lds_dwordx4 v[156:157], off
	v_mfma_f32_32x32x16_bf16 v[32:47], v[132:135], v[140:143], v[32:47]
	s_add_u32 m0, s27, 40960
	v_lshl_add_u64 v[152:153], v[194:195], 0, s[24:25]
	global_load_lds_dwordx4 v[152:153], off
	s_add_u32 m0, s27, 16384
	v_lshl_add_u64 v[154:155], v[196:197], 0, s[20:21]
	global_load_lds_dwordx4 v[154:155], off
	s_add_u32 m0, s27, 49152
	v_lshl_add_u64 v[156:157], v[196:197], 0, s[24:25]
	global_load_lds_dwordx4 v[156:157], off
	s_add_u32 m0, s27, 24576
	v_lshl_add_u64 v[152:153], v[198:199], 0, s[20:21]
	global_load_lds_dwordx4 v[152:153], off
	s_add_u32 m0, s27, 57344
	v_lshl_add_u64 v[154:155], v[198:199], 0, s[24:25]
	global_load_lds_dwordx4 v[154:155], off
	ds_read_b128 v[128:131], v185
	ds_read_b128 v[136:139], v189
	ds_read_b128 v[132:135], v185 offset:4096
	ds_read_b128 v[140:143], v189 offset:4096
	s_waitcnt lgkmcnt(4)
	v_mfma_f32_32x32x16_bf16 v[112:127], v[160:163], v[168:171], v[112:127]
	v_mfma_f32_32x32x16_bf16 v[48:63], v[164:167], v[168:171], v[48:63]
	v_mfma_f32_32x32x16_bf16 v[96:111], v[160:163], v[172:175], v[96:111]
	v_mfma_f32_32x32x16_bf16 v[32:47], v[164:167], v[172:175], v[32:47]
	ds_read_b128 v[160:163], v186
	ds_read_b128 v[168:171], v190
	ds_read_b128 v[164:167], v186 offset:4096
	ds_read_b128 v[172:175], v190 offset:4096
	s_waitcnt lgkmcnt(4)
	v_mfma_f32_32x32x16_bf16 v[112:127], v[128:131], v[136:139], v[112:127]
	v_mfma_f32_32x32x16_bf16 v[48:63], v[132:135], v[136:139], v[48:63]
	v_mfma_f32_32x32x16_bf16 v[96:111], v[128:131], v[140:143], v[96:111]
	v_mfma_f32_32x32x16_bf16 v[32:47], v[132:135], v[140:143], v[32:47]
	ds_read_b128 v[128:131], v187
	ds_read_b128 v[136:139], v191
	ds_read_b128 v[132:135], v187 offset:4096
	ds_read_b128 v[140:143], v191 offset:4096
	s_waitcnt lgkmcnt(4)
	v_mfma_f32_32x32x16_bf16 v[112:127], v[160:163], v[168:171], v[112:127]
	v_mfma_f32_32x32x16_bf16 v[48:63], v[164:167], v[168:171], v[48:63]
	v_mfma_f32_32x32x16_bf16 v[96:111], v[160:163], v[172:175], v[96:111]
	v_mfma_f32_32x32x16_bf16 v[32:47], v[164:167], v[172:175], v[32:47]
	s_waitcnt vmcnt(0) lgkmcnt(0)
	s_barrier
	v_xor_b32_e32 v184, 0x10000, v184
	v_xor_b32_e32 v188, 0x10000, v188
	ds_read_b128 v[160:163], v184
	ds_read_b128 v[168:171], v188
	ds_read_b128 v[164:167], v184 offset:4096
	ds_read_b128 v[172:175], v188 offset:4096
	s_add_u32 s20, s16, 640
	s_addc_u32 s21, s17, 0
	s_add_u32 s24, s18, 640
	s_addc_u32 s25, s19, 0
	v_mfma_f32_32x32x16_bf16 v[112:127], v[128:131], v[136:139], v[112:127]
	v_xor_b32_e32 v185, 0x10000, v185
	v_xor_b32_e32 v189, 0x10000, v189
	s_add_u32 m0, s27, 65536
	v_lshl_add_u64 v[152:153], v[192:193], 0, s[20:21]
	global_load_lds_dwordx4 v[152:153], off
	v_mfma_f32_32x32x16_bf16 v[48:63], v[132:135], v[136:139], v[48:63]
	v_xor_b32_e32 v186, 0x10000, v186
	v_xor_b32_e32 v190, 0x10000, v190
	s_add_u32 m0, s27, 98304
	v_lshl_add_u64 v[154:155], v[192:193], 0, s[24:25]
	global_load_lds_dwordx4 v[154:155], off
	v_mfma_f32_32x32x16_bf16 v[96:111], v[128:131], v[140:143], v[96:111]
	v_xor_b32_e32 v187, 0x10000, v187
	v_xor_b32_e32 v191, 0x10000, v191
	s_add_u32 m0, s27, 73728
	v_lshl_add_u64 v[156:157], v[194:195], 0, s[20:21]
	global_load_lds_dwordx4 v[156:157], off
	v_mfma_f32_32x32x16_bf16 v[32:47], v[132:135], v[140:143], v[32:47]
	s_add_u32 m0, s27, 106496
	v_lshl_add_u64 v[152:153], v[194:195], 0, s[24:25]
	global_load_lds_dwordx4 v[152:153], off
	s_add_u32 m0, s27, 81920
	v_lshl_add_u64 v[154:155], v[196:197], 0, s[20:21]
	global_load_lds_dwordx4 v[154:155], off
	s_add_u32 m0, s27, 114688
	v_lshl_add_u64 v[156:157], v[196:197], 0, s[24:25]
	global_load_lds_dwordx4 v[156:157], off
	s_add_u32 m0, s27, 90112
	v_lshl_add_u64 v[152:153], v[198:199], 0, s[20:21]
	global_load_lds_dwordx4 v[152:153], off
	s_add_u32 m0, s27, 122880
	v_lshl_add_u64 v[154:155], v[198:199], 0, s[24:25]
	global_load_lds_dwordx4 v[154:155], off
	ds_read_b128 v[128:131], v185
	ds_read_b128 v[136:139], v189
	ds_read_b128 v[132:135], v185 offset:4096
	ds_read_b128 v[140:143], v189 offset:4096
	s_waitcnt lgkmcnt(4)
	v_mfma_f32_32x32x16_bf16 v[112:127], v[160:163], v[168:171], v[112:127]
	v_mfma_f32_32x32x16_bf16 v[48:63], v[164:167], v[168:171], v[48:63]
	v_mfma_f32_32x32x16_bf16 v[96:111], v[160:163], v[172:175], v[96:111]
	v_mfma_f32_32x32x16_bf16 v[32:47], v[164:167], v[172:175], v[32:47]
	ds_read_b128 v[160:163], v186
	ds_read_b128 v[168:171], v190
	ds_read_b128 v[164:167], v186 offset:4096
	ds_read_b128 v[172:175], v190 offset:4096
	s_waitcnt lgkmcnt(4)
	v_mfma_f32_32x32x16_bf16 v[112:127], v[128:131], v[136:139], v[112:127]
	v_mfma_f32_32x32x16_bf16 v[48:63], v[132:135], v[136:139], v[48:63]
	v_mfma_f32_32x32x16_bf16 v[96:111], v[128:131], v[140:143], v[96:111]
	v_mfma_f32_32x32x16_bf16 v[32:47], v[132:135], v[140:143], v[32:47]
	ds_read_b128 v[128:131], v187
	ds_read_b128 v[136:139], v191
	ds_read_b128 v[132:135], v187 offset:4096
	ds_read_b128 v[140:143], v191 offset:4096
	s_waitcnt lgkmcnt(4)
	v_mfma_f32_32x32x16_bf16 v[112:127], v[160:163], v[168:171], v[112:127]
	v_mfma_f32_32x32x16_bf16 v[48:63], v[164:167], v[168:171], v[48:63]
	v_mfma_f32_32x32x16_bf16 v[96:111], v[160:163], v[172:175], v[96:111]
	v_mfma_f32_32x32x16_bf16 v[32:47], v[164:167], v[172:175], v[32:47]
	s_waitcnt vmcnt(0) lgkmcnt(0)
	s_barrier
	v_xor_b32_e32 v184, 0x10000, v184
	v_xor_b32_e32 v188, 0x10000, v188
	ds_read_b128 v[160:163], v184
	ds_read_b128 v[168:171], v188
	ds_read_b128 v[164:167], v184 offset:4096
	ds_read_b128 v[172:175], v188 offset:4096
	s_add_u32 s20, s16, 768
	s_addc_u32 s21, s17, 0
	s_add_u32 s24, s18, 768
	s_addc_u32 s25, s19, 0
	v_mfma_f32_32x32x16_bf16 v[112:127], v[128:131], v[136:139], v[112:127]
	v_xor_b32_e32 v185, 0x10000, v185
	v_xor_b32_e32 v189, 0x10000, v189
	s_add_u32 m0, s27, 0
	v_lshl_add_u64 v[152:153], v[192:193], 0, s[20:21]
	global_load_lds_dwordx4 v[152:153], off
	v_mfma_f32_32x32x16_bf16 v[48:63], v[132:135], v[136:139], v[48:63]
	v_xor_b32_e32 v186, 0x10000, v186
	v_xor_b32_e32 v190, 0x10000, v190
	s_add_u32 m0, s27, 32768
	v_lshl_add_u64 v[154:155], v[192:193], 0, s[24:25]
	global_load_lds_dwordx4 v[154:155], off
	v_mfma_f32_32x32x16_bf16 v[96:111], v[128:131], v[140:143], v[96:111]
	v_xor_b32_e32 v187, 0x10000, v187
	v_xor_b32_e32 v191, 0x10000, v191
	s_add_u32 m0, s27, 8192
	v_lshl_add_u64 v[156:157], v[194:195], 0, s[20:21]
	global_load_lds_dwordx4 v[156:157], off
	v_mfma_f32_32x32x16_bf16 v[32:47], v[132:135], v[140:143], v[32:47]
	s_add_u32 m0, s27, 40960
	v_lshl_add_u64 v[152:153], v[194:195], 0, s[24:25]
	global_load_lds_dwordx4 v[152:153], off
	s_add_u32 m0, s27, 16384
	v_lshl_add_u64 v[154:155], v[196:197], 0, s[20:21]
	global_load_lds_dwordx4 v[154:155], off
	s_add_u32 m0, s27, 49152
	v_lshl_add_u64 v[156:157], v[196:197], 0, s[24:25]
	global_load_lds_dwordx4 v[156:157], off
	s_add_u32 m0, s27, 24576
	v_lshl_add_u64 v[152:153], v[198:199], 0, s[20:21]
	global_load_lds_dwordx4 v[152:153], off
	s_add_u32 m0, s27, 57344
	v_lshl_add_u64 v[154:155], v[198:199], 0, s[24:25]
	global_load_lds_dwordx4 v[154:155], off
	ds_read_b128 v[128:131], v185
	ds_read_b128 v[136:139], v189
	ds_read_b128 v[132:135], v185 offset:4096
	ds_read_b128 v[140:143], v189 offset:4096
	s_waitcnt lgkmcnt(4)
	v_mfma_f32_32x32x16_bf16 v[112:127], v[160:163], v[168:171], v[112:127]
	v_mfma_f32_32x32x16_bf16 v[48:63], v[164:167], v[168:171], v[48:63]
	v_mfma_f32_32x32x16_bf16 v[96:111], v[160:163], v[172:175], v[96:111]
	v_mfma_f32_32x32x16_bf16 v[32:47], v[164:167], v[172:175], v[32:47]
	ds_read_b128 v[160:163], v186
	ds_read_b128 v[168:171], v190
	ds_read_b128 v[164:167], v186 offset:4096
	ds_read_b128 v[172:175], v190 offset:4096
	s_waitcnt lgkmcnt(4)
	v_mfma_f32_32x32x16_bf16 v[112:127], v[128:131], v[136:139], v[112:127]
	v_mfma_f32_32x32x16_bf16 v[48:63], v[132:135], v[136:139], v[48:63]
	v_mfma_f32_32x32x16_bf16 v[96:111], v[128:131], v[140:143], v[96:111]
	v_mfma_f32_32x32x16_bf16 v[32:47], v[132:135], v[140:143], v[32:47]
	ds_read_b128 v[128:131], v187
	ds_read_b128 v[136:139], v191
	ds_read_b128 v[132:135], v187 offset:4096
	ds_read_b128 v[140:143], v191 offset:4096
	s_waitcnt lgkmcnt(4)
	v_mfma_f32_32x32x16_bf16 v[112:127], v[160:163], v[168:171], v[112:127]
	v_mfma_f32_32x32x16_bf16 v[48:63], v[164:167], v[168:171], v[48:63]
	v_mfma_f32_32x32x16_bf16 v[96:111], v[160:163], v[172:175], v[96:111]
	v_mfma_f32_32x32x16_bf16 v[32:47], v[164:167], v[172:175], v[32:47]
	s_waitcnt vmcnt(0) lgkmcnt(0)
	s_barrier
	v_xor_b32_e32 v184, 0x10000, v184
	v_xor_b32_e32 v188, 0x10000, v188
	ds_read_b128 v[160:163], v184
	ds_read_b128 v[168:171], v188
	ds_read_b128 v[164:167], v184 offset:4096
	ds_read_b128 v[172:175], v188 offset:4096
	s_add_u32 s20, s16, 896
	s_addc_u32 s21, s17, 0
	s_add_u32 s24, s18, 896
	s_addc_u32 s25, s19, 0
	v_mfma_f32_32x32x16_bf16 v[112:127], v[128:131], v[136:139], v[112:127]
	v_xor_b32_e32 v185, 0x10000, v185
	v_xor_b32_e32 v189, 0x10000, v189
	s_add_u32 m0, s27, 65536
	v_lshl_add_u64 v[152:153], v[192:193], 0, s[20:21]
	global_load_lds_dwordx4 v[152:153], off
	v_mfma_f32_32x32x16_bf16 v[48:63], v[132:135], v[136:139], v[48:63]
	v_xor_b32_e32 v186, 0x10000, v186
	v_xor_b32_e32 v190, 0x10000, v190
	s_add_u32 m0, s27, 98304
	v_lshl_add_u64 v[154:155], v[192:193], 0, s[24:25]
	global_load_lds_dwordx4 v[154:155], off
	v_mfma_f32_32x32x16_bf16 v[96:111], v[128:131], v[140:143], v[96:111]
	v_xor_b32_e32 v187, 0x10000, v187
	v_xor_b32_e32 v191, 0x10000, v191
	s_add_u32 m0, s27, 73728
	v_lshl_add_u64 v[156:157], v[194:195], 0, s[20:21]
	global_load_lds_dwordx4 v[156:157], off
	v_mfma_f32_32x32x16_bf16 v[32:47], v[132:135], v[140:143], v[32:47]
	s_add_u32 m0, s27, 106496
	v_lshl_add_u64 v[152:153], v[194:195], 0, s[24:25]
	global_load_lds_dwordx4 v[152:153], off
	s_add_u32 m0, s27, 81920
	v_lshl_add_u64 v[154:155], v[196:197], 0, s[20:21]
	global_load_lds_dwordx4 v[154:155], off
	s_add_u32 m0, s27, 114688
	v_lshl_add_u64 v[156:157], v[196:197], 0, s[24:25]
	global_load_lds_dwordx4 v[156:157], off
	s_add_u32 m0, s27, 90112
	v_lshl_add_u64 v[152:153], v[198:199], 0, s[20:21]
	global_load_lds_dwordx4 v[152:153], off
	s_add_u32 m0, s27, 122880
	v_lshl_add_u64 v[154:155], v[198:199], 0, s[24:25]
	global_load_lds_dwordx4 v[154:155], off
	ds_read_b128 v[128:131], v185
	ds_read_b128 v[136:139], v189
	ds_read_b128 v[132:135], v185 offset:4096
	ds_read_b128 v[140:143], v189 offset:4096
	s_waitcnt lgkmcnt(4)
	v_mfma_f32_32x32x16_bf16 v[112:127], v[160:163], v[168:171], v[112:127]
	v_mfma_f32_32x32x16_bf16 v[48:63], v[164:167], v[168:171], v[48:63]
	v_mfma_f32_32x32x16_bf16 v[96:111], v[160:163], v[172:175], v[96:111]
	v_mfma_f32_32x32x16_bf16 v[32:47], v[164:167], v[172:175], v[32:47]
	ds_read_b128 v[160:163], v186
	ds_read_b128 v[168:171], v190
	ds_read_b128 v[164:167], v186 offset:4096
	ds_read_b128 v[172:175], v190 offset:4096
	s_waitcnt lgkmcnt(4)
	v_mfma_f32_32x32x16_bf16 v[112:127], v[128:131], v[136:139], v[112:127]
	v_mfma_f32_32x32x16_bf16 v[48:63], v[132:135], v[136:139], v[48:63]
	v_mfma_f32_32x32x16_bf16 v[96:111], v[128:131], v[140:143], v[96:111]
	v_mfma_f32_32x32x16_bf16 v[32:47], v[132:135], v[140:143], v[32:47]
	ds_read_b128 v[128:131], v187
	ds_read_b128 v[136:139], v191
	ds_read_b128 v[132:135], v187 offset:4096
	ds_read_b128 v[140:143], v191 offset:4096
	s_waitcnt lgkmcnt(4)
	v_mfma_f32_32x32x16_bf16 v[112:127], v[160:163], v[168:171], v[112:127]
	v_mfma_f32_32x32x16_bf16 v[48:63], v[164:167], v[168:171], v[48:63]
	v_mfma_f32_32x32x16_bf16 v[96:111], v[160:163], v[172:175], v[96:111]
	v_mfma_f32_32x32x16_bf16 v[32:47], v[164:167], v[172:175], v[32:47]
	s_waitcnt vmcnt(0) lgkmcnt(0)
	s_barrier
	v_xor_b32_e32 v184, 0x10000, v184
	v_xor_b32_e32 v188, 0x10000, v188
	ds_read_b128 v[160:163], v184
	ds_read_b128 v[168:171], v188
	ds_read_b128 v[164:167], v184 offset:4096
	ds_read_b128 v[172:175], v188 offset:4096
	s_add_u32 s20, s16, 1024
	s_addc_u32 s21, s17, 0
	s_add_u32 s24, s18, 1024
	s_addc_u32 s25, s19, 0
	v_mfma_f32_32x32x16_bf16 v[112:127], v[128:131], v[136:139], v[112:127]
	v_xor_b32_e32 v185, 0x10000, v185
	v_xor_b32_e32 v189, 0x10000, v189
	s_add_u32 m0, s27, 0
	v_lshl_add_u64 v[152:153], v[192:193], 0, s[20:21]
	global_load_lds_dwordx4 v[152:153], off
	v_mfma_f32_32x32x16_bf16 v[48:63], v[132:135], v[136:139], v[48:63]
	v_xor_b32_e32 v186, 0x10000, v186
	v_xor_b32_e32 v190, 0x10000, v190
	s_add_u32 m0, s27, 32768
	v_lshl_add_u64 v[154:155], v[192:193], 0, s[24:25]
	global_load_lds_dwordx4 v[154:155], off
	v_mfma_f32_32x32x16_bf16 v[96:111], v[128:131], v[140:143], v[96:111]
	v_xor_b32_e32 v187, 0x10000, v187
	v_xor_b32_e32 v191, 0x10000, v191
	s_add_u32 m0, s27, 8192
	v_lshl_add_u64 v[156:157], v[194:195], 0, s[20:21]
	global_load_lds_dwordx4 v[156:157], off
	v_mfma_f32_32x32x16_bf16 v[32:47], v[132:135], v[140:143], v[32:47]
	s_add_u32 m0, s27, 40960
	v_lshl_add_u64 v[152:153], v[194:195], 0, s[24:25]
	global_load_lds_dwordx4 v[152:153], off
	s_add_u32 m0, s27, 16384
	v_lshl_add_u64 v[154:155], v[196:197], 0, s[20:21]
	global_load_lds_dwordx4 v[154:155], off
	s_add_u32 m0, s27, 49152
	v_lshl_add_u64 v[156:157], v[196:197], 0, s[24:25]
	global_load_lds_dwordx4 v[156:157], off
	s_add_u32 m0, s27, 24576
	v_lshl_add_u64 v[152:153], v[198:199], 0, s[20:21]
	global_load_lds_dwordx4 v[152:153], off
	s_add_u32 m0, s27, 57344
	v_lshl_add_u64 v[154:155], v[198:199], 0, s[24:25]
	global_load_lds_dwordx4 v[154:155], off
	ds_read_b128 v[128:131], v185
	ds_read_b128 v[136:139], v189
	ds_read_b128 v[132:135], v185 offset:4096
	ds_read_b128 v[140:143], v189 offset:4096
	s_waitcnt lgkmcnt(4)
	v_mfma_f32_32x32x16_bf16 v[112:127], v[160:163], v[168:171], v[112:127]
	v_mfma_f32_32x32x16_bf16 v[48:63], v[164:167], v[168:171], v[48:63]
	v_mfma_f32_32x32x16_bf16 v[96:111], v[160:163], v[172:175], v[96:111]
	v_mfma_f32_32x32x16_bf16 v[32:47], v[164:167], v[172:175], v[32:47]
	ds_read_b128 v[160:163], v186
	ds_read_b128 v[168:171], v190
	ds_read_b128 v[164:167], v186 offset:4096
	ds_read_b128 v[172:175], v190 offset:4096
	s_waitcnt lgkmcnt(4)
	v_mfma_f32_32x32x16_bf16 v[112:127], v[128:131], v[136:139], v[112:127]
	v_mfma_f32_32x32x16_bf16 v[48:63], v[132:135], v[136:139], v[48:63]
	v_mfma_f32_32x32x16_bf16 v[96:111], v[128:131], v[140:143], v[96:111]
	v_mfma_f32_32x32x16_bf16 v[32:47], v[132:135], v[140:143], v[32:47]
	ds_read_b128 v[128:131], v187
	ds_read_b128 v[136:139], v191
	ds_read_b128 v[132:135], v187 offset:4096
	ds_read_b128 v[140:143], v191 offset:4096
	s_waitcnt lgkmcnt(4)
	v_mfma_f32_32x32x16_bf16 v[112:127], v[160:163], v[168:171], v[112:127]
	v_mfma_f32_32x32x16_bf16 v[48:63], v[164:167], v[168:171], v[48:63]
	v_mfma_f32_32x32x16_bf16 v[96:111], v[160:163], v[172:175], v[96:111]
	v_mfma_f32_32x32x16_bf16 v[32:47], v[164:167], v[172:175], v[32:47]
	s_waitcnt vmcnt(0) lgkmcnt(0)
	s_barrier
	v_xor_b32_e32 v184, 0x10000, v184
	v_xor_b32_e32 v188, 0x10000, v188
	ds_read_b128 v[160:163], v184
	ds_read_b128 v[168:171], v188
	ds_read_b128 v[164:167], v184 offset:4096
	ds_read_b128 v[172:175], v188 offset:4096
	s_add_u32 s20, s16, 1152
	s_addc_u32 s21, s17, 0
	s_add_u32 s24, s18, 1152
	s_addc_u32 s25, s19, 0
	v_mfma_f32_32x32x16_bf16 v[112:127], v[128:131], v[136:139], v[112:127]
	v_xor_b32_e32 v185, 0x10000, v185
	v_xor_b32_e32 v189, 0x10000, v189
	s_add_u32 m0, s27, 65536
	v_lshl_add_u64 v[152:153], v[192:193], 0, s[20:21]
	global_load_lds_dwordx4 v[152:153], off
	v_mfma_f32_32x32x16_bf16 v[48:63], v[132:135], v[136:139], v[48:63]
	v_xor_b32_e32 v186, 0x10000, v186
	v_xor_b32_e32 v190, 0x10000, v190
	s_add_u32 m0, s27, 98304
	v_lshl_add_u64 v[154:155], v[192:193], 0, s[24:25]
	global_load_lds_dwordx4 v[154:155], off
	v_mfma_f32_32x32x16_bf16 v[96:111], v[128:131], v[140:143], v[96:111]
	v_xor_b32_e32 v187, 0x10000, v187
	v_xor_b32_e32 v191, 0x10000, v191
	s_add_u32 m0, s27, 73728
	v_lshl_add_u64 v[156:157], v[194:195], 0, s[20:21]
	global_load_lds_dwordx4 v[156:157], off
	v_mfma_f32_32x32x16_bf16 v[32:47], v[132:135], v[140:143], v[32:47]
	s_add_u32 m0, s27, 106496
	v_lshl_add_u64 v[152:153], v[194:195], 0, s[24:25]
	global_load_lds_dwordx4 v[152:153], off
	s_add_u32 m0, s27, 81920
	v_lshl_add_u64 v[154:155], v[196:197], 0, s[20:21]
	global_load_lds_dwordx4 v[154:155], off
	s_add_u32 m0, s27, 114688
	v_lshl_add_u64 v[156:157], v[196:197], 0, s[24:25]
	global_load_lds_dwordx4 v[156:157], off
	s_add_u32 m0, s27, 90112
	v_lshl_add_u64 v[152:153], v[198:199], 0, s[20:21]
	global_load_lds_dwordx4 v[152:153], off
	s_add_u32 m0, s27, 122880
	v_lshl_add_u64 v[154:155], v[198:199], 0, s[24:25]
	global_load_lds_dwordx4 v[154:155], off
	ds_read_b128 v[128:131], v185
	ds_read_b128 v[136:139], v189
	ds_read_b128 v[132:135], v185 offset:4096
	ds_read_b128 v[140:143], v189 offset:4096
	s_waitcnt lgkmcnt(4)
	v_mfma_f32_32x32x16_bf16 v[112:127], v[160:163], v[168:171], v[112:127]
	v_mfma_f32_32x32x16_bf16 v[48:63], v[164:167], v[168:171], v[48:63]
	v_mfma_f32_32x32x16_bf16 v[96:111], v[160:163], v[172:175], v[96:111]
	v_mfma_f32_32x32x16_bf16 v[32:47], v[164:167], v[172:175], v[32:47]
	ds_read_b128 v[160:163], v186
	ds_read_b128 v[168:171], v190
	ds_read_b128 v[164:167], v186 offset:4096
	ds_read_b128 v[172:175], v190 offset:4096
	s_waitcnt lgkmcnt(4)
	v_mfma_f32_32x32x16_bf16 v[112:127], v[128:131], v[136:139], v[112:127]
	v_mfma_f32_32x32x16_bf16 v[48:63], v[132:135], v[136:139], v[48:63]
	v_mfma_f32_32x32x16_bf16 v[96:111], v[128:131], v[140:143], v[96:111]
	v_mfma_f32_32x32x16_bf16 v[32:47], v[132:135], v[140:143], v[32:47]
	ds_read_b128 v[128:131], v187
	ds_read_b128 v[136:139], v191
	ds_read_b128 v[132:135], v187 offset:4096
	ds_read_b128 v[140:143], v191 offset:4096
	s_waitcnt lgkmcnt(4)
	v_mfma_f32_32x32x16_bf16 v[112:127], v[160:163], v[168:171], v[112:127]
	v_mfma_f32_32x32x16_bf16 v[48:63], v[164:167], v[168:171], v[48:63]
	v_mfma_f32_32x32x16_bf16 v[96:111], v[160:163], v[172:175], v[96:111]
	v_mfma_f32_32x32x16_bf16 v[32:47], v[164:167], v[172:175], v[32:47]
	s_waitcnt vmcnt(0) lgkmcnt(0)
	s_barrier
	v_xor_b32_e32 v184, 0x10000, v184
	v_xor_b32_e32 v188, 0x10000, v188
	ds_read_b128 v[160:163], v184
	ds_read_b128 v[168:171], v188
	ds_read_b128 v[164:167], v184 offset:4096
	ds_read_b128 v[172:175], v188 offset:4096
	s_add_u32 s20, s16, 1280
	s_addc_u32 s21, s17, 0
	s_add_u32 s24, s18, 1280
	s_addc_u32 s25, s19, 0
	v_mfma_f32_32x32x16_bf16 v[112:127], v[128:131], v[136:139], v[112:127]
	v_xor_b32_e32 v185, 0x10000, v185
	v_xor_b32_e32 v189, 0x10000, v189
	s_add_u32 m0, s27, 0
	v_lshl_add_u64 v[152:153], v[192:193], 0, s[20:21]
	global_load_lds_dwordx4 v[152:153], off
	v_mfma_f32_32x32x16_bf16 v[48:63], v[132:135], v[136:139], v[48:63]
	v_xor_b32_e32 v186, 0x10000, v186
	v_xor_b32_e32 v190, 0x10000, v190
	s_add_u32 m0, s27, 32768
	v_lshl_add_u64 v[154:155], v[192:193], 0, s[24:25]
	global_load_lds_dwordx4 v[154:155], off
	v_mfma_f32_32x32x16_bf16 v[96:111], v[128:131], v[140:143], v[96:111]
	v_xor_b32_e32 v187, 0x10000, v187
	v_xor_b32_e32 v191, 0x10000, v191
	s_add_u32 m0, s27, 8192
	v_lshl_add_u64 v[156:157], v[194:195], 0, s[20:21]
	global_load_lds_dwordx4 v[156:157], off
	v_mfma_f32_32x32x16_bf16 v[32:47], v[132:135], v[140:143], v[32:47]
	s_add_u32 m0, s27, 40960
	v_lshl_add_u64 v[152:153], v[194:195], 0, s[24:25]
	global_load_lds_dwordx4 v[152:153], off
	s_add_u32 m0, s27, 16384
	v_lshl_add_u64 v[154:155], v[196:197], 0, s[20:21]
	global_load_lds_dwordx4 v[154:155], off
	s_add_u32 m0, s27, 49152
	v_lshl_add_u64 v[156:157], v[196:197], 0, s[24:25]
	global_load_lds_dwordx4 v[156:157], off
	s_add_u32 m0, s27, 24576
	v_lshl_add_u64 v[152:153], v[198:199], 0, s[20:21]
	global_load_lds_dwordx4 v[152:153], off
	s_add_u32 m0, s27, 57344
	v_lshl_add_u64 v[154:155], v[198:199], 0, s[24:25]
	global_load_lds_dwordx4 v[154:155], off
	ds_read_b128 v[128:131], v185
	ds_read_b128 v[136:139], v189
	ds_read_b128 v[132:135], v185 offset:4096
	ds_read_b128 v[140:143], v189 offset:4096
	s_waitcnt lgkmcnt(4)
	v_mfma_f32_32x32x16_bf16 v[112:127], v[160:163], v[168:171], v[112:127]
	v_mfma_f32_32x32x16_bf16 v[48:63], v[164:167], v[168:171], v[48:63]
	v_mfma_f32_32x32x16_bf16 v[96:111], v[160:163], v[172:175], v[96:111]
	v_mfma_f32_32x32x16_bf16 v[32:47], v[164:167], v[172:175], v[32:47]
	ds_read_b128 v[160:163], v186
	ds_read_b128 v[168:171], v190
	ds_read_b128 v[164:167], v186 offset:4096
	ds_read_b128 v[172:175], v190 offset:4096
	s_waitcnt lgkmcnt(4)
	v_mfma_f32_32x32x16_bf16 v[112:127], v[128:131], v[136:139], v[112:127]
	v_mfma_f32_32x32x16_bf16 v[48:63], v[132:135], v[136:139], v[48:63]
	v_mfma_f32_32x32x16_bf16 v[96:111], v[128:131], v[140:143], v[96:111]
	v_mfma_f32_32x32x16_bf16 v[32:47], v[132:135], v[140:143], v[32:47]
	ds_read_b128 v[128:131], v187
	ds_read_b128 v[136:139], v191
	ds_read_b128 v[132:135], v187 offset:4096
	ds_read_b128 v[140:143], v191 offset:4096
	s_waitcnt lgkmcnt(4)
	v_mfma_f32_32x32x16_bf16 v[112:127], v[160:163], v[168:171], v[112:127]
	v_mfma_f32_32x32x16_bf16 v[48:63], v[164:167], v[168:171], v[48:63]
	v_mfma_f32_32x32x16_bf16 v[96:111], v[160:163], v[172:175], v[96:111]
	v_mfma_f32_32x32x16_bf16 v[32:47], v[164:167], v[172:175], v[32:47]
	s_waitcnt vmcnt(0) lgkmcnt(0)
	s_barrier
	v_xor_b32_e32 v184, 0x10000, v184
	v_xor_b32_e32 v188, 0x10000, v188
	ds_read_b128 v[160:163], v184
	ds_read_b128 v[168:171], v188
	ds_read_b128 v[164:167], v184 offset:4096
	ds_read_b128 v[172:175], v188 offset:4096
	s_add_u32 s20, s16, 1408
	s_addc_u32 s21, s17, 0
	s_add_u32 s24, s18, 1408
	s_addc_u32 s25, s19, 0
	v_mfma_f32_32x32x16_bf16 v[112:127], v[128:131], v[136:139], v[112:127]
	v_xor_b32_e32 v185, 0x10000, v185
	v_xor_b32_e32 v189, 0x10000, v189
	s_add_u32 m0, s27, 65536
	v_lshl_add_u64 v[152:153], v[192:193], 0, s[20:21]
	global_load_lds_dwordx4 v[152:153], off
	v_mfma_f32_32x32x16_bf16 v[48:63], v[132:135], v[136:139], v[48:63]
	v_xor_b32_e32 v186, 0x10000, v186
	v_xor_b32_e32 v190, 0x10000, v190
	s_add_u32 m0, s27, 98304
	v_lshl_add_u64 v[154:155], v[192:193], 0, s[24:25]
	global_load_lds_dwordx4 v[154:155], off
	v_mfma_f32_32x32x16_bf16 v[96:111], v[128:131], v[140:143], v[96:111]
	v_xor_b32_e32 v187, 0x10000, v187
	v_xor_b32_e32 v191, 0x10000, v191
	s_add_u32 m0, s27, 73728
	v_lshl_add_u64 v[156:157], v[194:195], 0, s[20:21]
	global_load_lds_dwordx4 v[156:157], off
	v_mfma_f32_32x32x16_bf16 v[32:47], v[132:135], v[140:143], v[32:47]
	s_add_u32 m0, s27, 106496
	v_lshl_add_u64 v[152:153], v[194:195], 0, s[24:25]
	global_load_lds_dwordx4 v[152:153], off
	s_add_u32 m0, s27, 81920
	v_lshl_add_u64 v[154:155], v[196:197], 0, s[20:21]
	global_load_lds_dwordx4 v[154:155], off
	s_add_u32 m0, s27, 114688
	v_lshl_add_u64 v[156:157], v[196:197], 0, s[24:25]
	global_load_lds_dwordx4 v[156:157], off
	s_add_u32 m0, s27, 90112
	v_lshl_add_u64 v[152:153], v[198:199], 0, s[20:21]
	global_load_lds_dwordx4 v[152:153], off
	s_add_u32 m0, s27, 122880
	v_lshl_add_u64 v[154:155], v[198:199], 0, s[24:25]
	global_load_lds_dwordx4 v[154:155], off
	ds_read_b128 v[128:131], v185
	ds_read_b128 v[136:139], v189
	ds_read_b128 v[132:135], v185 offset:4096
	ds_read_b128 v[140:143], v189 offset:4096
	s_waitcnt lgkmcnt(4)
	v_mfma_f32_32x32x16_bf16 v[112:127], v[160:163], v[168:171], v[112:127]
	v_mfma_f32_32x32x16_bf16 v[48:63], v[164:167], v[168:171], v[48:63]
	v_mfma_f32_32x32x16_bf16 v[96:111], v[160:163], v[172:175], v[96:111]
	v_mfma_f32_32x32x16_bf16 v[32:47], v[164:167], v[172:175], v[32:47]
	ds_read_b128 v[160:163], v186
	ds_read_b128 v[168:171], v190
	ds_read_b128 v[164:167], v186 offset:4096
	ds_read_b128 v[172:175], v190 offset:4096
	s_waitcnt lgkmcnt(4)
	v_mfma_f32_32x32x16_bf16 v[112:127], v[128:131], v[136:139], v[112:127]
	v_mfma_f32_32x32x16_bf16 v[48:63], v[132:135], v[136:139], v[48:63]
	v_mfma_f32_32x32x16_bf16 v[96:111], v[128:131], v[140:143], v[96:111]
	v_mfma_f32_32x32x16_bf16 v[32:47], v[132:135], v[140:143], v[32:47]
	ds_read_b128 v[128:131], v187
	ds_read_b128 v[136:139], v191
	ds_read_b128 v[132:135], v187 offset:4096
	ds_read_b128 v[140:143], v191 offset:4096
	s_waitcnt lgkmcnt(4)
	v_mfma_f32_32x32x16_bf16 v[112:127], v[160:163], v[168:171], v[112:127]
	v_mfma_f32_32x32x16_bf16 v[48:63], v[164:167], v[168:171], v[48:63]
	v_mfma_f32_32x32x16_bf16 v[96:111], v[160:163], v[172:175], v[96:111]
	v_mfma_f32_32x32x16_bf16 v[32:47], v[164:167], v[172:175], v[32:47]
	s_waitcnt vmcnt(0) lgkmcnt(0)
	s_barrier
	v_xor_b32_e32 v184, 0x10000, v184
	v_xor_b32_e32 v188, 0x10000, v188
	ds_read_b128 v[160:163], v184
	ds_read_b128 v[168:171], v188
	ds_read_b128 v[164:167], v184 offset:4096
	ds_read_b128 v[172:175], v188 offset:4096
	s_add_u32 s20, s16, 1536
	s_addc_u32 s21, s17, 0
	s_add_u32 s24, s18, 1536
	s_addc_u32 s25, s19, 0
	v_mfma_f32_32x32x16_bf16 v[112:127], v[128:131], v[136:139], v[112:127]
	v_xor_b32_e32 v185, 0x10000, v185
	v_xor_b32_e32 v189, 0x10000, v189
	s_add_u32 m0, s27, 0
	v_lshl_add_u64 v[152:153], v[192:193], 0, s[20:21]
	global_load_lds_dwordx4 v[152:153], off
	v_mfma_f32_32x32x16_bf16 v[48:63], v[132:135], v[136:139], v[48:63]
	v_xor_b32_e32 v186, 0x10000, v186
	v_xor_b32_e32 v190, 0x10000, v190
	s_add_u32 m0, s27, 32768
	v_lshl_add_u64 v[154:155], v[192:193], 0, s[24:25]
	global_load_lds_dwordx4 v[154:155], off
	v_mfma_f32_32x32x16_bf16 v[96:111], v[128:131], v[140:143], v[96:111]
	v_xor_b32_e32 v187, 0x10000, v187
	v_xor_b32_e32 v191, 0x10000, v191
	s_add_u32 m0, s27, 8192
	v_lshl_add_u64 v[156:157], v[194:195], 0, s[20:21]
	global_load_lds_dwordx4 v[156:157], off
	v_mfma_f32_32x32x16_bf16 v[32:47], v[132:135], v[140:143], v[32:47]
	s_add_u32 m0, s27, 40960
	v_lshl_add_u64 v[152:153], v[194:195], 0, s[24:25]
	global_load_lds_dwordx4 v[152:153], off
	s_add_u32 m0, s27, 16384
	v_lshl_add_u64 v[154:155], v[196:197], 0, s[20:21]
	global_load_lds_dwordx4 v[154:155], off
	s_add_u32 m0, s27, 49152
	v_lshl_add_u64 v[156:157], v[196:197], 0, s[24:25]
	global_load_lds_dwordx4 v[156:157], off
	s_add_u32 m0, s27, 24576
	v_lshl_add_u64 v[152:153], v[198:199], 0, s[20:21]
	global_load_lds_dwordx4 v[152:153], off
	s_add_u32 m0, s27, 57344
	v_lshl_add_u64 v[154:155], v[198:199], 0, s[24:25]
	global_load_lds_dwordx4 v[154:155], off
	ds_read_b128 v[128:131], v185
	ds_read_b128 v[136:139], v189
	ds_read_b128 v[132:135], v185 offset:4096
	ds_read_b128 v[140:143], v189 offset:4096
	s_waitcnt lgkmcnt(4)
	v_mfma_f32_32x32x16_bf16 v[112:127], v[160:163], v[168:171], v[112:127]
	v_mfma_f32_32x32x16_bf16 v[48:63], v[164:167], v[168:171], v[48:63]
	v_mfma_f32_32x32x16_bf16 v[96:111], v[160:163], v[172:175], v[96:111]
	v_mfma_f32_32x32x16_bf16 v[32:47], v[164:167], v[172:175], v[32:47]
	ds_read_b128 v[160:163], v186
	ds_read_b128 v[168:171], v190
	ds_read_b128 v[164:167], v186 offset:4096
	ds_read_b128 v[172:175], v190 offset:4096
	s_waitcnt lgkmcnt(4)
	v_mfma_f32_32x32x16_bf16 v[112:127], v[128:131], v[136:139], v[112:127]
	v_mfma_f32_32x32x16_bf16 v[48:63], v[132:135], v[136:139], v[48:63]
	v_mfma_f32_32x32x16_bf16 v[96:111], v[128:131], v[140:143], v[96:111]
	v_mfma_f32_32x32x16_bf16 v[32:47], v[132:135], v[140:143], v[32:47]
	ds_read_b128 v[128:131], v187
	ds_read_b128 v[136:139], v191
	ds_read_b128 v[132:135], v187 offset:4096
	ds_read_b128 v[140:143], v191 offset:4096
	s_waitcnt lgkmcnt(4)
	v_mfma_f32_32x32x16_bf16 v[112:127], v[160:163], v[168:171], v[112:127]
	v_mfma_f32_32x32x16_bf16 v[48:63], v[164:167], v[168:171], v[48:63]
	v_mfma_f32_32x32x16_bf16 v[96:111], v[160:163], v[172:175], v[96:111]
	v_mfma_f32_32x32x16_bf16 v[32:47], v[164:167], v[172:175], v[32:47]
	s_waitcnt vmcnt(0) lgkmcnt(0)
	s_barrier
	v_xor_b32_e32 v184, 0x10000, v184
	v_xor_b32_e32 v188, 0x10000, v188
	ds_read_b128 v[160:163], v184
	ds_read_b128 v[168:171], v188
	ds_read_b128 v[164:167], v184 offset:4096
	ds_read_b128 v[172:175], v188 offset:4096
	s_add_u32 s20, s16, 1664
	s_addc_u32 s21, s17, 0
	s_add_u32 s24, s18, 1664
	s_addc_u32 s25, s19, 0
	v_mfma_f32_32x32x16_bf16 v[112:127], v[128:131], v[136:139], v[112:127]
	v_xor_b32_e32 v185, 0x10000, v185
	v_xor_b32_e32 v189, 0x10000, v189
	s_add_u32 m0, s27, 65536
	v_lshl_add_u64 v[152:153], v[192:193], 0, s[20:21]
	global_load_lds_dwordx4 v[152:153], off
	v_mfma_f32_32x32x16_bf16 v[48:63], v[132:135], v[136:139], v[48:63]
	v_xor_b32_e32 v186, 0x10000, v186
	v_xor_b32_e32 v190, 0x10000, v190
	s_add_u32 m0, s27, 98304
	v_lshl_add_u64 v[154:155], v[192:193], 0, s[24:25]
	global_load_lds_dwordx4 v[154:155], off
	v_mfma_f32_32x32x16_bf16 v[96:111], v[128:131], v[140:143], v[96:111]
	v_xor_b32_e32 v187, 0x10000, v187
	v_xor_b32_e32 v191, 0x10000, v191
	s_add_u32 m0, s27, 73728
	v_lshl_add_u64 v[156:157], v[194:195], 0, s[20:21]
	global_load_lds_dwordx4 v[156:157], off
	v_mfma_f32_32x32x16_bf16 v[32:47], v[132:135], v[140:143], v[32:47]
	s_add_u32 m0, s27, 106496
	v_lshl_add_u64 v[152:153], v[194:195], 0, s[24:25]
	global_load_lds_dwordx4 v[152:153], off
	s_add_u32 m0, s27, 81920
	v_lshl_add_u64 v[154:155], v[196:197], 0, s[20:21]
	global_load_lds_dwordx4 v[154:155], off
	s_add_u32 m0, s27, 114688
	v_lshl_add_u64 v[156:157], v[196:197], 0, s[24:25]
	global_load_lds_dwordx4 v[156:157], off
	s_add_u32 m0, s27, 90112
	v_lshl_add_u64 v[152:153], v[198:199], 0, s[20:21]
	global_load_lds_dwordx4 v[152:153], off
	s_add_u32 m0, s27, 122880
	v_lshl_add_u64 v[154:155], v[198:199], 0, s[24:25]
	global_load_lds_dwordx4 v[154:155], off
	ds_read_b128 v[128:131], v185
	ds_read_b128 v[136:139], v189
	ds_read_b128 v[132:135], v185 offset:4096
	ds_read_b128 v[140:143], v189 offset:4096
	s_waitcnt lgkmcnt(4)
	v_mfma_f32_32x32x16_bf16 v[112:127], v[160:163], v[168:171], v[112:127]
	v_mfma_f32_32x32x16_bf16 v[48:63], v[164:167], v[168:171], v[48:63]
	v_mfma_f32_32x32x16_bf16 v[96:111], v[160:163], v[172:175], v[96:111]
	v_mfma_f32_32x32x16_bf16 v[32:47], v[164:167], v[172:175], v[32:47]
	ds_read_b128 v[160:163], v186
	ds_read_b128 v[168:171], v190
	ds_read_b128 v[164:167], v186 offset:4096
	ds_read_b128 v[172:175], v190 offset:4096
	s_waitcnt lgkmcnt(4)
	v_mfma_f32_32x32x16_bf16 v[112:127], v[128:131], v[136:139], v[112:127]
	v_mfma_f32_32x32x16_bf16 v[48:63], v[132:135], v[136:139], v[48:63]
	v_mfma_f32_32x32x16_bf16 v[96:111], v[128:131], v[140:143], v[96:111]
	v_mfma_f32_32x32x16_bf16 v[32:47], v[132:135], v[140:143], v[32:47]
	ds_read_b128 v[128:131], v187
	ds_read_b128 v[136:139], v191
	ds_read_b128 v[132:135], v187 offset:4096
	ds_read_b128 v[140:143], v191 offset:4096
	s_waitcnt lgkmcnt(4)
	v_mfma_f32_32x32x16_bf16 v[112:127], v[160:163], v[168:171], v[112:127]
	v_mfma_f32_32x32x16_bf16 v[48:63], v[164:167], v[168:171], v[48:63]
	v_mfma_f32_32x32x16_bf16 v[96:111], v[160:163], v[172:175], v[96:111]
	v_mfma_f32_32x32x16_bf16 v[32:47], v[164:167], v[172:175], v[32:47]
	s_waitcnt vmcnt(0) lgkmcnt(0)
	s_barrier
	v_xor_b32_e32 v184, 0x10000, v184
	v_xor_b32_e32 v188, 0x10000, v188
	ds_read_b128 v[160:163], v184
	ds_read_b128 v[168:171], v188
	ds_read_b128 v[164:167], v184 offset:4096
	ds_read_b128 v[172:175], v188 offset:4096
	s_add_u32 s20, s16, 1792
	s_addc_u32 s21, s17, 0
	s_add_u32 s24, s18, 1792
	s_addc_u32 s25, s19, 0
	v_mfma_f32_32x32x16_bf16 v[112:127], v[128:131], v[136:139], v[112:127]
	v_xor_b32_e32 v185, 0x10000, v185
	v_xor_b32_e32 v189, 0x10000, v189
	s_add_u32 m0, s27, 0
	v_lshl_add_u64 v[152:153], v[192:193], 0, s[20:21]
	global_load_lds_dwordx4 v[152:153], off
	v_mfma_f32_32x32x16_bf16 v[48:63], v[132:135], v[136:139], v[48:63]
	v_xor_b32_e32 v186, 0x10000, v186
	v_xor_b32_e32 v190, 0x10000, v190
	s_add_u32 m0, s27, 32768
	v_lshl_add_u64 v[154:155], v[192:193], 0, s[24:25]
	global_load_lds_dwordx4 v[154:155], off
	v_mfma_f32_32x32x16_bf16 v[96:111], v[128:131], v[140:143], v[96:111]
	v_xor_b32_e32 v187, 0x10000, v187
	v_xor_b32_e32 v191, 0x10000, v191
	s_add_u32 m0, s27, 8192
	v_lshl_add_u64 v[156:157], v[194:195], 0, s[20:21]
	global_load_lds_dwordx4 v[156:157], off
	v_mfma_f32_32x32x16_bf16 v[32:47], v[132:135], v[140:143], v[32:47]
	s_add_u32 m0, s27, 40960
	v_lshl_add_u64 v[152:153], v[194:195], 0, s[24:25]
	global_load_lds_dwordx4 v[152:153], off
	s_add_u32 m0, s27, 16384
	v_lshl_add_u64 v[154:155], v[196:197], 0, s[20:21]
	global_load_lds_dwordx4 v[154:155], off
	s_add_u32 m0, s27, 49152
	v_lshl_add_u64 v[156:157], v[196:197], 0, s[24:25]
	global_load_lds_dwordx4 v[156:157], off
	s_add_u32 m0, s27, 24576
	v_lshl_add_u64 v[152:153], v[198:199], 0, s[20:21]
	global_load_lds_dwordx4 v[152:153], off
	s_add_u32 m0, s27, 57344
	v_lshl_add_u64 v[154:155], v[198:199], 0, s[24:25]
	global_load_lds_dwordx4 v[154:155], off
	ds_read_b128 v[128:131], v185
	ds_read_b128 v[136:139], v189
	ds_read_b128 v[132:135], v185 offset:4096
	ds_read_b128 v[140:143], v189 offset:4096
	s_waitcnt lgkmcnt(4)
	v_mfma_f32_32x32x16_bf16 v[112:127], v[160:163], v[168:171], v[112:127]
	v_mfma_f32_32x32x16_bf16 v[48:63], v[164:167], v[168:171], v[48:63]
	v_mfma_f32_32x32x16_bf16 v[96:111], v[160:163], v[172:175], v[96:111]
	v_mfma_f32_32x32x16_bf16 v[32:47], v[164:167], v[172:175], v[32:47]
	ds_read_b128 v[160:163], v186
	ds_read_b128 v[168:171], v190
	ds_read_b128 v[164:167], v186 offset:4096
	ds_read_b128 v[172:175], v190 offset:4096
	s_waitcnt lgkmcnt(4)
	v_mfma_f32_32x32x16_bf16 v[112:127], v[128:131], v[136:139], v[112:127]
	v_mfma_f32_32x32x16_bf16 v[48:63], v[132:135], v[136:139], v[48:63]
	v_mfma_f32_32x32x16_bf16 v[96:111], v[128:131], v[140:143], v[96:111]
	v_mfma_f32_32x32x16_bf16 v[32:47], v[132:135], v[140:143], v[32:47]
	ds_read_b128 v[128:131], v187
	ds_read_b128 v[136:139], v191
	ds_read_b128 v[132:135], v187 offset:4096
	ds_read_b128 v[140:143], v191 offset:4096
	s_waitcnt lgkmcnt(4)
	v_mfma_f32_32x32x16_bf16 v[112:127], v[160:163], v[168:171], v[112:127]
	v_mfma_f32_32x32x16_bf16 v[48:63], v[164:167], v[168:171], v[48:63]
	v_mfma_f32_32x32x16_bf16 v[96:111], v[160:163], v[172:175], v[96:111]
	v_mfma_f32_32x32x16_bf16 v[32:47], v[164:167], v[172:175], v[32:47]
	s_waitcnt vmcnt(0) lgkmcnt(0)
	s_barrier
	v_xor_b32_e32 v184, 0x10000, v184
	v_xor_b32_e32 v188, 0x10000, v188
	ds_read_b128 v[160:163], v184
	ds_read_b128 v[168:171], v188
	ds_read_b128 v[164:167], v184 offset:4096
	ds_read_b128 v[172:175], v188 offset:4096
	s_add_u32 s20, s16, 1920
	s_addc_u32 s21, s17, 0
	s_add_u32 s24, s18, 1920
	s_addc_u32 s25, s19, 0
	v_mfma_f32_32x32x16_bf16 v[112:127], v[128:131], v[136:139], v[112:127]
	v_xor_b32_e32 v185, 0x10000, v185
	v_xor_b32_e32 v189, 0x10000, v189
	s_add_u32 m0, s27, 65536
	v_lshl_add_u64 v[152:153], v[192:193], 0, s[20:21]
	global_load_lds_dwordx4 v[152:153], off
	v_mfma_f32_32x32x16_bf16 v[48:63], v[132:135], v[136:139], v[48:63]
	v_xor_b32_e32 v186, 0x10000, v186
	v_xor_b32_e32 v190, 0x10000, v190
	s_add_u32 m0, s27, 98304
	v_lshl_add_u64 v[154:155], v[192:193], 0, s[24:25]
	global_load_lds_dwordx4 v[154:155], off
	v_mfma_f32_32x32x16_bf16 v[96:111], v[128:131], v[140:143], v[96:111]
	v_xor_b32_e32 v187, 0x10000, v187
	v_xor_b32_e32 v191, 0x10000, v191
	s_add_u32 m0, s27, 73728
	v_lshl_add_u64 v[156:157], v[194:195], 0, s[20:21]
	global_load_lds_dwordx4 v[156:157], off
	v_mfma_f32_32x32x16_bf16 v[32:47], v[132:135], v[140:143], v[32:47]
	s_add_u32 m0, s27, 106496
	v_lshl_add_u64 v[152:153], v[194:195], 0, s[24:25]
	global_load_lds_dwordx4 v[152:153], off
	s_add_u32 m0, s27, 81920
	v_lshl_add_u64 v[154:155], v[196:197], 0, s[20:21]
	global_load_lds_dwordx4 v[154:155], off
	s_add_u32 m0, s27, 114688
	v_lshl_add_u64 v[156:157], v[196:197], 0, s[24:25]
	global_load_lds_dwordx4 v[156:157], off
	s_add_u32 m0, s27, 90112
	v_lshl_add_u64 v[152:153], v[198:199], 0, s[20:21]
	global_load_lds_dwordx4 v[152:153], off
	s_add_u32 m0, s27, 122880
	v_lshl_add_u64 v[154:155], v[198:199], 0, s[24:25]
	global_load_lds_dwordx4 v[154:155], off
	ds_read_b128 v[128:131], v185
	ds_read_b128 v[136:139], v189
	ds_read_b128 v[132:135], v185 offset:4096
	ds_read_b128 v[140:143], v189 offset:4096
	s_waitcnt lgkmcnt(4)
	v_mfma_f32_32x32x16_bf16 v[112:127], v[160:163], v[168:171], v[112:127]
	v_mfma_f32_32x32x16_bf16 v[48:63], v[164:167], v[168:171], v[48:63]
	v_mfma_f32_32x32x16_bf16 v[96:111], v[160:163], v[172:175], v[96:111]
	v_mfma_f32_32x32x16_bf16 v[32:47], v[164:167], v[172:175], v[32:47]
	ds_read_b128 v[160:163], v186
	ds_read_b128 v[168:171], v190
	ds_read_b128 v[164:167], v186 offset:4096
	ds_read_b128 v[172:175], v190 offset:4096
	s_waitcnt lgkmcnt(4)
	v_mfma_f32_32x32x16_bf16 v[112:127], v[128:131], v[136:139], v[112:127]
	v_mfma_f32_32x32x16_bf16 v[48:63], v[132:135], v[136:139], v[48:63]
	v_mfma_f32_32x32x16_bf16 v[96:111], v[128:131], v[140:143], v[96:111]
	v_mfma_f32_32x32x16_bf16 v[32:47], v[132:135], v[140:143], v[32:47]
	ds_read_b128 v[128:131], v187
	ds_read_b128 v[136:139], v191
	ds_read_b128 v[132:135], v187 offset:4096
	ds_read_b128 v[140:143], v191 offset:4096
	s_waitcnt lgkmcnt(4)
	v_mfma_f32_32x32x16_bf16 v[112:127], v[160:163], v[168:171], v[112:127]
	v_mfma_f32_32x32x16_bf16 v[48:63], v[164:167], v[168:171], v[48:63]
	v_mfma_f32_32x32x16_bf16 v[96:111], v[160:163], v[172:175], v[96:111]
	v_mfma_f32_32x32x16_bf16 v[32:47], v[164:167], v[172:175], v[32:47]
	s_waitcnt vmcnt(0) lgkmcnt(0)
	s_barrier
	v_xor_b32_e32 v184, 0x10000, v184
	v_xor_b32_e32 v188, 0x10000, v188
	ds_read_b128 v[160:163], v184
	ds_read_b128 v[168:171], v188
	ds_read_b128 v[164:167], v184 offset:4096
	ds_read_b128 v[172:175], v188 offset:4096
	s_add_u32 s37, s30, s42
	s_cmpk_ge_u32 s37, 0x780
	s_cbranch_scc1 .Lip11_lc_nonext
	s_mul_hi_u32 s38, s37, 0x92492493
	s_lshr_b32 s38, s38, 3
	s_mul_i32 s39, s38, 14
	s_sub_u32 s39, s37, s39
	s_sub_u32 s98, s37, 0x700
	s_cmpk_lt_u32 s37, 0x700
	s_cselect_b32 s39, s39, 14
	s_cselect_b32 s38, s38, s98
	s_lshl_b32 s98, s38, 19
	s_add_u32 s16, s4, s98
	s_addc_u32 s17, s5, 0
	s_lshl_b32 s98, s39, 19
	s_add_u32 s18, s6, s98
	s_addc_u32 s19, s7, 0
	v_mfma_f32_32x32x16_bf16 v[112:127], v[128:131], v[136:139], v[112:127]
	v_xor_b32_e32 v185, 0x10000, v185
	v_xor_b32_e32 v189, 0x10000, v189
	s_add_u32 m0, s27, 0
	v_lshl_add_u64 v[152:153], v[192:193], 0, s[16:17]
	global_load_lds_dwordx4 v[152:153], off
	v_mfma_f32_32x32x16_bf16 v[48:63], v[132:135], v[136:139], v[48:63]
	v_xor_b32_e32 v186, 0x10000, v186
	v_xor_b32_e32 v190, 0x10000, v190
	s_add_u32 m0, s27, 32768
	v_lshl_add_u64 v[154:155], v[192:193], 0, s[18:19]
	global_load_lds_dwordx4 v[154:155], off
	v_mfma_f32_32x32x16_bf16 v[96:111], v[128:131], v[140:143], v[96:111]
	v_xor_b32_e32 v187, 0x10000, v187
	v_xor_b32_e32 v191, 0x10000, v191
	s_add_u32 m0, s27, 8192
	v_lshl_add_u64 v[156:157], v[194:195], 0, s[16:17]
	global_load_lds_dwordx4 v[156:157], off
	v_mfma_f32_32x32x16_bf16 v[32:47], v[132:135], v[140:143], v[32:47]
	s_add_u32 m0, s27, 40960
	v_lshl_add_u64 v[152:153], v[194:195], 0, s[18:19]
	global_load_lds_dwordx4 v[152:153], off
	s_add_u32 m0, s27, 16384
	v_lshl_add_u64 v[154:155], v[196:197], 0, s[16:17]
	global_load_lds_dwordx4 v[154:155], off
	s_add_u32 m0, s27, 49152
	v_lshl_add_u64 v[156:157], v[196:197], 0, s[18:19]
	global_load_lds_dwordx4 v[156:157], off
	s_add_u32 m0, s27, 24576
	v_lshl_add_u64 v[152:153], v[198:199], 0, s[16:17]
	global_load_lds_dwordx4 v[152:153], off
	s_add_u32 m0, s27, 57344
	v_lshl_add_u64 v[154:155], v[198:199], 0, s[18:19]
	global_load_lds_dwordx4 v[154:155], off
	s_branch .Lip11_lc_join

.Lip11_lc_join:
	ds_read_b128 v[128:131], v185
	ds_read_b128 v[136:139], v189
	ds_read_b128 v[132:135], v185 offset:4096
	ds_read_b128 v[140:143], v189 offset:4096
	s_waitcnt lgkmcnt(4)
	v_mfma_f32_32x32x16_bf16 v[112:127], v[160:163], v[168:171], v[112:127]
	v_mfma_f32_32x32x16_bf16 v[48:63], v[164:167], v[168:171], v[48:63]
	v_mfma_f32_32x32x16_bf16 v[96:111], v[160:163], v[172:175], v[96:111]
	v_mfma_f32_32x32x16_bf16 v[32:47], v[164:167], v[172:175], v[32:47]
	ds_read_b128 v[160:163], v186
	ds_read_b128 v[168:171], v190
	ds_read_b128 v[164:167], v186 offset:4096
	ds_read_b128 v[172:175], v190 offset:4096
	s_waitcnt lgkmcnt(4)
	v_mfma_f32_32x32x16_bf16 v[112:127], v[128:131], v[136:139], v[112:127]
	v_mfma_f32_32x32x16_bf16 v[48:63], v[132:135], v[136:139], v[48:63]
	v_mfma_f32_32x32x16_bf16 v[96:111], v[128:131], v[140:143], v[96:111]
	v_mfma_f32_32x32x16_bf16 v[32:47], v[132:135], v[140:143], v[32:47]
	ds_read_b128 v[128:131], v187
	ds_read_b128 v[136:139], v191
	ds_read_b128 v[132:135], v187 offset:4096
	ds_read_b128 v[140:143], v191 offset:4096
	s_waitcnt lgkmcnt(4)
	v_mfma_f32_32x32x16_bf16 v[112:127], v[160:163], v[168:171], v[112:127]
	v_mfma_f32_32x32x16_bf16 v[48:63], v[164:167], v[168:171], v[48:63]
	v_mfma_f32_32x32x16_bf16 v[96:111], v[160:163], v[172:175], v[96:111]
	v_mfma_f32_32x32x16_bf16 v[32:47], v[164:167], v[172:175], v[32:47]
	s_waitcnt vmcnt(0) lgkmcnt(0)
	s_barrier
	v_xor_b32_e32 v184, 0x10000, v184
	v_xor_b32_e32 v188, 0x10000, v188
	v_mfma_f32_32x32x16_bf16 v[112:127], v[128:131], v[136:139], v[112:127]
	v_xor_b32_e32 v185, 0x10000, v185
	v_xor_b32_e32 v189, 0x10000, v189
	v_mfma_f32_32x32x16_bf16 v[48:63], v[132:135], v[136:139], v[48:63]
	v_xor_b32_e32 v186, 0x10000, v186
	v_xor_b32_e32 v190, 0x10000, v190
	v_mfma_f32_32x32x16_bf16 v[96:111], v[128:131], v[140:143], v[96:111]
	v_xor_b32_e32 v187, 0x10000, v187
	v_xor_b32_e32 v191, 0x10000, v191
	v_mfma_f32_32x32x16_bf16 v[32:47], v[132:135], v[140:143], v[32:47]
	s_branch .Lip11_epi
.Lip11_lload:
	s_waitcnt vmcnt(0) lgkmcnt(0)
	s_barrier
	s_add_u32 s20, s16, 256
	s_addc_u32 s21, s17, 0
	s_add_u32 s24, s18, 256
	s_addc_u32 s25, s19, 0
	s_add_u32 m0, s27, 0
	v_lshl_add_u64 v[152:153], v[192:193], 0, s[20:21]
	global_load_lds_dwordx4 v[152:153], off
	s_add_u32 m0, s27, 32768
	v_lshl_add_u64 v[154:155], v[192:193], 0, s[24:25]
	global_load_lds_dwordx4 v[154:155], off
	s_add_u32 m0, s27, 8192
	v_lshl_add_u64 v[156:157], v[194:195], 0, s[20:21]
	global_load_lds_dwordx4 v[156:157], off
	s_add_u32 m0, s27, 40960
	v_lshl_add_u64 v[152:153], v[194:195], 0, s[24:25]
	global_load_lds_dwordx4 v[152:153], off
	s_add_u32 m0, s27, 16384
	v_lshl_add_u64 v[154:155], v[196:197], 0, s[20:21]
	global_load_lds_dwordx4 v[154:155], off
	s_add_u32 m0, s27, 49152
	v_lshl_add_u64 v[156:157], v[196:197], 0, s[24:25]
	global_load_lds_dwordx4 v[156:157], off
	s_add_u32 m0, s27, 24576
	v_lshl_add_u64 v[152:153], v[198:199], 0, s[20:21]
	global_load_lds_dwordx4 v[152:153], off
	s_add_u32 m0, s27, 57344
	v_lshl_add_u64 v[154:155], v[198:199], 0, s[24:25]
	global_load_lds_dwordx4 v[154:155], off
	s_waitcnt vmcnt(0) lgkmcnt(0)
	s_barrier
	s_add_u32 s20, s16, 384
	s_addc_u32 s21, s17, 0
	s_add_u32 s24, s18, 384
	s_addc_u32 s25, s19, 0
	s_add_u32 m0, s27, 65536
	v_lshl_add_u64 v[152:153], v[192:193], 0, s[20:21]
	global_load_lds_dwordx4 v[152:153], off
	s_add_u32 m0, s27, 98304
	v_lshl_add_u64 v[154:155], v[192:193], 0, s[24:25]
	global_load_lds_dwordx4 v[154:155], off
	s_add_u32 m0, s27, 73728
	v_lshl_add_u64 v[156:157], v[194:195], 0, s[20:21]
	global_load_lds_dwordx4 v[156:157], off
	s_add_u32 m0, s27, 106496
	v_lshl_add_u64 v[152:153], v[194:195], 0, s[24:25]
	global_load_lds_dwordx4 v[152:153], off
	s_add_u32 m0, s27, 81920
	v_lshl_add_u64 v[154:155], v[196:197], 0, s[20:21]
	global_load_lds_dwordx4 v[154:155], off
	s_add_u32 m0, s27, 114688
	v_lshl_add_u64 v[156:157], v[196:197], 0, s[24:25]
	global_load_lds_dwordx4 v[156:157], off
	s_add_u32 m0, s27, 90112
	v_lshl_add_u64 v[152:153], v[198:199], 0, s[20:21]
	global_load_lds_dwordx4 v[152:153], off
	s_add_u32 m0, s27, 122880
	v_lshl_add_u64 v[154:155], v[198:199], 0, s[24:25]
	global_load_lds_dwordx4 v[154:155], off
	s_waitcnt vmcnt(0) lgkmcnt(0)
	s_barrier
	s_add_u32 s20, s16, 512
	s_addc_u32 s21, s17, 0
	s_add_u32 s24, s18, 512
	s_addc_u32 s25, s19, 0
	s_add_u32 m0, s27, 0
	v_lshl_add_u64 v[152:153], v[192:193], 0, s[20:21]
	global_load_lds_dwordx4 v[152:153], off
	s_add_u32 m0, s27, 32768
	v_lshl_add_u64 v[154:155], v[192:193], 0, s[24:25]
	global_load_lds_dwordx4 v[154:155], off
	s_add_u32 m0, s27, 8192
	v_lshl_add_u64 v[156:157], v[194:195], 0, s[20:21]
	global_load_lds_dwordx4 v[156:157], off
	s_add_u32 m0, s27, 40960
	v_lshl_add_u64 v[152:153], v[194:195], 0, s[24:25]
	global_load_lds_dwordx4 v[152:153], off
	s_add_u32 m0, s27, 16384
	v_lshl_add_u64 v[154:155], v[196:197], 0, s[20:21]
	global_load_lds_dwordx4 v[154:155], off
	s_add_u32 m0, s27, 49152
	v_lshl_add_u64 v[156:157], v[196:197], 0, s[24:25]
	global_load_lds_dwordx4 v[156:157], off
	s_add_u32 m0, s27, 24576
	v_lshl_add_u64 v[152:153], v[198:199], 0, s[20:21]
	global_load_lds_dwordx4 v[152:153], off
	s_add_u32 m0, s27, 57344
	v_lshl_add_u64 v[154:155], v[198:199], 0, s[24:25]
	global_load_lds_dwordx4 v[154:155], off
	s_waitcnt vmcnt(0) lgkmcnt(0)
	s_barrier
	s_add_u32 s20, s16, 640
	s_addc_u32 s21, s17, 0
	s_add_u32 s24, s18, 640
	s_addc_u32 s25, s19, 0
	s_add_u32 m0, s27, 65536
	v_lshl_add_u64 v[152:153], v[192:193], 0, s[20:21]
	global_load_lds_dwordx4 v[152:153], off
	s_add_u32 m0, s27, 98304
	v_lshl_add_u64 v[154:155], v[192:193], 0, s[24:25]
	global_load_lds_dwordx4 v[154:155], off
	s_add_u32 m0, s27, 73728
	v_lshl_add_u64 v[156:157], v[194:195], 0, s[20:21]
	global_load_lds_dwordx4 v[156:157], off
	s_add_u32 m0, s27, 106496
	v_lshl_add_u64 v[152:153], v[194:195], 0, s[24:25]
	global_load_lds_dwordx4 v[152:153], off
	s_add_u32 m0, s27, 81920
	v_lshl_add_u64 v[154:155], v[196:197], 0, s[20:21]
	global_load_lds_dwordx4 v[154:155], off
	s_add_u32 m0, s27, 114688
	v_lshl_add_u64 v[156:157], v[196:197], 0, s[24:25]
	global_load_lds_dwordx4 v[156:157], off
	s_add_u32 m0, s27, 90112
	v_lshl_add_u64 v[152:153], v[198:199], 0, s[20:21]
	global_load_lds_dwordx4 v[152:153], off
	s_add_u32 m0, s27, 122880
	v_lshl_add_u64 v[154:155], v[198:199], 0, s[24:25]
	global_load_lds_dwordx4 v[154:155], off
	s_waitcnt vmcnt(0) lgkmcnt(0)
	s_barrier
	s_add_u32 s20, s16, 768
	s_addc_u32 s21, s17, 0
	s_add_u32 s24, s18, 768
	s_addc_u32 s25, s19, 0
	s_add_u32 m0, s27, 0
	v_lshl_add_u64 v[152:153], v[192:193], 0, s[20:21]
	global_load_lds_dwordx4 v[152:153], off
	s_add_u32 m0, s27, 32768
	v_lshl_add_u64 v[154:155], v[192:193], 0, s[24:25]
	global_load_lds_dwordx4 v[154:155], off
	s_add_u32 m0, s27, 8192
	v_lshl_add_u64 v[156:157], v[194:195], 0, s[20:21]
	global_load_lds_dwordx4 v[156:157], off
	s_add_u32 m0, s27, 40960
	v_lshl_add_u64 v[152:153], v[194:195], 0, s[24:25]
	global_load_lds_dwordx4 v[152:153], off
	s_add_u32 m0, s27, 16384
	v_lshl_add_u64 v[154:155], v[196:197], 0, s[20:21]
	global_load_lds_dwordx4 v[154:155], off
	s_add_u32 m0, s27, 49152
	v_lshl_add_u64 v[156:157], v[196:197], 0, s[24:25]
	global_load_lds_dwordx4 v[156:157], off
	s_add_u32 m0, s27, 24576
	v_lshl_add_u64 v[152:153], v[198:199], 0, s[20:21]
	global_load_lds_dwordx4 v[152:153], off
	s_add_u32 m0, s27, 57344
	v_lshl_add_u64 v[154:155], v[198:199], 0, s[24:25]
	global_load_lds_dwordx4 v[154:155], off
	s_waitcnt vmcnt(0) lgkmcnt(0)
	s_barrier
	s_add_u32 s20, s16, 896
	s_addc_u32 s21, s17, 0
	s_add_u32 s24, s18, 896
	s_addc_u32 s25, s19, 0
	s_add_u32 m0, s27, 65536
	v_lshl_add_u64 v[152:153], v[192:193], 0, s[20:21]
	global_load_lds_dwordx4 v[152:153], off
	s_add_u32 m0, s27, 98304
	v_lshl_add_u64 v[154:155], v[192:193], 0, s[24:25]
	global_load_lds_dwordx4 v[154:155], off
	s_add_u32 m0, s27, 73728
	v_lshl_add_u64 v[156:157], v[194:195], 0, s[20:21]
	global_load_lds_dwordx4 v[156:157], off
	s_add_u32 m0, s27, 106496
	v_lshl_add_u64 v[152:153], v[194:195], 0, s[24:25]
	global_load_lds_dwordx4 v[152:153], off
	s_add_u32 m0, s27, 81920
	v_lshl_add_u64 v[154:155], v[196:197], 0, s[20:21]
	global_load_lds_dwordx4 v[154:155], off
	s_add_u32 m0, s27, 114688
	v_lshl_add_u64 v[156:157], v[196:197], 0, s[24:25]
	global_load_lds_dwordx4 v[156:157], off
	s_add_u32 m0, s27, 90112
	v_lshl_add_u64 v[152:153], v[198:199], 0, s[20:21]
	global_load_lds_dwordx4 v[152:153], off
	s_add_u32 m0, s27, 122880
	v_lshl_add_u64 v[154:155], v[198:199], 0, s[24:25]
	global_load_lds_dwordx4 v[154:155], off
	s_waitcnt vmcnt(0) lgkmcnt(0)
	s_barrier
	s_add_u32 s20, s16, 1024
	s_addc_u32 s21, s17, 0
	s_add_u32 s24, s18, 1024
	s_addc_u32 s25, s19, 0
	s_add_u32 m0, s27, 0
	v_lshl_add_u64 v[152:153], v[192:193], 0, s[20:21]
	global_load_lds_dwordx4 v[152:153], off
	s_add_u32 m0, s27, 32768
	v_lshl_add_u64 v[154:155], v[192:193], 0, s[24:25]
	global_load_lds_dwordx4 v[154:155], off
	s_add_u32 m0, s27, 8192
	v_lshl_add_u64 v[156:157], v[194:195], 0, s[20:21]
	global_load_lds_dwordx4 v[156:157], off
	s_add_u32 m0, s27, 40960
	v_lshl_add_u64 v[152:153], v[194:195], 0, s[24:25]
	global_load_lds_dwordx4 v[152:153], off
	s_add_u32 m0, s27, 16384
	v_lshl_add_u64 v[154:155], v[196:197], 0, s[20:21]
	global_load_lds_dwordx4 v[154:155], off
	s_add_u32 m0, s27, 49152
	v_lshl_add_u64 v[156:157], v[196:197], 0, s[24:25]
	global_load_lds_dwordx4 v[156:157], off
	s_add_u32 m0, s27, 24576
	v_lshl_add_u64 v[152:153], v[198:199], 0, s[20:21]
	global_load_lds_dwordx4 v[152:153], off
	s_add_u32 m0, s27, 57344
	v_lshl_add_u64 v[154:155], v[198:199], 0, s[24:25]
	global_load_lds_dwordx4 v[154:155], off
	s_waitcnt vmcnt(0) lgkmcnt(0)
	s_barrier
	s_add_u32 s20, s16, 1152
	s_addc_u32 s21, s17, 0
	s_add_u32 s24, s18, 1152
	s_addc_u32 s25, s19, 0
	s_add_u32 m0, s27, 65536
	v_lshl_add_u64 v[152:153], v[192:193], 0, s[20:21]
	global_load_lds_dwordx4 v[152:153], off
	s_add_u32 m0, s27, 98304
	v_lshl_add_u64 v[154:155], v[192:193], 0, s[24:25]
	global_load_lds_dwordx4 v[154:155], off
	s_add_u32 m0, s27, 73728
	v_lshl_add_u64 v[156:157], v[194:195], 0, s[20:21]
	global_load_lds_dwordx4 v[156:157], off
	s_add_u32 m0, s27, 106496
	v_lshl_add_u64 v[152:153], v[194:195], 0, s[24:25]
	global_load_lds_dwordx4 v[152:153], off
	s_add_u32 m0, s27, 81920
	v_lshl_add_u64 v[154:155], v[196:197], 0, s[20:21]
	global_load_lds_dwordx4 v[154:155], off
	s_add_u32 m0, s27, 114688
	v_lshl_add_u64 v[156:157], v[196:197], 0, s[24:25]
	global_load_lds_dwordx4 v[156:157], off
	s_add_u32 m0, s27, 90112
	v_lshl_add_u64 v[152:153], v[198:199], 0, s[20:21]
	global_load_lds_dwordx4 v[152:153], off
	s_add_u32 m0, s27, 122880
	v_lshl_add_u64 v[154:155], v[198:199], 0, s[24:25]
	global_load_lds_dwordx4 v[154:155], off
	s_waitcnt vmcnt(0) lgkmcnt(0)
	s_barrier
	s_add_u32 s20, s16, 1280
	s_addc_u32 s21, s17, 0
	s_add_u32 s24, s18, 1280
	s_addc_u32 s25, s19, 0
	s_add_u32 m0, s27, 0
	v_lshl_add_u64 v[152:153], v[192:193], 0, s[20:21]
	global_load_lds_dwordx4 v[152:153], off
	s_add_u32 m0, s27, 32768
	v_lshl_add_u64 v[154:155], v[192:193], 0, s[24:25]
	global_load_lds_dwordx4 v[154:155], off
	s_add_u32 m0, s27, 8192
	v_lshl_add_u64 v[156:157], v[194:195], 0, s[20:21]
	global_load_lds_dwordx4 v[156:157], off
	s_add_u32 m0, s27, 40960
	v_lshl_add_u64 v[152:153], v[194:195], 0, s[24:25]
	global_load_lds_dwordx4 v[152:153], off
	s_add_u32 m0, s27, 16384
	v_lshl_add_u64 v[154:155], v[196:197], 0, s[20:21]
	global_load_lds_dwordx4 v[154:155], off
	s_add_u32 m0, s27, 49152
	v_lshl_add_u64 v[156:157], v[196:197], 0, s[24:25]
	global_load_lds_dwordx4 v[156:157], off
	s_add_u32 m0, s27, 24576
	v_lshl_add_u64 v[152:153], v[198:199], 0, s[20:21]
	global_load_lds_dwordx4 v[152:153], off
	s_add_u32 m0, s27, 57344
	v_lshl_add_u64 v[154:155], v[198:199], 0, s[24:25]
	global_load_lds_dwordx4 v[154:155], off
	s_waitcnt vmcnt(0) lgkmcnt(0)
	s_barrier
	s_add_u32 s20, s16, 1408
	s_addc_u32 s21, s17, 0
	s_add_u32 s24, s18, 1408
	s_addc_u32 s25, s19, 0
	s_add_u32 m0, s27, 65536
	v_lshl_add_u64 v[152:153], v[192:193], 0, s[20:21]
	global_load_lds_dwordx4 v[152:153], off
	s_add_u32 m0, s27, 98304
	v_lshl_add_u64 v[154:155], v[192:193], 0, s[24:25]
	global_load_lds_dwordx4 v[154:155], off
	s_add_u32 m0, s27, 73728
	v_lshl_add_u64 v[156:157], v[194:195], 0, s[20:21]
	global_load_lds_dwordx4 v[156:157], off
	s_add_u32 m0, s27, 106496
	v_lshl_add_u64 v[152:153], v[194:195], 0, s[24:25]
	global_load_lds_dwordx4 v[152:153], off
	s_add_u32 m0, s27, 81920
	v_lshl_add_u64 v[154:155], v[196:197], 0, s[20:21]
	global_load_lds_dwordx4 v[154:155], off
	s_add_u32 m0, s27, 114688
	v_lshl_add_u64 v[156:157], v[196:197], 0, s[24:25]
	global_load_lds_dwordx4 v[156:157], off
	s_add_u32 m0, s27, 90112
	v_lshl_add_u64 v[152:153], v[198:199], 0, s[20:21]
	global_load_lds_dwordx4 v[152:153], off
	s_add_u32 m0, s27, 122880
	v_lshl_add_u64 v[154:155], v[198:199], 0, s[24:25]
	global_load_lds_dwordx4 v[154:155], off
	s_waitcnt vmcnt(0) lgkmcnt(0)
	s_barrier
	s_add_u32 s20, s16, 1536
	s_addc_u32 s21, s17, 0
	s_add_u32 s24, s18, 1536
	s_addc_u32 s25, s19, 0
	s_add_u32 m0, s27, 0
	v_lshl_add_u64 v[152:153], v[192:193], 0, s[20:21]
	global_load_lds_dwordx4 v[152:153], off
	s_add_u32 m0, s27, 32768
	v_lshl_add_u64 v[154:155], v[192:193], 0, s[24:25]
	global_load_lds_dwordx4 v[154:155], off
	s_add_u32 m0, s27, 8192
	v_lshl_add_u64 v[156:157], v[194:195], 0, s[20:21]
	global_load_lds_dwordx4 v[156:157], off
	s_add_u32 m0, s27, 40960
	v_lshl_add_u64 v[152:153], v[194:195], 0, s[24:25]
	global_load_lds_dwordx4 v[152:153], off
	s_add_u32 m0, s27, 16384
	v_lshl_add_u64 v[154:155], v[196:197], 0, s[20:21]
	global_load_lds_dwordx4 v[154:155], off
	s_add_u32 m0, s27, 49152
	v_lshl_add_u64 v[156:157], v[196:197], 0, s[24:25]
	global_load_lds_dwordx4 v[156:157], off
	s_add_u32 m0, s27, 24576
	v_lshl_add_u64 v[152:153], v[198:199], 0, s[20:21]
	global_load_lds_dwordx4 v[152:153], off
	s_add_u32 m0, s27, 57344
	v_lshl_add_u64 v[154:155], v[198:199], 0, s[24:25]
	global_load_lds_dwordx4 v[154:155], off
	s_waitcnt vmcnt(0) lgkmcnt(0)
	s_barrier
	s_add_u32 s20, s16, 1664
	s_addc_u32 s21, s17, 0
	s_add_u32 s24, s18, 1664
	s_addc_u32 s25, s19, 0
	s_add_u32 m0, s27, 65536
	v_lshl_add_u64 v[152:153], v[192:193], 0, s[20:21]
	global_load_lds_dwordx4 v[152:153], off
	s_add_u32 m0, s27, 98304
	v_lshl_add_u64 v[154:155], v[192:193], 0, s[24:25]
	global_load_lds_dwordx4 v[154:155], off
	s_add_u32 m0, s27, 73728
	v_lshl_add_u64 v[156:157], v[194:195], 0, s[20:21]
	global_load_lds_dwordx4 v[156:157], off
	s_add_u32 m0, s27, 106496
	v_lshl_add_u64 v[152:153], v[194:195], 0, s[24:25]
	global_load_lds_dwordx4 v[152:153], off
	s_add_u32 m0, s27, 81920
	v_lshl_add_u64 v[154:155], v[196:197], 0, s[20:21]
	global_load_lds_dwordx4 v[154:155], off
	s_add_u32 m0, s27, 114688
	v_lshl_add_u64 v[156:157], v[196:197], 0, s[24:25]
	global_load_lds_dwordx4 v[156:157], off
	s_add_u32 m0, s27, 90112
	v_lshl_add_u64 v[152:153], v[198:199], 0, s[20:21]
	global_load_lds_dwordx4 v[152:153], off
	s_add_u32 m0, s27, 122880
	v_lshl_add_u64 v[154:155], v[198:199], 0, s[24:25]
	global_load_lds_dwordx4 v[154:155], off
	s_waitcnt vmcnt(0) lgkmcnt(0)
	s_barrier
	s_add_u32 s20, s16, 1792
	s_addc_u32 s21, s17, 0
	s_add_u32 s24, s18, 1792
	s_addc_u32 s25, s19, 0
	s_add_u32 m0, s27, 0
	v_lshl_add_u64 v[152:153], v[192:193], 0, s[20:21]
	global_load_lds_dwordx4 v[152:153], off
	s_add_u32 m0, s27, 32768
	v_lshl_add_u64 v[154:155], v[192:193], 0, s[24:25]
	global_load_lds_dwordx4 v[154:155], off
	s_add_u32 m0, s27, 8192
	v_lshl_add_u64 v[156:157], v[194:195], 0, s[20:21]
	global_load_lds_dwordx4 v[156:157], off
	s_add_u32 m0, s27, 40960
	v_lshl_add_u64 v[152:153], v[194:195], 0, s[24:25]
	global_load_lds_dwordx4 v[152:153], off
	s_add_u32 m0, s27, 16384
	v_lshl_add_u64 v[154:155], v[196:197], 0, s[20:21]
	global_load_lds_dwordx4 v[154:155], off
	s_add_u32 m0, s27, 49152
	v_lshl_add_u64 v[156:157], v[196:197], 0, s[24:25]
	global_load_lds_dwordx4 v[156:157], off
	s_add_u32 m0, s27, 24576
	v_lshl_add_u64 v[152:153], v[198:199], 0, s[20:21]
	global_load_lds_dwordx4 v[152:153], off
	s_add_u32 m0, s27, 57344
	v_lshl_add_u64 v[154:155], v[198:199], 0, s[24:25]
	global_load_lds_dwordx4 v[154:155], off
	s_waitcnt vmcnt(0) lgkmcnt(0)
	s_barrier
	s_add_u32 s20, s16, 1920
	s_addc_u32 s21, s17, 0
	s_add_u32 s24, s18, 1920
	s_addc_u32 s25, s19, 0
	s_add_u32 m0, s27, 65536
	v_lshl_add_u64 v[152:153], v[192:193], 0, s[20:21]
	global_load_lds_dwordx4 v[152:153], off
	s_add_u32 m0, s27, 98304
	v_lshl_add_u64 v[154:155], v[192:193], 0, s[24:25]
	global_load_lds_dwordx4 v[154:155], off
	s_add_u32 m0, s27, 73728
	v_lshl_add_u64 v[156:157], v[194:195], 0, s[20:21]
	global_load_lds_dwordx4 v[156:157], off
	s_add_u32 m0, s27, 106496
	v_lshl_add_u64 v[152:153], v[194:195], 0, s[24:25]
	global_load_lds_dwordx4 v[152:153], off
	s_add_u32 m0, s27, 81920
	v_lshl_add_u64 v[154:155], v[196:197], 0, s[20:21]
	global_load_lds_dwordx4 v[154:155], off
	s_add_u32 m0, s27, 114688
	v_lshl_add_u64 v[156:157], v[196:197], 0, s[24:25]
	global_load_lds_dwordx4 v[156:157], off
	s_add_u32 m0, s27, 90112
	v_lshl_add_u64 v[152:153], v[198:199], 0, s[20:21]
	global_load_lds_dwordx4 v[152:153], off
	s_add_u32 m0, s27, 122880
	v_lshl_add_u64 v[154:155], v[198:199], 0, s[24:25]
	global_load_lds_dwordx4 v[154:155], off
	s_waitcnt vmcnt(0) lgkmcnt(0)
	s_barrier
	s_add_u32 s37, s30, s42
	s_cmpk_ge_u32 s37, 0x780
	s_cbranch_scc1 .Lip11_ll_nonext
	s_mul_hi_u32 s38, s37, 0x92492493
	s_lshr_b32 s38, s38, 3
	s_mul_i32 s39, s38, 14
	s_sub_u32 s39, s37, s39
	s_sub_u32 s98, s37, 0x700
	s_cmpk_lt_u32 s37, 0x700
	s_cselect_b32 s39, s39, 14
	s_cselect_b32 s38, s38, s98
	s_lshl_b32 s98, s38, 19
	s_add_u32 s16, s4, s98
	s_addc_u32 s17, s5, 0
	s_lshl_b32 s98, s39, 19
	s_add_u32 s18, s6, s98
	s_addc_u32 s19, s7, 0
	s_add_u32 m0, s27, 0
	v_lshl_add_u64 v[152:153], v[192:193], 0, s[16:17]
	global_load_lds_dwordx4 v[152:153], off
	s_add_u32 m0, s27, 32768
	v_lshl_add_u64 v[154:155], v[192:193], 0, s[18:19]
	global_load_lds_dwordx4 v[154:155], off
	s_add_u32 m0, s27, 8192
	v_lshl_add_u64 v[156:157], v[194:195], 0, s[16:17]
	global_load_lds_dwordx4 v[156:157], off
	s_add_u32 m0, s27, 40960
	v_lshl_add_u64 v[152:153], v[194:195], 0, s[18:19]
	global_load_lds_dwordx4 v[152:153], off
	s_add_u32 m0, s27, 16384
	v_lshl_add_u64 v[154:155], v[196:197], 0, s[16:17]
	global_load_lds_dwordx4 v[154:155], off
	s_add_u32 m0, s27, 49152
	v_lshl_add_u64 v[156:157], v[196:197], 0, s[18:19]
	global_load_lds_dwordx4 v[156:157], off
	s_add_u32 m0, s27, 24576
	v_lshl_add_u64 v[152:153], v[198:199], 0, s[16:17]
	global_load_lds_dwordx4 v[152:153], off
	s_add_u32 m0, s27, 57344
	v_lshl_add_u64 v[154:155], v[198:199], 0, s[18:19]
	global_load_lds_dwordx4 v[154:155], off
	s_branch .Lip11_ll_join
.Lip11_ll_nonext:
.Lip11_ll_join:
	s_waitcnt vmcnt(0) lgkmcnt(0)
	s_barrier
.Lip11_epi:
	s_mul_i32 s39, s35, 15
	s_add_u32 s39, s39, s36
	s_nop 7
	v_mbcnt_hi_u32_b32 v224, -1, v210
	v_and_b32_e32 v225, 31, v224
	v_lshrrev_b32_e32 v226, 5, v224
	v_lshlrev_b32_e32 v201, 3, v225
	v_lshlrev_b32_e32 v221, 2, v226
	s_lshr_b32 s90, s70, 6
	s_mul_i32 s91, s90, 0x1200
	s_add_u32 s91, s91, 0x12000
	v_mul_u32_u24_e32 v227, 0x240, v226
	v_lshl_add_u32 v227, v225, 1, v227
	v_add_u32_e32 v211, s91, v227
	v_lshrrev_b32_e32 v222, 3, v224
	v_and_b32_e32 v228, 7, v224
	v_lshlrev_b32_e32 v223, 4, v228
	v_mul_u32_u24_e32 v227, 0x90, v222
	v_add3_u32 v220, v227, v223, s91
	s_mul_i32 s92, s35, 15
	s_sub_u32 s93, s39, s92
	s_lshl_b32 s93, s93, 8
	s_lshl_b32 s92, s35, 8
	s_lshr_b32 s94, s90, 1
	s_lshl_b32 s94, s94, 6
	s_add_u32 s92, s92, s94
	s_and_b32 s94, s90, 1
	s_lshl_b32 s94, s94, 7
	s_add_u32 s93, s93, s94

.Lep11_00_mG:
	v_mul_f32_e32 v224, 0xbfb8aa3b, v112
	v_mul_f32_e32 v225, 0xbfb8aa3b, v96
	v_exp_f32_e32 v224, v224
	v_exp_f32_e32 v225, v225
	v_add_f32_e32 v224, 1.0, v224
	v_add_f32_e32 v225, 1.0, v225
	v_rcp_f32_e32 v224, v224
	v_rcp_f32_e32 v225, v225
	s_nop 0
	v_cvt_pk_bf16_f32 v224, v224, v225
	ds_write_b16 v211, v224
	ds_write_b16_d16_hi v211, v224 offset:64
	v_mul_f32_e32 v226, 0xbfb8aa3b, v113
	v_mul_f32_e32 v227, 0xbfb8aa3b, v97
	v_exp_f32_e32 v226, v226
	v_exp_f32_e32 v227, v227
	v_add_f32_e32 v226, 1.0, v226
	v_add_f32_e32 v227, 1.0, v227
	v_rcp_f32_e32 v226, v226
	v_rcp_f32_e32 v227, v227
	s_nop 0
	v_cvt_pk_bf16_f32 v226, v226, v227
	ds_write_b16 v211, v226 offset:144
	ds_write_b16_d16_hi v211, v226 offset:208
	v_mul_f32_e32 v224, 0xbfb8aa3b, v114
	v_mul_f32_e32 v225, 0xbfb8aa3b, v98
	v_exp_f32_e32 v224, v224
	v_exp_f32_e32 v225, v225
	v_add_f32_e32 v224, 1.0, v224
	v_add_f32_e32 v225, 1.0, v225
	v_rcp_f32_e32 v224, v224
	v_rcp_f32_e32 v225, v225
	s_nop 0
	v_cvt_pk_bf16_f32 v224, v224, v225
	ds_write_b16 v211, v224 offset:288
	ds_write_b16_d16_hi v211, v224 offset:352
	v_mul_f32_e32 v226, 0xbfb8aa3b, v115
	v_mul_f32_e32 v227, 0xbfb8aa3b, v99
	v_exp_f32_e32 v226, v226
	v_exp_f32_e32 v227, v227
	v_add_f32_e32 v226, 1.0, v226
	v_add_f32_e32 v227, 1.0, v227
	v_rcp_f32_e32 v226, v226
	v_rcp_f32_e32 v227, v227
	s_nop 0
	v_cvt_pk_bf16_f32 v226, v226, v227
	ds_write_b16 v211, v226 offset:432
	ds_write_b16_d16_hi v211, v226 offset:496
	v_mul_f32_e32 v224, 0xbfb8aa3b, v116
	v_mul_f32_e32 v225, 0xbfb8aa3b, v100
	v_exp_f32_e32 v224, v224
	v_exp_f32_e32 v225, v225
	v_add_f32_e32 v224, 1.0, v224
	v_add_f32_e32 v225, 1.0, v225
	v_rcp_f32_e32 v224, v224
	v_rcp_f32_e32 v225, v225
	s_nop 0
	v_cvt_pk_bf16_f32 v224, v224, v225
	ds_write_b16 v211, v224 offset:1152
	ds_write_b16_d16_hi v211, v224 offset:1216
	v_mul_f32_e32 v226, 0xbfb8aa3b, v117
	v_mul_f32_e32 v227, 0xbfb8aa3b, v101
	v_exp_f32_e32 v226, v226
	v_exp_f32_e32 v227, v227
	v_add_f32_e32 v226, 1.0, v226
	v_add_f32_e32 v227, 1.0, v227
	v_rcp_f32_e32 v226, v226
	v_rcp_f32_e32 v227, v227
	s_nop 0
	v_cvt_pk_bf16_f32 v226, v226, v227
	ds_write_b16 v211, v226 offset:1296
	ds_write_b16_d16_hi v211, v226 offset:1360
	v_mul_f32_e32 v224, 0xbfb8aa3b, v118
	v_mul_f32_e32 v225, 0xbfb8aa3b, v102
	v_exp_f32_e32 v224, v224
	v_exp_f32_e32 v225, v225
	v_add_f32_e32 v224, 1.0, v224
	v_add_f32_e32 v225, 1.0, v225
	v_rcp_f32_e32 v224, v224
	v_rcp_f32_e32 v225, v225
	s_nop 0
	v_cvt_pk_bf16_f32 v224, v224, v225
	ds_write_b16 v211, v224 offset:1440
	ds_write_b16_d16_hi v211, v224 offset:1504
	v_mul_f32_e32 v226, 0xbfb8aa3b, v119
	v_mul_f32_e32 v227, 0xbfb8aa3b, v103
	v_exp_f32_e32 v226, v226
	v_exp_f32_e32 v227, v227
	v_add_f32_e32 v226, 1.0, v226
	v_add_f32_e32 v227, 1.0, v227
	v_rcp_f32_e32 v226, v226
	v_rcp_f32_e32 v227, v227
	s_nop 0
	v_cvt_pk_bf16_f32 v226, v226, v227
	ds_write_b16 v211, v226 offset:1584
	ds_write_b16_d16_hi v211, v226 offset:1648
	v_mul_f32_e32 v224, 0xbfb8aa3b, v120
	v_mul_f32_e32 v225, 0xbfb8aa3b, v104
	v_exp_f32_e32 v224, v224
	v_exp_f32_e32 v225, v225
	v_add_f32_e32 v224, 1.0, v224
	v_add_f32_e32 v225, 1.0, v225
	v_rcp_f32_e32 v224, v224
	v_rcp_f32_e32 v225, v225
	s_nop 0
	v_cvt_pk_bf16_f32 v224, v224, v225
	ds_write_b16 v211, v224 offset:2304
	ds_write_b16_d16_hi v211, v224 offset:2368
	v_mul_f32_e32 v226, 0xbfb8aa3b, v121
	v_mul_f32_e32 v227, 0xbfb8aa3b, v105
	v_exp_f32_e32 v226, v226
	v_exp_f32_e32 v227, v227
	v_add_f32_e32 v226, 1.0, v226
	v_add_f32_e32 v227, 1.0, v227
	v_rcp_f32_e32 v226, v226
	v_rcp_f32_e32 v227, v227
	s_nop 0
	v_cvt_pk_bf16_f32 v226, v226, v227
	ds_write_b16 v211, v226 offset:2448
	ds_write_b16_d16_hi v211, v226 offset:2512
	v_mul_f32_e32 v224, 0xbfb8aa3b, v122
	v_mul_f32_e32 v225, 0xbfb8aa3b, v106
	v_exp_f32_e32 v224, v224
	v_exp_f32_e32 v225, v225
	v_add_f32_e32 v224, 1.0, v224
	v_add_f32_e32 v225, 1.0, v225
	v_rcp_f32_e32 v224, v224
	v_rcp_f32_e32 v225, v225
	s_nop 0
	v_cvt_pk_bf16_f32 v224, v224, v225
	ds_write_b16 v211, v224 offset:2592
	ds_write_b16_d16_hi v211, v224 offset:2656
	v_mul_f32_e32 v226, 0xbfb8aa3b, v123
	v_mul_f32_e32 v227, 0xbfb8aa3b, v107
	v_exp_f32_e32 v226, v226
	v_exp_f32_e32 v227, v227
	v_add_f32_e32 v226, 1.0, v226
	v_add_f32_e32 v227, 1.0, v227
	v_rcp_f32_e32 v226, v226
	v_rcp_f32_e32 v227, v227
	s_nop 0
	v_cvt_pk_bf16_f32 v226, v226, v227
	ds_write_b16 v211, v226 offset:2736
	ds_write_b16_d16_hi v211, v226 offset:2800
	v_mul_f32_e32 v224, 0xbfb8aa3b, v124
	v_mul_f32_e32 v225, 0xbfb8aa3b, v108
	v_exp_f32_e32 v224, v224
	v_exp_f32_e32 v225, v225
	v_add_f32_e32 v224, 1.0, v224
	v_add_f32_e32 v225, 1.0, v225
	v_rcp_f32_e32 v224, v224
	v_rcp_f32_e32 v225, v225
	s_nop 0
	v_cvt_pk_bf16_f32 v224, v224, v225
	ds_write_b16 v211, v224 offset:3456
	ds_write_b16_d16_hi v211, v224 offset:3520
	v_mul_f32_e32 v226, 0xbfb8aa3b, v125
	v_mul_f32_e32 v227, 0xbfb8aa3b, v109
	v_exp_f32_e32 v226, v226
	v_exp_f32_e32 v227, v227
	v_add_f32_e32 v226, 1.0, v226
	v_add_f32_e32 v227, 1.0, v227
	v_rcp_f32_e32 v226, v226
	v_rcp_f32_e32 v227, v227
	s_nop 0
	v_cvt_pk_bf16_f32 v226, v226, v227
	ds_write_b16 v211, v226 offset:3600
	ds_write_b16_d16_hi v211, v226 offset:3664
	v_mul_f32_e32 v224, 0xbfb8aa3b, v126
	v_mul_f32_e32 v225, 0xbfb8aa3b, v110
	v_exp_f32_e32 v224, v224
	v_exp_f32_e32 v225, v225
	v_add_f32_e32 v224, 1.0, v224
	v_add_f32_e32 v225, 1.0, v225
	v_rcp_f32_e32 v224, v224
	v_rcp_f32_e32 v225, v225
	s_nop 0
	v_cvt_pk_bf16_f32 v224, v224, v225
	ds_write_b16 v211, v224 offset:3744
	ds_write_b16_d16_hi v211, v224 offset:3808
	v_mul_f32_e32 v226, 0xbfb8aa3b, v127
	v_mul_f32_e32 v227, 0xbfb8aa3b, v111
	v_exp_f32_e32 v226, v226
	v_exp_f32_e32 v227, v227
	v_add_f32_e32 v226, 1.0, v226
	v_add_f32_e32 v227, 1.0, v227
	v_rcp_f32_e32 v226, v226
	v_rcp_f32_e32 v227, v227
	s_nop 0
	v_cvt_pk_bf16_f32 v226, v226, v227
	ds_write_b16 v211, v226 offset:3888
	ds_write_b16_d16_hi v211, v226 offset:3952
	s_branch .Lep11_00_st
.Lep11_00_mP:
	v_cvt_pk_bf16_f32 v224, v112, v96
	ds_write_b16 v211, v224
	ds_write_b16_d16_hi v211, v224 offset:64
	v_cvt_pk_bf16_f32 v225, v113, v97
	ds_write_b16 v211, v225 offset:144
	ds_write_b16_d16_hi v211, v225 offset:208
	v_cvt_pk_bf16_f32 v226, v114, v98
	ds_write_b16 v211, v226 offset:288
	ds_write_b16_d16_hi v211, v226 offset:352
	v_cvt_pk_bf16_f32 v227, v115, v99
	ds_write_b16 v211, v227 offset:432
	ds_write_b16_d16_hi v211, v227 offset:496
	v_cvt_pk_bf16_f32 v224, v116, v100
	ds_write_b16 v211, v224 offset:1152
	ds_write_b16_d16_hi v211, v224 offset:1216
	v_cvt_pk_bf16_f32 v225, v117, v101
	ds_write_b16 v211, v225 offset:1296
	ds_write_b16_d16_hi v211, v225 offset:1360
	v_cvt_pk_bf16_f32 v226, v118, v102
	ds_write_b16 v211, v226 offset:1440
	ds_write_b16_d16_hi v211, v226 offset:1504
	v_cvt_pk_bf16_f32 v227, v119, v103
	ds_write_b16 v211, v227 offset:1584
	ds_write_b16_d16_hi v211, v227 offset:1648
	v_cvt_pk_bf16_f32 v224, v120, v104
	ds_write_b16 v211, v224 offset:2304
	ds_write_b16_d16_hi v211, v224 offset:2368
	v_cvt_pk_bf16_f32 v225, v121, v105
	ds_write_b16 v211, v225 offset:2448
	ds_write_b16_d16_hi v211, v225 offset:2512
	v_cvt_pk_bf16_f32 v226, v122, v106
	ds_write_b16 v211, v226 offset:2592
	ds_write_b16_d16_hi v211, v226 offset:2656
	v_cvt_pk_bf16_f32 v227, v123, v107
	ds_write_b16 v211, v227 offset:2736
	ds_write_b16_d16_hi v211, v227 offset:2800
	v_cvt_pk_bf16_f32 v224, v124, v108
	ds_write_b16 v211, v224 offset:3456
	ds_write_b16_d16_hi v211, v224 offset:3520
	v_cvt_pk_bf16_f32 v225, v125, v109
	ds_write_b16 v211, v225 offset:3600
	ds_write_b16_d16_hi v211, v225 offset:3664
	v_cvt_pk_bf16_f32 v226, v126, v110
	ds_write_b16 v211, v226 offset:3744
	ds_write_b16_d16_hi v211, v226 offset:3808
	v_cvt_pk_bf16_f32 v227, v127, v111
	ds_write_b16 v211, v227 offset:3888
	ds_write_b16_d16_hi v211, v227 offset:3952
	s_branch .Lep11_00_st
.Lep11_00_mR:
	s_load_dwordx2 s[98:99], s[0:1], 0x148
	v_add_u32_e32 v224, s94, v221
	v_lshlrev_b32_e32 v224, 8, v224
	v_add_u32_e32 v230, v224, v201
	v_mov_b32_e32 v231, 0
	s_waitcnt lgkmcnt(0)
	v_lshl_add_u64 v[230:231], s[98:99], 0, v[230:231]
	global_load_dwordx2 v[128:129], v[230:231], off
	global_load_dwordx2 v[130:131], v[230:231], off offset:256
	global_load_dwordx2 v[132:133], v[230:231], off offset:512
	global_load_dwordx2 v[134:135], v[230:231], off offset:768
	global_load_dwordx2 v[136:137], v[230:231], off offset:2048
	global_load_dwordx2 v[138:139], v[230:231], off offset:2304
	global_load_dwordx2 v[140:141], v[230:231], off offset:2560
	global_load_dwordx2 v[142:143], v[230:231], off offset:2816
	v_add_co_u32_e32 v232, vcc, 0x1000, v230
	s_nop 1
	v_addc_co_u32_e32 v233, vcc, 0, v231, vcc
	global_load_dwordx2 v[144:145], v[232:233], off
	global_load_dwordx2 v[146:147], v[232:233], off offset:256
	global_load_dwordx2 v[148:149], v[232:233], off offset:512
	global_load_dwordx2 v[150:151], v[232:233], off offset:768
	global_load_dwordx2 v[152:153], v[232:233], off offset:2048
	global_load_dwordx2 v[154:155], v[232:233], off offset:2304
	global_load_dwordx2 v[156:157], v[232:233], off offset:2560
	global_load_dwordx2 v[158:159], v[232:233], off offset:2816
	s_waitcnt vmcnt(15)
	v_mul_f32_e32 v224, v96, v129
	v_mul_f32_e32 v225, v112, v129
	v_fma_f32 v224, v112, v128, -v224
	v_fma_f32 v225, v96, v128, v225
	v_mul_f32_e32 v224, s88, v224
	v_mul_f32_e32 v225, s88, v225
	v_cvt_pk_bf16_f32 v224, v224, v225
	ds_write_b16 v211, v224
	ds_write_b16_d16_hi v211, v224 offset:64
	s_waitcnt vmcnt(14)
	v_mul_f32_e32 v224, v97, v131
	v_mul_f32_e32 v225, v113, v131
	v_fma_f32 v224, v113, v130, -v224
	v_fma_f32 v225, v97, v130, v225
	v_mul_f32_e32 v224, s88, v224
	v_mul_f32_e32 v225, s88, v225
	v_cvt_pk_bf16_f32 v224, v224, v225
	ds_write_b16 v211, v224 offset:144
	ds_write_b16_d16_hi v211, v224 offset:208
	s_waitcnt vmcnt(13)
	v_mul_f32_e32 v224, v98, v133
	v_mul_f32_e32 v225, v114, v133
	v_fma_f32 v224, v114, v132, -v224
	v_fma_f32 v225, v98, v132, v225
	v_mul_f32_e32 v224, s88, v224
	v_mul_f32_e32 v225, s88, v225
	v_cvt_pk_bf16_f32 v224, v224, v225
	ds_write_b16 v211, v224 offset:288
	ds_write_b16_d16_hi v211, v224 offset:352
	s_waitcnt vmcnt(12)
	v_mul_f32_e32 v224, v99, v135
	v_mul_f32_e32 v225, v115, v135
	v_fma_f32 v224, v115, v134, -v224
	v_fma_f32 v225, v99, v134, v225
	v_mul_f32_e32 v224, s88, v224
	v_mul_f32_e32 v225, s88, v225
	v_cvt_pk_bf16_f32 v224, v224, v225
	ds_write_b16 v211, v224 offset:432
	ds_write_b16_d16_hi v211, v224 offset:496
	s_waitcnt vmcnt(11)
	v_mul_f32_e32 v224, v100, v137
	v_mul_f32_e32 v225, v116, v137
	v_fma_f32 v224, v116, v136, -v224
	v_fma_f32 v225, v100, v136, v225
	v_mul_f32_e32 v224, s88, v224
	v_mul_f32_e32 v225, s88, v225
	v_cvt_pk_bf16_f32 v224, v224, v225
	ds_write_b16 v211, v224 offset:1152
	ds_write_b16_d16_hi v211, v224 offset:1216
	s_waitcnt vmcnt(10)
	v_mul_f32_e32 v224, v101, v139
	v_mul_f32_e32 v225, v117, v139
	v_fma_f32 v224, v117, v138, -v224
	v_fma_f32 v225, v101, v138, v225
	v_mul_f32_e32 v224, s88, v224
	v_mul_f32_e32 v225, s88, v225
	v_cvt_pk_bf16_f32 v224, v224, v225
	ds_write_b16 v211, v224 offset:1296
	ds_write_b16_d16_hi v211, v224 offset:1360
	s_waitcnt vmcnt(9)
	v_mul_f32_e32 v224, v102, v141
	v_mul_f32_e32 v225, v118, v141
	v_fma_f32 v224, v118, v140, -v224
	v_fma_f32 v225, v102, v140, v225
	v_mul_f32_e32 v224, s88, v224
	v_mul_f32_e32 v225, s88, v225
	v_cvt_pk_bf16_f32 v224, v224, v225
	ds_write_b16 v211, v224 offset:1440
	ds_write_b16_d16_hi v211, v224 offset:1504
	s_waitcnt vmcnt(8)
	v_mul_f32_e32 v224, v103, v143
	v_mul_f32_e32 v225, v119, v143
	v_fma_f32 v224, v119, v142, -v224
	v_fma_f32 v225, v103, v142, v225
	v_mul_f32_e32 v224, s88, v224
	v_mul_f32_e32 v225, s88, v225
	v_cvt_pk_bf16_f32 v224, v224, v225
	ds_write_b16 v211, v224 offset:1584
	ds_write_b16_d16_hi v211, v224 offset:1648
	s_waitcnt vmcnt(7)
	v_mul_f32_e32 v224, v104, v145
	v_mul_f32_e32 v225, v120, v145
	v_fma_f32 v224, v120, v144, -v224
	v_fma_f32 v225, v104, v144, v225
	v_mul_f32_e32 v224, s88, v224
	v_mul_f32_e32 v225, s88, v225
	v_cvt_pk_bf16_f32 v224, v224, v225
	ds_write_b16 v211, v224 offset:2304
	ds_write_b16_d16_hi v211, v224 offset:2368
	s_waitcnt vmcnt(6)
	v_mul_f32_e32 v224, v105, v147
	v_mul_f32_e32 v225, v121, v147
	v_fma_f32 v224, v121, v146, -v224
	v_fma_f32 v225, v105, v146, v225
	v_mul_f32_e32 v224, s88, v224
	v_mul_f32_e32 v225, s88, v225
	v_cvt_pk_bf16_f32 v224, v224, v225
	ds_write_b16 v211, v224 offset:2448
	ds_write_b16_d16_hi v211, v224 offset:2512
	s_waitcnt vmcnt(5)
	v_mul_f32_e32 v224, v106, v149
	v_mul_f32_e32 v225, v122, v149
	v_fma_f32 v224, v122, v148, -v224
	v_fma_f32 v225, v106, v148, v225
	v_mul_f32_e32 v224, s88, v224
	v_mul_f32_e32 v225, s88, v225
	v_cvt_pk_bf16_f32 v224, v224, v225
	ds_write_b16 v211, v224 offset:2592
	ds_write_b16_d16_hi v211, v224 offset:2656
	s_waitcnt vmcnt(4)
	v_mul_f32_e32 v224, v107, v151
	v_mul_f32_e32 v225, v123, v151
	v_fma_f32 v224, v123, v150, -v224
	v_fma_f32 v225, v107, v150, v225
	v_mul_f32_e32 v224, s88, v224
	v_mul_f32_e32 v225, s88, v225
	v_cvt_pk_bf16_f32 v224, v224, v225
	ds_write_b16 v211, v224 offset:2736
	ds_write_b16_d16_hi v211, v224 offset:2800
	s_waitcnt vmcnt(3)
	v_mul_f32_e32 v224, v108, v153
	v_mul_f32_e32 v225, v124, v153
	v_fma_f32 v224, v124, v152, -v224
	v_fma_f32 v225, v108, v152, v225
	v_mul_f32_e32 v224, s88, v224
	v_mul_f32_e32 v225, s88, v225
	v_cvt_pk_bf16_f32 v224, v224, v225
	ds_write_b16 v211, v224 offset:3456
	ds_write_b16_d16_hi v211, v224 offset:3520
	s_waitcnt vmcnt(2)
	v_mul_f32_e32 v224, v109, v155
	v_mul_f32_e32 v225, v125, v155
	v_fma_f32 v224, v125, v154, -v224
	v_fma_f32 v225, v109, v154, v225
	v_mul_f32_e32 v224, s88, v224
	v_mul_f32_e32 v225, s88, v225
	v_cvt_pk_bf16_f32 v224, v224, v225
	ds_write_b16 v211, v224 offset:3600
	ds_write_b16_d16_hi v211, v224 offset:3664
	s_waitcnt vmcnt(1)
	v_mul_f32_e32 v224, v110, v157
	v_mul_f32_e32 v225, v126, v157
	v_fma_f32 v224, v126, v156, -v224
	v_fma_f32 v225, v110, v156, v225
	v_mul_f32_e32 v224, s88, v224
	v_mul_f32_e32 v225, s88, v225
	v_cvt_pk_bf16_f32 v224, v224, v225
	ds_write_b16 v211, v224 offset:3744
	ds_write_b16_d16_hi v211, v224 offset:3808
	s_waitcnt vmcnt(0)
	v_mul_f32_e32 v224, v111, v159
	v_mul_f32_e32 v225, v127, v159
	v_fma_f32 v224, v127, v158, -v224
	v_fma_f32 v225, v111, v158, v225
	v_mul_f32_e32 v224, s88, v224
	v_mul_f32_e32 v225, s88, v225
	v_cvt_pk_bf16_f32 v224, v224, v225
	ds_write_b16 v211, v224 offset:3888
	ds_write_b16_d16_hi v211, v224 offset:3952
	s_branch .Lep11_00_st
.Lep11_00_mS:
	v_mul_f32_e32 v224, 0xbfb8aa3b, v112
	v_mul_f32_e32 v225, 0xbfb8aa3b, v96
	v_exp_f32_e32 v224, v224
	v_exp_f32_e32 v225, v225
	v_add_f32_e32 v224, 1.0, v224
	v_add_f32_e32 v225, 1.0, v225
	v_rcp_f32_e32 v224, v224
	v_rcp_f32_e32 v225, v225
	v_mul_f32_e32 v224, v112, v224
	v_mul_f32_e32 v225, v96, v225
	v_cvt_pk_bf16_f32 v224, v224, v225
	ds_write_b16 v211, v224
	ds_write_b16_d16_hi v211, v224 offset:64
	v_mul_f32_e32 v226, 0xbfb8aa3b, v113
	v_mul_f32_e32 v227, 0xbfb8aa3b, v97
	v_exp_f32_e32 v226, v226
	v_exp_f32_e32 v227, v227
	v_add_f32_e32 v226, 1.0, v226
	v_add_f32_e32 v227, 1.0, v227
	v_rcp_f32_e32 v226, v226
	v_rcp_f32_e32 v227, v227
	v_mul_f32_e32 v226, v113, v226
	v_mul_f32_e32 v227, v97, v227
	v_cvt_pk_bf16_f32 v226, v226, v227
	ds_write_b16 v211, v226 offset:144
	ds_write_b16_d16_hi v211, v226 offset:208
	v_mul_f32_e32 v224, 0xbfb8aa3b, v114
	v_mul_f32_e32 v225, 0xbfb8aa3b, v98
	v_exp_f32_e32 v224, v224
	v_exp_f32_e32 v225, v225
	v_add_f32_e32 v224, 1.0, v224
	v_add_f32_e32 v225, 1.0, v225
	v_rcp_f32_e32 v224, v224
	v_rcp_f32_e32 v225, v225
	v_mul_f32_e32 v224, v114, v224
	v_mul_f32_e32 v225, v98, v225
	v_cvt_pk_bf16_f32 v224, v224, v225
	ds_write_b16 v211, v224 offset:288
	ds_write_b16_d16_hi v211, v224 offset:352
	v_mul_f32_e32 v226, 0xbfb8aa3b, v115
	v_mul_f32_e32 v227, 0xbfb8aa3b, v99
	v_exp_f32_e32 v226, v226
	v_exp_f32_e32 v227, v227
	v_add_f32_e32 v226, 1.0, v226
	v_add_f32_e32 v227, 1.0, v227
	v_rcp_f32_e32 v226, v226
	v_rcp_f32_e32 v227, v227
	v_mul_f32_e32 v226, v115, v226
	v_mul_f32_e32 v227, v99, v227
	v_cvt_pk_bf16_f32 v226, v226, v227
	ds_write_b16 v211, v226 offset:432
	ds_write_b16_d16_hi v211, v226 offset:496
	v_mul_f32_e32 v224, 0xbfb8aa3b, v116
	v_mul_f32_e32 v225, 0xbfb8aa3b, v100
	v_exp_f32_e32 v224, v224
	v_exp_f32_e32 v225, v225
	v_add_f32_e32 v224, 1.0, v224
	v_add_f32_e32 v225, 1.0, v225
	v_rcp_f32_e32 v224, v224
	v_rcp_f32_e32 v225, v225
	v_mul_f32_e32 v224, v116, v224
	v_mul_f32_e32 v225, v100, v225
	v_cvt_pk_bf16_f32 v224, v224, v225
	ds_write_b16 v211, v224 offset:1152
	ds_write_b16_d16_hi v211, v224 offset:1216
	v_mul_f32_e32 v226, 0xbfb8aa3b, v117
	v_mul_f32_e32 v227, 0xbfb8aa3b, v101
	v_exp_f32_e32 v226, v226
	v_exp_f32_e32 v227, v227
	v_add_f32_e32 v226, 1.0, v226
	v_add_f32_e32 v227, 1.0, v227
	v_rcp_f32_e32 v226, v226
	v_rcp_f32_e32 v227, v227
	v_mul_f32_e32 v226, v117, v226
	v_mul_f32_e32 v227, v101, v227
	v_cvt_pk_bf16_f32 v226, v226, v227
	ds_write_b16 v211, v226 offset:1296
	ds_write_b16_d16_hi v211, v226 offset:1360
	v_mul_f32_e32 v224, 0xbfb8aa3b, v118
	v_mul_f32_e32 v225, 0xbfb8aa3b, v102
	v_exp_f32_e32 v224, v224
	v_exp_f32_e32 v225, v225
	v_add_f32_e32 v224, 1.0, v224
	v_add_f32_e32 v225, 1.0, v225
	v_rcp_f32_e32 v224, v224
	v_rcp_f32_e32 v225, v225
	v_mul_f32_e32 v224, v118, v224
	v_mul_f32_e32 v225, v102, v225
	v_cvt_pk_bf16_f32 v224, v224, v225
	ds_write_b16 v211, v224 offset:1440
	ds_write_b16_d16_hi v211, v224 offset:1504
	v_mul_f32_e32 v226, 0xbfb8aa3b, v119
	v_mul_f32_e32 v227, 0xbfb8aa3b, v103
	v_exp_f32_e32 v226, v226
	v_exp_f32_e32 v227, v227
	v_add_f32_e32 v226, 1.0, v226
	v_add_f32_e32 v227, 1.0, v227
	v_rcp_f32_e32 v226, v226
	v_rcp_f32_e32 v227, v227
	v_mul_f32_e32 v226, v119, v226
	v_mul_f32_e32 v227, v103, v227
	v_cvt_pk_bf16_f32 v226, v226, v227
	ds_write_b16 v211, v226 offset:1584
	ds_write_b16_d16_hi v211, v226 offset:1648
	v_mul_f32_e32 v224, 0xbfb8aa3b, v120
	v_mul_f32_e32 v225, 0xbfb8aa3b, v104
	v_exp_f32_e32 v224, v224
	v_exp_f32_e32 v225, v225
	v_add_f32_e32 v224, 1.0, v224
	v_add_f32_e32 v225, 1.0, v225
	v_rcp_f32_e32 v224, v224
	v_rcp_f32_e32 v225, v225
	v_mul_f32_e32 v224, v120, v224
	v_mul_f32_e32 v225, v104, v225
	v_cvt_pk_bf16_f32 v224, v224, v225
	ds_write_b16 v211, v224 offset:2304
	ds_write_b16_d16_hi v211, v224 offset:2368
	v_mul_f32_e32 v226, 0xbfb8aa3b, v121
	v_mul_f32_e32 v227, 0xbfb8aa3b, v105
	v_exp_f32_e32 v226, v226
	v_exp_f32_e32 v227, v227
	v_add_f32_e32 v226, 1.0, v226
	v_add_f32_e32 v227, 1.0, v227
	v_rcp_f32_e32 v226, v226
	v_rcp_f32_e32 v227, v227
	v_mul_f32_e32 v226, v121, v226
	v_mul_f32_e32 v227, v105, v227
	v_cvt_pk_bf16_f32 v226, v226, v227
	ds_write_b16 v211, v226 offset:2448
	ds_write_b16_d16_hi v211, v226 offset:2512
	v_mul_f32_e32 v224, 0xbfb8aa3b, v122
	v_mul_f32_e32 v225, 0xbfb8aa3b, v106
	v_exp_f32_e32 v224, v224
	v_exp_f32_e32 v225, v225
	v_add_f32_e32 v224, 1.0, v224
	v_add_f32_e32 v225, 1.0, v225
	v_rcp_f32_e32 v224, v224
	v_rcp_f32_e32 v225, v225
	v_mul_f32_e32 v224, v122, v224
	v_mul_f32_e32 v225, v106, v225
	v_cvt_pk_bf16_f32 v224, v224, v225
	ds_write_b16 v211, v224 offset:2592
	ds_write_b16_d16_hi v211, v224 offset:2656
	v_mul_f32_e32 v226, 0xbfb8aa3b, v123
	v_mul_f32_e32 v227, 0xbfb8aa3b, v107
	v_exp_f32_e32 v226, v226
	v_exp_f32_e32 v227, v227
	v_add_f32_e32 v226, 1.0, v226
	v_add_f32_e32 v227, 1.0, v227
	v_rcp_f32_e32 v226, v226
	v_rcp_f32_e32 v227, v227
	v_mul_f32_e32 v226, v123, v226
	v_mul_f32_e32 v227, v107, v227
	v_cvt_pk_bf16_f32 v226, v226, v227
	ds_write_b16 v211, v226 offset:2736
	ds_write_b16_d16_hi v211, v226 offset:2800
	v_mul_f32_e32 v224, 0xbfb8aa3b, v124
	v_mul_f32_e32 v225, 0xbfb8aa3b, v108
	v_exp_f32_e32 v224, v224
	v_exp_f32_e32 v225, v225
	v_add_f32_e32 v224, 1.0, v224
	v_add_f32_e32 v225, 1.0, v225
	v_rcp_f32_e32 v224, v224
	v_rcp_f32_e32 v225, v225
	v_mul_f32_e32 v224, v124, v224
	v_mul_f32_e32 v225, v108, v225
	v_cvt_pk_bf16_f32 v224, v224, v225
	ds_write_b16 v211, v224 offset:3456
	ds_write_b16_d16_hi v211, v224 offset:3520
	v_mul_f32_e32 v226, 0xbfb8aa3b, v125
	v_mul_f32_e32 v227, 0xbfb8aa3b, v109
	v_exp_f32_e32 v226, v226
	v_exp_f32_e32 v227, v227
	v_add_f32_e32 v226, 1.0, v226
	v_add_f32_e32 v227, 1.0, v227
	v_rcp_f32_e32 v226, v226
	v_rcp_f32_e32 v227, v227
	v_mul_f32_e32 v226, v125, v226
	v_mul_f32_e32 v227, v109, v227
	v_cvt_pk_bf16_f32 v226, v226, v227
	ds_write_b16 v211, v226 offset:3600
	ds_write_b16_d16_hi v211, v226 offset:3664
	v_mul_f32_e32 v224, 0xbfb8aa3b, v126
	v_mul_f32_e32 v225, 0xbfb8aa3b, v110
	v_exp_f32_e32 v224, v224
	v_exp_f32_e32 v225, v225
	v_add_f32_e32 v224, 1.0, v224
	v_add_f32_e32 v225, 1.0, v225
	v_rcp_f32_e32 v224, v224
	v_rcp_f32_e32 v225, v225
	v_mul_f32_e32 v224, v126, v224
	v_mul_f32_e32 v225, v110, v225
	v_cvt_pk_bf16_f32 v224, v224, v225
	ds_write_b16 v211, v224 offset:3744
	ds_write_b16_d16_hi v211, v224 offset:3808
	v_mul_f32_e32 v226, 0xbfb8aa3b, v127
	v_mul_f32_e32 v227, 0xbfb8aa3b, v111
	v_exp_f32_e32 v226, v226
	v_exp_f32_e32 v227, v227
	v_add_f32_e32 v226, 1.0, v226
	v_add_f32_e32 v227, 1.0, v227
	v_rcp_f32_e32 v226, v226
	v_rcp_f32_e32 v227, v227
	v_mul_f32_e32 v226, v127, v226
	v_mul_f32_e32 v227, v111, v227
	v_cvt_pk_bf16_f32 v226, v226, v227
	ds_write_b16 v211, v226 offset:3888
	ds_write_b16_d16_hi v211, v226 offset:3952
	s_branch .Lep11_00_st
.Lep11_00_st:
	v_add_u32_e32 v228, s94, v222
	s_waitcnt lgkmcnt(0)
	ds_read_b128 v[202:205], v220
	ds_read_b128 v[206:209], v220 offset:1152
	ds_read_b128 v[212:215], v220 offset:2304
	ds_read_b128 v[216:219], v220 offset:3456
	s_cmp_eq_u32 s89, 96
	s_cbranch_scc0 .Lep11_00_full
	v_cmp_gt_u32_e32 vcc, 0x60, v223
	s_and_b64 exec, exec, vcc
.Lep11_00_full:
	v_add_u32_e32 v224, 0, v228
	v_mul_lo_u32 v224, v224, s89
	v_add3_u32 v224, v224, v223, s91
	v_add_u32_e32 v225, 8, v228
	v_mul_lo_u32 v225, v225, s89
	v_add3_u32 v225, v225, v223, s91
	v_add_u32_e32 v226, 16, v228
	v_mul_lo_u32 v226, v226, s89
	v_add3_u32 v226, v226, v223, s91
	v_add_u32_e32 v227, 24, v228
	v_mul_lo_u32 v227, v227, s89
	v_add3_u32 v227, v227, v223, s91
	s_waitcnt lgkmcnt(3)
	global_store_dwordx4 v224, v[202:205], s[96:97]
	s_waitcnt lgkmcnt(2)
	global_store_dwordx4 v225, v[206:209], s[96:97]
	s_waitcnt lgkmcnt(1)
	global_store_dwordx4 v226, v[212:215], s[96:97]
	s_waitcnt lgkmcnt(0)
	global_store_dwordx4 v227, v[216:219], s[96:97]
	s_mov_b64 exec, -1

.Lep11_01_mG:
	v_mul_f32_e32 v224, 0xbfb8aa3b, v80
	v_mul_f32_e32 v225, 0xbfb8aa3b, v64
	v_exp_f32_e32 v224, v224
	v_exp_f32_e32 v225, v225
	v_add_f32_e32 v224, 1.0, v224
	v_add_f32_e32 v225, 1.0, v225
	v_rcp_f32_e32 v224, v224
	v_rcp_f32_e32 v225, v225
	s_nop 0
	v_cvt_pk_bf16_f32 v224, v224, v225
	ds_write_b16 v211, v224
	ds_write_b16_d16_hi v211, v224 offset:64
	v_mul_f32_e32 v226, 0xbfb8aa3b, v81
	v_mul_f32_e32 v227, 0xbfb8aa3b, v65
	v_exp_f32_e32 v226, v226
	v_exp_f32_e32 v227, v227
	v_add_f32_e32 v226, 1.0, v226
	v_add_f32_e32 v227, 1.0, v227
	v_rcp_f32_e32 v226, v226
	v_rcp_f32_e32 v227, v227
	s_nop 0
	v_cvt_pk_bf16_f32 v226, v226, v227
	ds_write_b16 v211, v226 offset:144
	ds_write_b16_d16_hi v211, v226 offset:208
	v_mul_f32_e32 v224, 0xbfb8aa3b, v82
	v_mul_f32_e32 v225, 0xbfb8aa3b, v66
	v_exp_f32_e32 v224, v224
	v_exp_f32_e32 v225, v225
	v_add_f32_e32 v224, 1.0, v224
	v_add_f32_e32 v225, 1.0, v225
	v_rcp_f32_e32 v224, v224
	v_rcp_f32_e32 v225, v225
	s_nop 0
	v_cvt_pk_bf16_f32 v224, v224, v225
	ds_write_b16 v211, v224 offset:288
	ds_write_b16_d16_hi v211, v224 offset:352
	v_mul_f32_e32 v226, 0xbfb8aa3b, v83
	v_mul_f32_e32 v227, 0xbfb8aa3b, v67
	v_exp_f32_e32 v226, v226
	v_exp_f32_e32 v227, v227
	v_add_f32_e32 v226, 1.0, v226
	v_add_f32_e32 v227, 1.0, v227
	v_rcp_f32_e32 v226, v226
	v_rcp_f32_e32 v227, v227
	s_nop 0
	v_cvt_pk_bf16_f32 v226, v226, v227
	ds_write_b16 v211, v226 offset:432
	ds_write_b16_d16_hi v211, v226 offset:496
	v_mul_f32_e32 v224, 0xbfb8aa3b, v84
	v_mul_f32_e32 v225, 0xbfb8aa3b, v68
	v_exp_f32_e32 v224, v224
	v_exp_f32_e32 v225, v225
	v_add_f32_e32 v224, 1.0, v224
	v_add_f32_e32 v225, 1.0, v225
	v_rcp_f32_e32 v224, v224
	v_rcp_f32_e32 v225, v225
	s_nop 0
	v_cvt_pk_bf16_f32 v224, v224, v225
	ds_write_b16 v211, v224 offset:1152
	ds_write_b16_d16_hi v211, v224 offset:1216
	v_mul_f32_e32 v226, 0xbfb8aa3b, v85
	v_mul_f32_e32 v227, 0xbfb8aa3b, v69
	v_exp_f32_e32 v226, v226
	v_exp_f32_e32 v227, v227
	v_add_f32_e32 v226, 1.0, v226
	v_add_f32_e32 v227, 1.0, v227
	v_rcp_f32_e32 v226, v226
	v_rcp_f32_e32 v227, v227
	s_nop 0
	v_cvt_pk_bf16_f32 v226, v226, v227
	ds_write_b16 v211, v226 offset:1296
	ds_write_b16_d16_hi v211, v226 offset:1360
	v_mul_f32_e32 v224, 0xbfb8aa3b, v86
	v_mul_f32_e32 v225, 0xbfb8aa3b, v70
	v_exp_f32_e32 v224, v224
	v_exp_f32_e32 v225, v225
	v_add_f32_e32 v224, 1.0, v224
	v_add_f32_e32 v225, 1.0, v225
	v_rcp_f32_e32 v224, v224
	v_rcp_f32_e32 v225, v225
	s_nop 0
	v_cvt_pk_bf16_f32 v224, v224, v225
	ds_write_b16 v211, v224 offset:1440
	ds_write_b16_d16_hi v211, v224 offset:1504
	v_mul_f32_e32 v226, 0xbfb8aa3b, v87
	v_mul_f32_e32 v227, 0xbfb8aa3b, v71
	v_exp_f32_e32 v226, v226
	v_exp_f32_e32 v227, v227
	v_add_f32_e32 v226, 1.0, v226
	v_add_f32_e32 v227, 1.0, v227
	v_rcp_f32_e32 v226, v226
	v_rcp_f32_e32 v227, v227
	s_nop 0
	v_cvt_pk_bf16_f32 v226, v226, v227
	ds_write_b16 v211, v226 offset:1584
	ds_write_b16_d16_hi v211, v226 offset:1648
	v_mul_f32_e32 v224, 0xbfb8aa3b, v88
	v_mul_f32_e32 v225, 0xbfb8aa3b, v72
	v_exp_f32_e32 v224, v224
	v_exp_f32_e32 v225, v225
	v_add_f32_e32 v224, 1.0, v224
	v_add_f32_e32 v225, 1.0, v225
	v_rcp_f32_e32 v224, v224
	v_rcp_f32_e32 v225, v225
	s_nop 0
	v_cvt_pk_bf16_f32 v224, v224, v225
	ds_write_b16 v211, v224 offset:2304
	ds_write_b16_d16_hi v211, v224 offset:2368
	v_mul_f32_e32 v226, 0xbfb8aa3b, v89
	v_mul_f32_e32 v227, 0xbfb8aa3b, v73
	v_exp_f32_e32 v226, v226
	v_exp_f32_e32 v227, v227
	v_add_f32_e32 v226, 1.0, v226
	v_add_f32_e32 v227, 1.0, v227
	v_rcp_f32_e32 v226, v226
	v_rcp_f32_e32 v227, v227
	s_nop 0
	v_cvt_pk_bf16_f32 v226, v226, v227
	ds_write_b16 v211, v226 offset:2448
	ds_write_b16_d16_hi v211, v226 offset:2512
	v_mul_f32_e32 v224, 0xbfb8aa3b, v90
	v_mul_f32_e32 v225, 0xbfb8aa3b, v74
	v_exp_f32_e32 v224, v224
	v_exp_f32_e32 v225, v225
	v_add_f32_e32 v224, 1.0, v224
	v_add_f32_e32 v225, 1.0, v225
	v_rcp_f32_e32 v224, v224
	v_rcp_f32_e32 v225, v225
	s_nop 0
	v_cvt_pk_bf16_f32 v224, v224, v225
	ds_write_b16 v211, v224 offset:2592
	ds_write_b16_d16_hi v211, v224 offset:2656
	v_mul_f32_e32 v226, 0xbfb8aa3b, v91
	v_mul_f32_e32 v227, 0xbfb8aa3b, v75
	v_exp_f32_e32 v226, v226
	v_exp_f32_e32 v227, v227
	v_add_f32_e32 v226, 1.0, v226
	v_add_f32_e32 v227, 1.0, v227
	v_rcp_f32_e32 v226, v226
	v_rcp_f32_e32 v227, v227
	s_nop 0
	v_cvt_pk_bf16_f32 v226, v226, v227
	ds_write_b16 v211, v226 offset:2736
	ds_write_b16_d16_hi v211, v226 offset:2800
	v_mul_f32_e32 v224, 0xbfb8aa3b, v92
	v_mul_f32_e32 v225, 0xbfb8aa3b, v76
	v_exp_f32_e32 v224, v224
	v_exp_f32_e32 v225, v225
	v_add_f32_e32 v224, 1.0, v224
	v_add_f32_e32 v225, 1.0, v225
	v_rcp_f32_e32 v224, v224
	v_rcp_f32_e32 v225, v225
	s_nop 0
	v_cvt_pk_bf16_f32 v224, v224, v225
	ds_write_b16 v211, v224 offset:3456
	ds_write_b16_d16_hi v211, v224 offset:3520
	v_mul_f32_e32 v226, 0xbfb8aa3b, v93
	v_mul_f32_e32 v227, 0xbfb8aa3b, v77
	v_exp_f32_e32 v226, v226
	v_exp_f32_e32 v227, v227
	v_add_f32_e32 v226, 1.0, v226
	v_add_f32_e32 v227, 1.0, v227
	v_rcp_f32_e32 v226, v226
	v_rcp_f32_e32 v227, v227
	s_nop 0
	v_cvt_pk_bf16_f32 v226, v226, v227
	ds_write_b16 v211, v226 offset:3600
	ds_write_b16_d16_hi v211, v226 offset:3664
	v_mul_f32_e32 v224, 0xbfb8aa3b, v94
	v_mul_f32_e32 v225, 0xbfb8aa3b, v78
	v_exp_f32_e32 v224, v224
	v_exp_f32_e32 v225, v225
	v_add_f32_e32 v224, 1.0, v224
	v_add_f32_e32 v225, 1.0, v225
	v_rcp_f32_e32 v224, v224
	v_rcp_f32_e32 v225, v225
	s_nop 0
	v_cvt_pk_bf16_f32 v224, v224, v225
	ds_write_b16 v211, v224 offset:3744
	ds_write_b16_d16_hi v211, v224 offset:3808
	v_mul_f32_e32 v226, 0xbfb8aa3b, v95
	v_mul_f32_e32 v227, 0xbfb8aa3b, v79
	v_exp_f32_e32 v226, v226
	v_exp_f32_e32 v227, v227
	v_add_f32_e32 v226, 1.0, v226
	v_add_f32_e32 v227, 1.0, v227
	v_rcp_f32_e32 v226, v226
	v_rcp_f32_e32 v227, v227
	s_nop 0
	v_cvt_pk_bf16_f32 v226, v226, v227
	ds_write_b16 v211, v226 offset:3888
	ds_write_b16_d16_hi v211, v226 offset:3952
	s_branch .Lep11_01_st
.Lep11_01_mP:
	v_cvt_pk_bf16_f32 v224, v80, v64
	ds_write_b16 v211, v224
	ds_write_b16_d16_hi v211, v224 offset:64
	v_cvt_pk_bf16_f32 v225, v81, v65
	ds_write_b16 v211, v225 offset:144
	ds_write_b16_d16_hi v211, v225 offset:208
	v_cvt_pk_bf16_f32 v226, v82, v66
	ds_write_b16 v211, v226 offset:288
	ds_write_b16_d16_hi v211, v226 offset:352
	v_cvt_pk_bf16_f32 v227, v83, v67
	ds_write_b16 v211, v227 offset:432
	ds_write_b16_d16_hi v211, v227 offset:496
	v_cvt_pk_bf16_f32 v224, v84, v68
	ds_write_b16 v211, v224 offset:1152
	ds_write_b16_d16_hi v211, v224 offset:1216
	v_cvt_pk_bf16_f32 v225, v85, v69
	ds_write_b16 v211, v225 offset:1296
	ds_write_b16_d16_hi v211, v225 offset:1360
	v_cvt_pk_bf16_f32 v226, v86, v70
	ds_write_b16 v211, v226 offset:1440
	ds_write_b16_d16_hi v211, v226 offset:1504
	v_cvt_pk_bf16_f32 v227, v87, v71
	ds_write_b16 v211, v227 offset:1584
	ds_write_b16_d16_hi v211, v227 offset:1648
	v_cvt_pk_bf16_f32 v224, v88, v72
	ds_write_b16 v211, v224 offset:2304
	ds_write_b16_d16_hi v211, v224 offset:2368
	v_cvt_pk_bf16_f32 v225, v89, v73
	ds_write_b16 v211, v225 offset:2448
	ds_write_b16_d16_hi v211, v225 offset:2512
	v_cvt_pk_bf16_f32 v226, v90, v74
	ds_write_b16 v211, v226 offset:2592
	ds_write_b16_d16_hi v211, v226 offset:2656
	v_cvt_pk_bf16_f32 v227, v91, v75
	ds_write_b16 v211, v227 offset:2736
	ds_write_b16_d16_hi v211, v227 offset:2800
	v_cvt_pk_bf16_f32 v224, v92, v76
	ds_write_b16 v211, v224 offset:3456
	ds_write_b16_d16_hi v211, v224 offset:3520
	v_cvt_pk_bf16_f32 v225, v93, v77
	ds_write_b16 v211, v225 offset:3600
	ds_write_b16_d16_hi v211, v225 offset:3664
	v_cvt_pk_bf16_f32 v226, v94, v78
	ds_write_b16 v211, v226 offset:3744
	ds_write_b16_d16_hi v211, v226 offset:3808
	v_cvt_pk_bf16_f32 v227, v95, v79
	ds_write_b16 v211, v227 offset:3888
	ds_write_b16_d16_hi v211, v227 offset:3952
	s_branch .Lep11_01_st
.Lep11_01_mR:
	s_load_dwordx2 s[98:99], s[0:1], 0x148
	v_add_u32_e32 v224, s94, v221
	v_lshlrev_b32_e32 v224, 8, v224
	v_add_u32_e32 v230, v224, v201
	v_mov_b32_e32 v231, 0
	s_waitcnt lgkmcnt(0)
	v_lshl_add_u64 v[230:231], s[98:99], 0, v[230:231]
	global_load_dwordx2 v[128:129], v[230:231], off
	global_load_dwordx2 v[130:131], v[230:231], off offset:256
	global_load_dwordx2 v[132:133], v[230:231], off offset:512
	global_load_dwordx2 v[134:135], v[230:231], off offset:768
	global_load_dwordx2 v[136:137], v[230:231], off offset:2048
	global_load_dwordx2 v[138:139], v[230:231], off offset:2304
	global_load_dwordx2 v[140:141], v[230:231], off offset:2560
	global_load_dwordx2 v[142:143], v[230:231], off offset:2816
	v_add_co_u32_e32 v232, vcc, 0x1000, v230
	s_nop 1
	v_addc_co_u32_e32 v233, vcc, 0, v231, vcc
	global_load_dwordx2 v[144:145], v[232:233], off
	global_load_dwordx2 v[146:147], v[232:233], off offset:256
	global_load_dwordx2 v[148:149], v[232:233], off offset:512
	global_load_dwordx2 v[150:151], v[232:233], off offset:768
	global_load_dwordx2 v[152:153], v[232:233], off offset:2048
	global_load_dwordx2 v[154:155], v[232:233], off offset:2304
	global_load_dwordx2 v[156:157], v[232:233], off offset:2560
	global_load_dwordx2 v[158:159], v[232:233], off offset:2816
	s_waitcnt vmcnt(15)
	v_mul_f32_e32 v224, v64, v129
	v_mul_f32_e32 v225, v80, v129
	v_fma_f32 v224, v80, v128, -v224
	v_fma_f32 v225, v64, v128, v225
	v_mul_f32_e32 v224, s88, v224
	v_mul_f32_e32 v225, s88, v225
	v_cvt_pk_bf16_f32 v224, v224, v225
	ds_write_b16 v211, v224
	ds_write_b16_d16_hi v211, v224 offset:64
	s_waitcnt vmcnt(14)
	v_mul_f32_e32 v224, v65, v131
	v_mul_f32_e32 v225, v81, v131
	v_fma_f32 v224, v81, v130, -v224
	v_fma_f32 v225, v65, v130, v225
	v_mul_f32_e32 v224, s88, v224
	v_mul_f32_e32 v225, s88, v225
	v_cvt_pk_bf16_f32 v224, v224, v225
	ds_write_b16 v211, v224 offset:144
	ds_write_b16_d16_hi v211, v224 offset:208
	s_waitcnt vmcnt(13)
	v_mul_f32_e32 v224, v66, v133
	v_mul_f32_e32 v225, v82, v133
	v_fma_f32 v224, v82, v132, -v224
	v_fma_f32 v225, v66, v132, v225
	v_mul_f32_e32 v224, s88, v224
	v_mul_f32_e32 v225, s88, v225
	v_cvt_pk_bf16_f32 v224, v224, v225
	ds_write_b16 v211, v224 offset:288
	ds_write_b16_d16_hi v211, v224 offset:352
	s_waitcnt vmcnt(12)
	v_mul_f32_e32 v224, v67, v135
	v_mul_f32_e32 v225, v83, v135
	v_fma_f32 v224, v83, v134, -v224
	v_fma_f32 v225, v67, v134, v225
	v_mul_f32_e32 v224, s88, v224
	v_mul_f32_e32 v225, s88, v225
	v_cvt_pk_bf16_f32 v224, v224, v225
	ds_write_b16 v211, v224 offset:432
	ds_write_b16_d16_hi v211, v224 offset:496
	s_waitcnt vmcnt(11)
	v_mul_f32_e32 v224, v68, v137
	v_mul_f32_e32 v225, v84, v137
	v_fma_f32 v224, v84, v136, -v224
	v_fma_f32 v225, v68, v136, v225
	v_mul_f32_e32 v224, s88, v224
	v_mul_f32_e32 v225, s88, v225
	v_cvt_pk_bf16_f32 v224, v224, v225
	ds_write_b16 v211, v224 offset:1152
	ds_write_b16_d16_hi v211, v224 offset:1216
	s_waitcnt vmcnt(10)
	v_mul_f32_e32 v224, v69, v139
	v_mul_f32_e32 v225, v85, v139
	v_fma_f32 v224, v85, v138, -v224
	v_fma_f32 v225, v69, v138, v225
	v_mul_f32_e32 v224, s88, v224
	v_mul_f32_e32 v225, s88, v225
	v_cvt_pk_bf16_f32 v224, v224, v225
	ds_write_b16 v211, v224 offset:1296
	ds_write_b16_d16_hi v211, v224 offset:1360
	s_waitcnt vmcnt(9)
	v_mul_f32_e32 v224, v70, v141
	v_mul_f32_e32 v225, v86, v141
	v_fma_f32 v224, v86, v140, -v224
	v_fma_f32 v225, v70, v140, v225
	v_mul_f32_e32 v224, s88, v224
	v_mul_f32_e32 v225, s88, v225
	v_cvt_pk_bf16_f32 v224, v224, v225
	ds_write_b16 v211, v224 offset:1440
	ds_write_b16_d16_hi v211, v224 offset:1504
	s_waitcnt vmcnt(8)
	v_mul_f32_e32 v224, v71, v143
	v_mul_f32_e32 v225, v87, v143
	v_fma_f32 v224, v87, v142, -v224
	v_fma_f32 v225, v71, v142, v225
	v_mul_f32_e32 v224, s88, v224
	v_mul_f32_e32 v225, s88, v225
	v_cvt_pk_bf16_f32 v224, v224, v225
	ds_write_b16 v211, v224 offset:1584
	ds_write_b16_d16_hi v211, v224 offset:1648
	s_waitcnt vmcnt(7)
	v_mul_f32_e32 v224, v72, v145
	v_mul_f32_e32 v225, v88, v145
	v_fma_f32 v224, v88, v144, -v224
	v_fma_f32 v225, v72, v144, v225
	v_mul_f32_e32 v224, s88, v224
	v_mul_f32_e32 v225, s88, v225
	v_cvt_pk_bf16_f32 v224, v224, v225
	ds_write_b16 v211, v224 offset:2304
	ds_write_b16_d16_hi v211, v224 offset:2368
	s_waitcnt vmcnt(6)
	v_mul_f32_e32 v224, v73, v147
	v_mul_f32_e32 v225, v89, v147
	v_fma_f32 v224, v89, v146, -v224
	v_fma_f32 v225, v73, v146, v225
	v_mul_f32_e32 v224, s88, v224
	v_mul_f32_e32 v225, s88, v225
	v_cvt_pk_bf16_f32 v224, v224, v225
	ds_write_b16 v211, v224 offset:2448
	ds_write_b16_d16_hi v211, v224 offset:2512
	s_waitcnt vmcnt(5)
	v_mul_f32_e32 v224, v74, v149
	v_mul_f32_e32 v225, v90, v149
	v_fma_f32 v224, v90, v148, -v224
	v_fma_f32 v225, v74, v148, v225
	v_mul_f32_e32 v224, s88, v224
	v_mul_f32_e32 v225, s88, v225
	v_cvt_pk_bf16_f32 v224, v224, v225
	ds_write_b16 v211, v224 offset:2592
	ds_write_b16_d16_hi v211, v224 offset:2656
	s_waitcnt vmcnt(4)
	v_mul_f32_e32 v224, v75, v151
	v_mul_f32_e32 v225, v91, v151
	v_fma_f32 v224, v91, v150, -v224
	v_fma_f32 v225, v75, v150, v225
	v_mul_f32_e32 v224, s88, v224
	v_mul_f32_e32 v225, s88, v225
	v_cvt_pk_bf16_f32 v224, v224, v225
	ds_write_b16 v211, v224 offset:2736
	ds_write_b16_d16_hi v211, v224 offset:2800
	s_waitcnt vmcnt(3)
	v_mul_f32_e32 v224, v76, v153
	v_mul_f32_e32 v225, v92, v153
	v_fma_f32 v224, v92, v152, -v224
	v_fma_f32 v225, v76, v152, v225
	v_mul_f32_e32 v224, s88, v224
	v_mul_f32_e32 v225, s88, v225
	v_cvt_pk_bf16_f32 v224, v224, v225
	ds_write_b16 v211, v224 offset:3456
	ds_write_b16_d16_hi v211, v224 offset:3520
	s_waitcnt vmcnt(2)
	v_mul_f32_e32 v224, v77, v155
	v_mul_f32_e32 v225, v93, v155
	v_fma_f32 v224, v93, v154, -v224
	v_fma_f32 v225, v77, v154, v225
	v_mul_f32_e32 v224, s88, v224
	v_mul_f32_e32 v225, s88, v225
	v_cvt_pk_bf16_f32 v224, v224, v225
	ds_write_b16 v211, v224 offset:3600
	ds_write_b16_d16_hi v211, v224 offset:3664
	s_waitcnt vmcnt(1)
	v_mul_f32_e32 v224, v78, v157
	v_mul_f32_e32 v225, v94, v157
	v_fma_f32 v224, v94, v156, -v224
	v_fma_f32 v225, v78, v156, v225
	v_mul_f32_e32 v224, s88, v224
	v_mul_f32_e32 v225, s88, v225
	v_cvt_pk_bf16_f32 v224, v224, v225
	ds_write_b16 v211, v224 offset:3744
	ds_write_b16_d16_hi v211, v224 offset:3808
	s_waitcnt vmcnt(0)
	v_mul_f32_e32 v224, v79, v159
	v_mul_f32_e32 v225, v95, v159
	v_fma_f32 v224, v95, v158, -v224
	v_fma_f32 v225, v79, v158, v225
	v_mul_f32_e32 v224, s88, v224
	v_mul_f32_e32 v225, s88, v225
	v_cvt_pk_bf16_f32 v224, v224, v225
	ds_write_b16 v211, v224 offset:3888
	ds_write_b16_d16_hi v211, v224 offset:3952
	s_branch .Lep11_01_st
.Lep11_01_mS:
	v_mul_f32_e32 v224, 0xbfb8aa3b, v80
	v_mul_f32_e32 v225, 0xbfb8aa3b, v64
	v_exp_f32_e32 v224, v224
	v_exp_f32_e32 v225, v225
	v_add_f32_e32 v224, 1.0, v224
	v_add_f32_e32 v225, 1.0, v225
	v_rcp_f32_e32 v224, v224
	v_rcp_f32_e32 v225, v225
	v_mul_f32_e32 v224, v80, v224
	v_mul_f32_e32 v225, v64, v225
	v_cvt_pk_bf16_f32 v224, v224, v225
	ds_write_b16 v211, v224
	ds_write_b16_d16_hi v211, v224 offset:64
	v_mul_f32_e32 v226, 0xbfb8aa3b, v81
	v_mul_f32_e32 v227, 0xbfb8aa3b, v65
	v_exp_f32_e32 v226, v226
	v_exp_f32_e32 v227, v227
	v_add_f32_e32 v226, 1.0, v226
	v_add_f32_e32 v227, 1.0, v227
	v_rcp_f32_e32 v226, v226
	v_rcp_f32_e32 v227, v227
	v_mul_f32_e32 v226, v81, v226
	v_mul_f32_e32 v227, v65, v227
	v_cvt_pk_bf16_f32 v226, v226, v227
	ds_write_b16 v211, v226 offset:144
	ds_write_b16_d16_hi v211, v226 offset:208
	v_mul_f32_e32 v224, 0xbfb8aa3b, v82
	v_mul_f32_e32 v225, 0xbfb8aa3b, v66
	v_exp_f32_e32 v224, v224
	v_exp_f32_e32 v225, v225
	v_add_f32_e32 v224, 1.0, v224
	v_add_f32_e32 v225, 1.0, v225
	v_rcp_f32_e32 v224, v224
	v_rcp_f32_e32 v225, v225
	v_mul_f32_e32 v224, v82, v224
	v_mul_f32_e32 v225, v66, v225
	v_cvt_pk_bf16_f32 v224, v224, v225
	ds_write_b16 v211, v224 offset:288
	ds_write_b16_d16_hi v211, v224 offset:352
	v_mul_f32_e32 v226, 0xbfb8aa3b, v83
	v_mul_f32_e32 v227, 0xbfb8aa3b, v67
	v_exp_f32_e32 v226, v226
	v_exp_f32_e32 v227, v227
	v_add_f32_e32 v226, 1.0, v226
	v_add_f32_e32 v227, 1.0, v227
	v_rcp_f32_e32 v226, v226
	v_rcp_f32_e32 v227, v227
	v_mul_f32_e32 v226, v83, v226
	v_mul_f32_e32 v227, v67, v227
	v_cvt_pk_bf16_f32 v226, v226, v227
	ds_write_b16 v211, v226 offset:432
	ds_write_b16_d16_hi v211, v226 offset:496
	v_mul_f32_e32 v224, 0xbfb8aa3b, v84
	v_mul_f32_e32 v225, 0xbfb8aa3b, v68
	v_exp_f32_e32 v224, v224
	v_exp_f32_e32 v225, v225
	v_add_f32_e32 v224, 1.0, v224
	v_add_f32_e32 v225, 1.0, v225
	v_rcp_f32_e32 v224, v224
	v_rcp_f32_e32 v225, v225
	v_mul_f32_e32 v224, v84, v224
	v_mul_f32_e32 v225, v68, v225
	v_cvt_pk_bf16_f32 v224, v224, v225
	ds_write_b16 v211, v224 offset:1152
	ds_write_b16_d16_hi v211, v224 offset:1216
	v_mul_f32_e32 v226, 0xbfb8aa3b, v85
	v_mul_f32_e32 v227, 0xbfb8aa3b, v69
	v_exp_f32_e32 v226, v226
	v_exp_f32_e32 v227, v227
	v_add_f32_e32 v226, 1.0, v226
	v_add_f32_e32 v227, 1.0, v227
	v_rcp_f32_e32 v226, v226
	v_rcp_f32_e32 v227, v227
	v_mul_f32_e32 v226, v85, v226
	v_mul_f32_e32 v227, v69, v227
	v_cvt_pk_bf16_f32 v226, v226, v227
	ds_write_b16 v211, v226 offset:1296
	ds_write_b16_d16_hi v211, v226 offset:1360
	v_mul_f32_e32 v224, 0xbfb8aa3b, v86
	v_mul_f32_e32 v225, 0xbfb8aa3b, v70
	v_exp_f32_e32 v224, v224
	v_exp_f32_e32 v225, v225
	v_add_f32_e32 v224, 1.0, v224
	v_add_f32_e32 v225, 1.0, v225
	v_rcp_f32_e32 v224, v224
	v_rcp_f32_e32 v225, v225
	v_mul_f32_e32 v224, v86, v224
	v_mul_f32_e32 v225, v70, v225
	v_cvt_pk_bf16_f32 v224, v224, v225
	ds_write_b16 v211, v224 offset:1440
	ds_write_b16_d16_hi v211, v224 offset:1504
	v_mul_f32_e32 v226, 0xbfb8aa3b, v87
	v_mul_f32_e32 v227, 0xbfb8aa3b, v71
	v_exp_f32_e32 v226, v226
	v_exp_f32_e32 v227, v227
	v_add_f32_e32 v226, 1.0, v226
	v_add_f32_e32 v227, 1.0, v227
	v_rcp_f32_e32 v226, v226
	v_rcp_f32_e32 v227, v227
	v_mul_f32_e32 v226, v87, v226
	v_mul_f32_e32 v227, v71, v227
	v_cvt_pk_bf16_f32 v226, v226, v227
	ds_write_b16 v211, v226 offset:1584
	ds_write_b16_d16_hi v211, v226 offset:1648
	v_mul_f32_e32 v224, 0xbfb8aa3b, v88
	v_mul_f32_e32 v225, 0xbfb8aa3b, v72
	v_exp_f32_e32 v224, v224
	v_exp_f32_e32 v225, v225
	v_add_f32_e32 v224, 1.0, v224
	v_add_f32_e32 v225, 1.0, v225
	v_rcp_f32_e32 v224, v224
	v_rcp_f32_e32 v225, v225
	v_mul_f32_e32 v224, v88, v224
	v_mul_f32_e32 v225, v72, v225
	v_cvt_pk_bf16_f32 v224, v224, v225
	ds_write_b16 v211, v224 offset:2304
	ds_write_b16_d16_hi v211, v224 offset:2368
	v_mul_f32_e32 v226, 0xbfb8aa3b, v89
	v_mul_f32_e32 v227, 0xbfb8aa3b, v73
	v_exp_f32_e32 v226, v226
	v_exp_f32_e32 v227, v227
	v_add_f32_e32 v226, 1.0, v226
	v_add_f32_e32 v227, 1.0, v227
	v_rcp_f32_e32 v226, v226
	v_rcp_f32_e32 v227, v227
	v_mul_f32_e32 v226, v89, v226
	v_mul_f32_e32 v227, v73, v227
	v_cvt_pk_bf16_f32 v226, v226, v227
	ds_write_b16 v211, v226 offset:2448
	ds_write_b16_d16_hi v211, v226 offset:2512
	v_mul_f32_e32 v224, 0xbfb8aa3b, v90
	v_mul_f32_e32 v225, 0xbfb8aa3b, v74
	v_exp_f32_e32 v224, v224
	v_exp_f32_e32 v225, v225
	v_add_f32_e32 v224, 1.0, v224
	v_add_f32_e32 v225, 1.0, v225
	v_rcp_f32_e32 v224, v224
	v_rcp_f32_e32 v225, v225
	v_mul_f32_e32 v224, v90, v224
	v_mul_f32_e32 v225, v74, v225
	v_cvt_pk_bf16_f32 v224, v224, v225
	ds_write_b16 v211, v224 offset:2592
	ds_write_b16_d16_hi v211, v224 offset:2656
	v_mul_f32_e32 v226, 0xbfb8aa3b, v91
	v_mul_f32_e32 v227, 0xbfb8aa3b, v75
	v_exp_f32_e32 v226, v226
	v_exp_f32_e32 v227, v227
	v_add_f32_e32 v226, 1.0, v226
	v_add_f32_e32 v227, 1.0, v227
	v_rcp_f32_e32 v226, v226
	v_rcp_f32_e32 v227, v227
	v_mul_f32_e32 v226, v91, v226
	v_mul_f32_e32 v227, v75, v227
	v_cvt_pk_bf16_f32 v226, v226, v227
	ds_write_b16 v211, v226 offset:2736
	ds_write_b16_d16_hi v211, v226 offset:2800
	v_mul_f32_e32 v224, 0xbfb8aa3b, v92
	v_mul_f32_e32 v225, 0xbfb8aa3b, v76
	v_exp_f32_e32 v224, v224
	v_exp_f32_e32 v225, v225
	v_add_f32_e32 v224, 1.0, v224
	v_add_f32_e32 v225, 1.0, v225
	v_rcp_f32_e32 v224, v224
	v_rcp_f32_e32 v225, v225
	v_mul_f32_e32 v224, v92, v224
	v_mul_f32_e32 v225, v76, v225
	v_cvt_pk_bf16_f32 v224, v224, v225
	ds_write_b16 v211, v224 offset:3456
	ds_write_b16_d16_hi v211, v224 offset:3520
	v_mul_f32_e32 v226, 0xbfb8aa3b, v93
	v_mul_f32_e32 v227, 0xbfb8aa3b, v77
	v_exp_f32_e32 v226, v226
	v_exp_f32_e32 v227, v227
	v_add_f32_e32 v226, 1.0, v226
	v_add_f32_e32 v227, 1.0, v227
	v_rcp_f32_e32 v226, v226
	v_rcp_f32_e32 v227, v227
	v_mul_f32_e32 v226, v93, v226
	v_mul_f32_e32 v227, v77, v227
	v_cvt_pk_bf16_f32 v226, v226, v227
	ds_write_b16 v211, v226 offset:3600
	ds_write_b16_d16_hi v211, v226 offset:3664
	v_mul_f32_e32 v224, 0xbfb8aa3b, v94
	v_mul_f32_e32 v225, 0xbfb8aa3b, v78
	v_exp_f32_e32 v224, v224
	v_exp_f32_e32 v225, v225
	v_add_f32_e32 v224, 1.0, v224
	v_add_f32_e32 v225, 1.0, v225
	v_rcp_f32_e32 v224, v224
	v_rcp_f32_e32 v225, v225
	v_mul_f32_e32 v224, v94, v224
	v_mul_f32_e32 v225, v78, v225
	v_cvt_pk_bf16_f32 v224, v224, v225
	ds_write_b16 v211, v224 offset:3744
	ds_write_b16_d16_hi v211, v224 offset:3808
	v_mul_f32_e32 v226, 0xbfb8aa3b, v95
	v_mul_f32_e32 v227, 0xbfb8aa3b, v79
	v_exp_f32_e32 v226, v226
	v_exp_f32_e32 v227, v227
	v_add_f32_e32 v226, 1.0, v226
	v_add_f32_e32 v227, 1.0, v227
	v_rcp_f32_e32 v226, v226
	v_rcp_f32_e32 v227, v227
	v_mul_f32_e32 v226, v95, v226
	v_mul_f32_e32 v227, v79, v227
	v_cvt_pk_bf16_f32 v226, v226, v227
	ds_write_b16 v211, v226 offset:3888
	ds_write_b16_d16_hi v211, v226 offset:3952
	s_branch .Lep11_01_st

.Lep11_10_mG:
	v_mul_f32_e32 v224, 0xbfb8aa3b, v48
	v_mul_f32_e32 v225, 0xbfb8aa3b, v32
	v_exp_f32_e32 v224, v224
	v_exp_f32_e32 v225, v225
	v_add_f32_e32 v224, 1.0, v224
	v_add_f32_e32 v225, 1.0, v225
	v_rcp_f32_e32 v224, v224
	v_rcp_f32_e32 v225, v225
	s_nop 0
	v_cvt_pk_bf16_f32 v224, v224, v225
	ds_write_b16 v211, v224
	ds_write_b16_d16_hi v211, v224 offset:64
	v_mul_f32_e32 v226, 0xbfb8aa3b, v49
	v_mul_f32_e32 v227, 0xbfb8aa3b, v33
	v_exp_f32_e32 v226, v226
	v_exp_f32_e32 v227, v227
	v_add_f32_e32 v226, 1.0, v226
	v_add_f32_e32 v227, 1.0, v227
	v_rcp_f32_e32 v226, v226
	v_rcp_f32_e32 v227, v227
	s_nop 0
	v_cvt_pk_bf16_f32 v226, v226, v227
	ds_write_b16 v211, v226 offset:144
	ds_write_b16_d16_hi v211, v226 offset:208
	v_mul_f32_e32 v224, 0xbfb8aa3b, v50
	v_mul_f32_e32 v225, 0xbfb8aa3b, v34
	v_exp_f32_e32 v224, v224
	v_exp_f32_e32 v225, v225
	v_add_f32_e32 v224, 1.0, v224
	v_add_f32_e32 v225, 1.0, v225
	v_rcp_f32_e32 v224, v224
	v_rcp_f32_e32 v225, v225
	s_nop 0
	v_cvt_pk_bf16_f32 v224, v224, v225
	ds_write_b16 v211, v224 offset:288
	ds_write_b16_d16_hi v211, v224 offset:352
	v_mul_f32_e32 v226, 0xbfb8aa3b, v51
	v_mul_f32_e32 v227, 0xbfb8aa3b, v35
	v_exp_f32_e32 v226, v226
	v_exp_f32_e32 v227, v227
	v_add_f32_e32 v226, 1.0, v226
	v_add_f32_e32 v227, 1.0, v227
	v_rcp_f32_e32 v226, v226
	v_rcp_f32_e32 v227, v227
	s_nop 0
	v_cvt_pk_bf16_f32 v226, v226, v227
	ds_write_b16 v211, v226 offset:432
	ds_write_b16_d16_hi v211, v226 offset:496
	v_mul_f32_e32 v224, 0xbfb8aa3b, v52
	v_mul_f32_e32 v225, 0xbfb8aa3b, v36
	v_exp_f32_e32 v224, v224
	v_exp_f32_e32 v225, v225
	v_add_f32_e32 v224, 1.0, v224
	v_add_f32_e32 v225, 1.0, v225
	v_rcp_f32_e32 v224, v224
	v_rcp_f32_e32 v225, v225
	s_nop 0
	v_cvt_pk_bf16_f32 v224, v224, v225
	ds_write_b16 v211, v224 offset:1152
	ds_write_b16_d16_hi v211, v224 offset:1216
	v_mul_f32_e32 v226, 0xbfb8aa3b, v53
	v_mul_f32_e32 v227, 0xbfb8aa3b, v37
	v_exp_f32_e32 v226, v226
	v_exp_f32_e32 v227, v227
	v_add_f32_e32 v226, 1.0, v226
	v_add_f32_e32 v227, 1.0, v227
	v_rcp_f32_e32 v226, v226
	v_rcp_f32_e32 v227, v227
	s_nop 0
	v_cvt_pk_bf16_f32 v226, v226, v227
	ds_write_b16 v211, v226 offset:1296
	ds_write_b16_d16_hi v211, v226 offset:1360
	v_mul_f32_e32 v224, 0xbfb8aa3b, v54
	v_mul_f32_e32 v225, 0xbfb8aa3b, v38
	v_exp_f32_e32 v224, v224
	v_exp_f32_e32 v225, v225
	v_add_f32_e32 v224, 1.0, v224
	v_add_f32_e32 v225, 1.0, v225
	v_rcp_f32_e32 v224, v224
	v_rcp_f32_e32 v225, v225
	s_nop 0
	v_cvt_pk_bf16_f32 v224, v224, v225
	ds_write_b16 v211, v224 offset:1440
	ds_write_b16_d16_hi v211, v224 offset:1504
	v_mul_f32_e32 v226, 0xbfb8aa3b, v55
	v_mul_f32_e32 v227, 0xbfb8aa3b, v39
	v_exp_f32_e32 v226, v226
	v_exp_f32_e32 v227, v227
	v_add_f32_e32 v226, 1.0, v226
	v_add_f32_e32 v227, 1.0, v227
	v_rcp_f32_e32 v226, v226
	v_rcp_f32_e32 v227, v227
	s_nop 0
	v_cvt_pk_bf16_f32 v226, v226, v227
	ds_write_b16 v211, v226 offset:1584
	ds_write_b16_d16_hi v211, v226 offset:1648
	v_mul_f32_e32 v224, 0xbfb8aa3b, v56
	v_mul_f32_e32 v225, 0xbfb8aa3b, v40
	v_exp_f32_e32 v224, v224
	v_exp_f32_e32 v225, v225
	v_add_f32_e32 v224, 1.0, v224
	v_add_f32_e32 v225, 1.0, v225
	v_rcp_f32_e32 v224, v224
	v_rcp_f32_e32 v225, v225
	s_nop 0
	v_cvt_pk_bf16_f32 v224, v224, v225
	ds_write_b16 v211, v224 offset:2304
	ds_write_b16_d16_hi v211, v224 offset:2368
	v_mul_f32_e32 v226, 0xbfb8aa3b, v57
	v_mul_f32_e32 v227, 0xbfb8aa3b, v41
	v_exp_f32_e32 v226, v226
	v_exp_f32_e32 v227, v227
	v_add_f32_e32 v226, 1.0, v226
	v_add_f32_e32 v227, 1.0, v227
	v_rcp_f32_e32 v226, v226
	v_rcp_f32_e32 v227, v227
	s_nop 0
	v_cvt_pk_bf16_f32 v226, v226, v227
	ds_write_b16 v211, v226 offset:2448
	ds_write_b16_d16_hi v211, v226 offset:2512
	v_mul_f32_e32 v224, 0xbfb8aa3b, v58
	v_mul_f32_e32 v225, 0xbfb8aa3b, v42
	v_exp_f32_e32 v224, v224
	v_exp_f32_e32 v225, v225
	v_add_f32_e32 v224, 1.0, v224
	v_add_f32_e32 v225, 1.0, v225
	v_rcp_f32_e32 v224, v224
	v_rcp_f32_e32 v225, v225
	s_nop 0
	v_cvt_pk_bf16_f32 v224, v224, v225
	ds_write_b16 v211, v224 offset:2592
	ds_write_b16_d16_hi v211, v224 offset:2656
	v_mul_f32_e32 v226, 0xbfb8aa3b, v59
	v_mul_f32_e32 v227, 0xbfb8aa3b, v43
	v_exp_f32_e32 v226, v226
	v_exp_f32_e32 v227, v227
	v_add_f32_e32 v226, 1.0, v226
	v_add_f32_e32 v227, 1.0, v227
	v_rcp_f32_e32 v226, v226
	v_rcp_f32_e32 v227, v227
	s_nop 0
	v_cvt_pk_bf16_f32 v226, v226, v227
	ds_write_b16 v211, v226 offset:2736
	ds_write_b16_d16_hi v211, v226 offset:2800
	v_mul_f32_e32 v224, 0xbfb8aa3b, v60
	v_mul_f32_e32 v225, 0xbfb8aa3b, v44
	v_exp_f32_e32 v224, v224
	v_exp_f32_e32 v225, v225
	v_add_f32_e32 v224, 1.0, v224
	v_add_f32_e32 v225, 1.0, v225
	v_rcp_f32_e32 v224, v224
	v_rcp_f32_e32 v225, v225
	s_nop 0
	v_cvt_pk_bf16_f32 v224, v224, v225
	ds_write_b16 v211, v224 offset:3456
	ds_write_b16_d16_hi v211, v224 offset:3520
	v_mul_f32_e32 v226, 0xbfb8aa3b, v61
	v_mul_f32_e32 v227, 0xbfb8aa3b, v45
	v_exp_f32_e32 v226, v226
	v_exp_f32_e32 v227, v227
	v_add_f32_e32 v226, 1.0, v226
	v_add_f32_e32 v227, 1.0, v227
	v_rcp_f32_e32 v226, v226
	v_rcp_f32_e32 v227, v227
	s_nop 0
	v_cvt_pk_bf16_f32 v226, v226, v227
	ds_write_b16 v211, v226 offset:3600
	ds_write_b16_d16_hi v211, v226 offset:3664
	v_mul_f32_e32 v224, 0xbfb8aa3b, v62
	v_mul_f32_e32 v225, 0xbfb8aa3b, v46
	v_exp_f32_e32 v224, v224
	v_exp_f32_e32 v225, v225
	v_add_f32_e32 v224, 1.0, v224
	v_add_f32_e32 v225, 1.0, v225
	v_rcp_f32_e32 v224, v224
	v_rcp_f32_e32 v225, v225
	s_nop 0
	v_cvt_pk_bf16_f32 v224, v224, v225
	ds_write_b16 v211, v224 offset:3744
	ds_write_b16_d16_hi v211, v224 offset:3808
	v_mul_f32_e32 v226, 0xbfb8aa3b, v63
	v_mul_f32_e32 v227, 0xbfb8aa3b, v47
	v_exp_f32_e32 v226, v226
	v_exp_f32_e32 v227, v227
	v_add_f32_e32 v226, 1.0, v226
	v_add_f32_e32 v227, 1.0, v227
	v_rcp_f32_e32 v226, v226
	v_rcp_f32_e32 v227, v227
	s_nop 0
	v_cvt_pk_bf16_f32 v226, v226, v227
	ds_write_b16 v211, v226 offset:3888
	ds_write_b16_d16_hi v211, v226 offset:3952
	s_branch .Lep11_10_st
.Lep11_10_mP:
	v_cvt_pk_bf16_f32 v224, v48, v32
	ds_write_b16 v211, v224
	ds_write_b16_d16_hi v211, v224 offset:64
	v_cvt_pk_bf16_f32 v225, v49, v33
	ds_write_b16 v211, v225 offset:144
	ds_write_b16_d16_hi v211, v225 offset:208
	v_cvt_pk_bf16_f32 v226, v50, v34
	ds_write_b16 v211, v226 offset:288
	ds_write_b16_d16_hi v211, v226 offset:352
	v_cvt_pk_bf16_f32 v227, v51, v35
	ds_write_b16 v211, v227 offset:432
	ds_write_b16_d16_hi v211, v227 offset:496
	v_cvt_pk_bf16_f32 v224, v52, v36
	ds_write_b16 v211, v224 offset:1152
	ds_write_b16_d16_hi v211, v224 offset:1216
	v_cvt_pk_bf16_f32 v225, v53, v37
	ds_write_b16 v211, v225 offset:1296
	ds_write_b16_d16_hi v211, v225 offset:1360
	v_cvt_pk_bf16_f32 v226, v54, v38
	ds_write_b16 v211, v226 offset:1440
	ds_write_b16_d16_hi v211, v226 offset:1504
	v_cvt_pk_bf16_f32 v227, v55, v39
	ds_write_b16 v211, v227 offset:1584
	ds_write_b16_d16_hi v211, v227 offset:1648
	v_cvt_pk_bf16_f32 v224, v56, v40
	ds_write_b16 v211, v224 offset:2304
	ds_write_b16_d16_hi v211, v224 offset:2368
	v_cvt_pk_bf16_f32 v225, v57, v41
	ds_write_b16 v211, v225 offset:2448
	ds_write_b16_d16_hi v211, v225 offset:2512
	v_cvt_pk_bf16_f32 v226, v58, v42
	ds_write_b16 v211, v226 offset:2592
	ds_write_b16_d16_hi v211, v226 offset:2656
	v_cvt_pk_bf16_f32 v227, v59, v43
	ds_write_b16 v211, v227 offset:2736
	ds_write_b16_d16_hi v211, v227 offset:2800
	v_cvt_pk_bf16_f32 v224, v60, v44
	ds_write_b16 v211, v224 offset:3456
	ds_write_b16_d16_hi v211, v224 offset:3520
	v_cvt_pk_bf16_f32 v225, v61, v45
	ds_write_b16 v211, v225 offset:3600
	ds_write_b16_d16_hi v211, v225 offset:3664
	v_cvt_pk_bf16_f32 v226, v62, v46
	ds_write_b16 v211, v226 offset:3744
	ds_write_b16_d16_hi v211, v226 offset:3808
	v_cvt_pk_bf16_f32 v227, v63, v47
	ds_write_b16 v211, v227 offset:3888
	ds_write_b16_d16_hi v211, v227 offset:3952
	s_branch .Lep11_10_st
.Lep11_10_mR:
	s_load_dwordx2 s[98:99], s[0:1], 0x148
	v_add_u32_e32 v224, s94, v221
	v_lshlrev_b32_e32 v224, 8, v224
	v_add_u32_e32 v230, v224, v201
	v_mov_b32_e32 v231, 0
	s_waitcnt lgkmcnt(0)
	v_lshl_add_u64 v[230:231], s[98:99], 0, v[230:231]
	global_load_dwordx2 v[128:129], v[230:231], off
	global_load_dwordx2 v[130:131], v[230:231], off offset:256
	global_load_dwordx2 v[132:133], v[230:231], off offset:512
	global_load_dwordx2 v[134:135], v[230:231], off offset:768
	global_load_dwordx2 v[136:137], v[230:231], off offset:2048
	global_load_dwordx2 v[138:139], v[230:231], off offset:2304
	global_load_dwordx2 v[140:141], v[230:231], off offset:2560
	global_load_dwordx2 v[142:143], v[230:231], off offset:2816
	v_add_co_u32_e32 v232, vcc, 0x1000, v230
	s_nop 1
	v_addc_co_u32_e32 v233, vcc, 0, v231, vcc
	global_load_dwordx2 v[144:145], v[232:233], off
	global_load_dwordx2 v[146:147], v[232:233], off offset:256
	global_load_dwordx2 v[148:149], v[232:233], off offset:512
	global_load_dwordx2 v[150:151], v[232:233], off offset:768
	global_load_dwordx2 v[152:153], v[232:233], off offset:2048
	global_load_dwordx2 v[154:155], v[232:233], off offset:2304
	global_load_dwordx2 v[156:157], v[232:233], off offset:2560
	global_load_dwordx2 v[158:159], v[232:233], off offset:2816
	s_waitcnt vmcnt(15)
	v_mul_f32_e32 v224, v32, v129
	v_mul_f32_e32 v225, v48, v129
	v_fma_f32 v224, v48, v128, -v224
	v_fma_f32 v225, v32, v128, v225
	v_mul_f32_e32 v224, s88, v224
	v_mul_f32_e32 v225, s88, v225
	v_cvt_pk_bf16_f32 v224, v224, v225
	ds_write_b16 v211, v224
	ds_write_b16_d16_hi v211, v224 offset:64
	s_waitcnt vmcnt(14)
	v_mul_f32_e32 v224, v33, v131
	v_mul_f32_e32 v225, v49, v131
	v_fma_f32 v224, v49, v130, -v224
	v_fma_f32 v225, v33, v130, v225
	v_mul_f32_e32 v224, s88, v224
	v_mul_f32_e32 v225, s88, v225
	v_cvt_pk_bf16_f32 v224, v224, v225
	ds_write_b16 v211, v224 offset:144
	ds_write_b16_d16_hi v211, v224 offset:208
	s_waitcnt vmcnt(13)
	v_mul_f32_e32 v224, v34, v133
	v_mul_f32_e32 v225, v50, v133
	v_fma_f32 v224, v50, v132, -v224
	v_fma_f32 v225, v34, v132, v225
	v_mul_f32_e32 v224, s88, v224
	v_mul_f32_e32 v225, s88, v225
	v_cvt_pk_bf16_f32 v224, v224, v225
	ds_write_b16 v211, v224 offset:288
	ds_write_b16_d16_hi v211, v224 offset:352
	s_waitcnt vmcnt(12)
	v_mul_f32_e32 v224, v35, v135
	v_mul_f32_e32 v225, v51, v135
	v_fma_f32 v224, v51, v134, -v224
	v_fma_f32 v225, v35, v134, v225
	v_mul_f32_e32 v224, s88, v224
	v_mul_f32_e32 v225, s88, v225
	v_cvt_pk_bf16_f32 v224, v224, v225
	ds_write_b16 v211, v224 offset:432
	ds_write_b16_d16_hi v211, v224 offset:496
	s_waitcnt vmcnt(11)
	v_mul_f32_e32 v224, v36, v137
	v_mul_f32_e32 v225, v52, v137
	v_fma_f32 v224, v52, v136, -v224
	v_fma_f32 v225, v36, v136, v225
	v_mul_f32_e32 v224, s88, v224
	v_mul_f32_e32 v225, s88, v225
	v_cvt_pk_bf16_f32 v224, v224, v225
	ds_write_b16 v211, v224 offset:1152
	ds_write_b16_d16_hi v211, v224 offset:1216
	s_waitcnt vmcnt(10)
	v_mul_f32_e32 v224, v37, v139
	v_mul_f32_e32 v225, v53, v139
	v_fma_f32 v224, v53, v138, -v224
	v_fma_f32 v225, v37, v138, v225
	v_mul_f32_e32 v224, s88, v224
	v_mul_f32_e32 v225, s88, v225
	v_cvt_pk_bf16_f32 v224, v224, v225
	ds_write_b16 v211, v224 offset:1296
	ds_write_b16_d16_hi v211, v224 offset:1360
	s_waitcnt vmcnt(9)
	v_mul_f32_e32 v224, v38, v141
	v_mul_f32_e32 v225, v54, v141
	v_fma_f32 v224, v54, v140, -v224
	v_fma_f32 v225, v38, v140, v225
	v_mul_f32_e32 v224, s88, v224
	v_mul_f32_e32 v225, s88, v225
	v_cvt_pk_bf16_f32 v224, v224, v225
	ds_write_b16 v211, v224 offset:1440
	ds_write_b16_d16_hi v211, v224 offset:1504
	s_waitcnt vmcnt(8)
	v_mul_f32_e32 v224, v39, v143
	v_mul_f32_e32 v225, v55, v143
	v_fma_f32 v224, v55, v142, -v224
	v_fma_f32 v225, v39, v142, v225
	v_mul_f32_e32 v224, s88, v224
	v_mul_f32_e32 v225, s88, v225
	v_cvt_pk_bf16_f32 v224, v224, v225
	ds_write_b16 v211, v224 offset:1584
	ds_write_b16_d16_hi v211, v224 offset:1648
	s_waitcnt vmcnt(7)
	v_mul_f32_e32 v224, v40, v145
	v_mul_f32_e32 v225, v56, v145
	v_fma_f32 v224, v56, v144, -v224
	v_fma_f32 v225, v40, v144, v225
	v_mul_f32_e32 v224, s88, v224
	v_mul_f32_e32 v225, s88, v225
	v_cvt_pk_bf16_f32 v224, v224, v225
	ds_write_b16 v211, v224 offset:2304
	ds_write_b16_d16_hi v211, v224 offset:2368
	s_waitcnt vmcnt(6)
	v_mul_f32_e32 v224, v41, v147
	v_mul_f32_e32 v225, v57, v147
	v_fma_f32 v224, v57, v146, -v224
	v_fma_f32 v225, v41, v146, v225
	v_mul_f32_e32 v224, s88, v224
	v_mul_f32_e32 v225, s88, v225
	v_cvt_pk_bf16_f32 v224, v224, v225
	ds_write_b16 v211, v224 offset:2448
	ds_write_b16_d16_hi v211, v224 offset:2512
	s_waitcnt vmcnt(5)
	v_mul_f32_e32 v224, v42, v149
	v_mul_f32_e32 v225, v58, v149
	v_fma_f32 v224, v58, v148, -v224
	v_fma_f32 v225, v42, v148, v225
	v_mul_f32_e32 v224, s88, v224
	v_mul_f32_e32 v225, s88, v225
	v_cvt_pk_bf16_f32 v224, v224, v225
	ds_write_b16 v211, v224 offset:2592
	ds_write_b16_d16_hi v211, v224 offset:2656
	s_waitcnt vmcnt(4)
	v_mul_f32_e32 v224, v43, v151
	v_mul_f32_e32 v225, v59, v151
	v_fma_f32 v224, v59, v150, -v224
	v_fma_f32 v225, v43, v150, v225
	v_mul_f32_e32 v224, s88, v224
	v_mul_f32_e32 v225, s88, v225
	v_cvt_pk_bf16_f32 v224, v224, v225
	ds_write_b16 v211, v224 offset:2736
	ds_write_b16_d16_hi v211, v224 offset:2800
	s_waitcnt vmcnt(3)
	v_mul_f32_e32 v224, v44, v153
	v_mul_f32_e32 v225, v60, v153
	v_fma_f32 v224, v60, v152, -v224
	v_fma_f32 v225, v44, v152, v225
	v_mul_f32_e32 v224, s88, v224
	v_mul_f32_e32 v225, s88, v225
	v_cvt_pk_bf16_f32 v224, v224, v225
	ds_write_b16 v211, v224 offset:3456
	ds_write_b16_d16_hi v211, v224 offset:3520
	s_waitcnt vmcnt(2)
	v_mul_f32_e32 v224, v45, v155
	v_mul_f32_e32 v225, v61, v155
	v_fma_f32 v224, v61, v154, -v224
	v_fma_f32 v225, v45, v154, v225
	v_mul_f32_e32 v224, s88, v224
	v_mul_f32_e32 v225, s88, v225
	v_cvt_pk_bf16_f32 v224, v224, v225
	ds_write_b16 v211, v224 offset:3600
	ds_write_b16_d16_hi v211, v224 offset:3664
	s_waitcnt vmcnt(1)
	v_mul_f32_e32 v224, v46, v157
	v_mul_f32_e32 v225, v62, v157
	v_fma_f32 v224, v62, v156, -v224
	v_fma_f32 v225, v46, v156, v225
	v_mul_f32_e32 v224, s88, v224
	v_mul_f32_e32 v225, s88, v225
	v_cvt_pk_bf16_f32 v224, v224, v225
	ds_write_b16 v211, v224 offset:3744
	ds_write_b16_d16_hi v211, v224 offset:3808
	s_waitcnt vmcnt(0)
	v_mul_f32_e32 v224, v47, v159
	v_mul_f32_e32 v225, v63, v159
	v_fma_f32 v224, v63, v158, -v224
	v_fma_f32 v225, v47, v158, v225
	v_mul_f32_e32 v224, s88, v224
	v_mul_f32_e32 v225, s88, v225
	v_cvt_pk_bf16_f32 v224, v224, v225
	ds_write_b16 v211, v224 offset:3888
	ds_write_b16_d16_hi v211, v224 offset:3952
	s_branch .Lep11_10_st
.Lep11_10_mS:
	v_mul_f32_e32 v224, 0xbfb8aa3b, v48
	v_mul_f32_e32 v225, 0xbfb8aa3b, v32
	v_exp_f32_e32 v224, v224
	v_exp_f32_e32 v225, v225
	v_add_f32_e32 v224, 1.0, v224
	v_add_f32_e32 v225, 1.0, v225
	v_rcp_f32_e32 v224, v224
	v_rcp_f32_e32 v225, v225
	v_mul_f32_e32 v224, v48, v224
	v_mul_f32_e32 v225, v32, v225
	v_cvt_pk_bf16_f32 v224, v224, v225
	ds_write_b16 v211, v224
	ds_write_b16_d16_hi v211, v224 offset:64
	v_mul_f32_e32 v226, 0xbfb8aa3b, v49
	v_mul_f32_e32 v227, 0xbfb8aa3b, v33
	v_exp_f32_e32 v226, v226
	v_exp_f32_e32 v227, v227
	v_add_f32_e32 v226, 1.0, v226
	v_add_f32_e32 v227, 1.0, v227
	v_rcp_f32_e32 v226, v226
	v_rcp_f32_e32 v227, v227
	v_mul_f32_e32 v226, v49, v226
	v_mul_f32_e32 v227, v33, v227
	v_cvt_pk_bf16_f32 v226, v226, v227
	ds_write_b16 v211, v226 offset:144
	ds_write_b16_d16_hi v211, v226 offset:208
	v_mul_f32_e32 v224, 0xbfb8aa3b, v50
	v_mul_f32_e32 v225, 0xbfb8aa3b, v34
	v_exp_f32_e32 v224, v224
	v_exp_f32_e32 v225, v225
	v_add_f32_e32 v224, 1.0, v224
	v_add_f32_e32 v225, 1.0, v225
	v_rcp_f32_e32 v224, v224
	v_rcp_f32_e32 v225, v225
	v_mul_f32_e32 v224, v50, v224
	v_mul_f32_e32 v225, v34, v225
	v_cvt_pk_bf16_f32 v224, v224, v225
	ds_write_b16 v211, v224 offset:288
	ds_write_b16_d16_hi v211, v224 offset:352
	v_mul_f32_e32 v226, 0xbfb8aa3b, v51
	v_mul_f32_e32 v227, 0xbfb8aa3b, v35
	v_exp_f32_e32 v226, v226
	v_exp_f32_e32 v227, v227
	v_add_f32_e32 v226, 1.0, v226
	v_add_f32_e32 v227, 1.0, v227
	v_rcp_f32_e32 v226, v226
	v_rcp_f32_e32 v227, v227
	v_mul_f32_e32 v226, v51, v226
	v_mul_f32_e32 v227, v35, v227
	v_cvt_pk_bf16_f32 v226, v226, v227
	ds_write_b16 v211, v226 offset:432
	ds_write_b16_d16_hi v211, v226 offset:496
	v_mul_f32_e32 v224, 0xbfb8aa3b, v52
	v_mul_f32_e32 v225, 0xbfb8aa3b, v36
	v_exp_f32_e32 v224, v224
	v_exp_f32_e32 v225, v225
	v_add_f32_e32 v224, 1.0, v224
	v_add_f32_e32 v225, 1.0, v225
	v_rcp_f32_e32 v224, v224
	v_rcp_f32_e32 v225, v225
	v_mul_f32_e32 v224, v52, v224
	v_mul_f32_e32 v225, v36, v225
	v_cvt_pk_bf16_f32 v224, v224, v225
	ds_write_b16 v211, v224 offset:1152
	ds_write_b16_d16_hi v211, v224 offset:1216
	v_mul_f32_e32 v226, 0xbfb8aa3b, v53
	v_mul_f32_e32 v227, 0xbfb8aa3b, v37
	v_exp_f32_e32 v226, v226
	v_exp_f32_e32 v227, v227
	v_add_f32_e32 v226, 1.0, v226
	v_add_f32_e32 v227, 1.0, v227
	v_rcp_f32_e32 v226, v226
	v_rcp_f32_e32 v227, v227
	v_mul_f32_e32 v226, v53, v226
	v_mul_f32_e32 v227, v37, v227
	v_cvt_pk_bf16_f32 v226, v226, v227
	ds_write_b16 v211, v226 offset:1296
	ds_write_b16_d16_hi v211, v226 offset:1360
	v_mul_f32_e32 v224, 0xbfb8aa3b, v54
	v_mul_f32_e32 v225, 0xbfb8aa3b, v38
	v_exp_f32_e32 v224, v224
	v_exp_f32_e32 v225, v225
	v_add_f32_e32 v224, 1.0, v224
	v_add_f32_e32 v225, 1.0, v225
	v_rcp_f32_e32 v224, v224
	v_rcp_f32_e32 v225, v225
	v_mul_f32_e32 v224, v54, v224
	v_mul_f32_e32 v225, v38, v225
	v_cvt_pk_bf16_f32 v224, v224, v225
	ds_write_b16 v211, v224 offset:1440
	ds_write_b16_d16_hi v211, v224 offset:1504
	v_mul_f32_e32 v226, 0xbfb8aa3b, v55
	v_mul_f32_e32 v227, 0xbfb8aa3b, v39
	v_exp_f32_e32 v226, v226
	v_exp_f32_e32 v227, v227
	v_add_f32_e32 v226, 1.0, v226
	v_add_f32_e32 v227, 1.0, v227
	v_rcp_f32_e32 v226, v226
	v_rcp_f32_e32 v227, v227
	v_mul_f32_e32 v226, v55, v226
	v_mul_f32_e32 v227, v39, v227
	v_cvt_pk_bf16_f32 v226, v226, v227
	ds_write_b16 v211, v226 offset:1584
	ds_write_b16_d16_hi v211, v226 offset:1648
	v_mul_f32_e32 v224, 0xbfb8aa3b, v56
	v_mul_f32_e32 v225, 0xbfb8aa3b, v40
	v_exp_f32_e32 v224, v224
	v_exp_f32_e32 v225, v225
	v_add_f32_e32 v224, 1.0, v224
	v_add_f32_e32 v225, 1.0, v225
	v_rcp_f32_e32 v224, v224
	v_rcp_f32_e32 v225, v225
	v_mul_f32_e32 v224, v56, v224
	v_mul_f32_e32 v225, v40, v225
	v_cvt_pk_bf16_f32 v224, v224, v225
	ds_write_b16 v211, v224 offset:2304
	ds_write_b16_d16_hi v211, v224 offset:2368
	v_mul_f32_e32 v226, 0xbfb8aa3b, v57
	v_mul_f32_e32 v227, 0xbfb8aa3b, v41
	v_exp_f32_e32 v226, v226
	v_exp_f32_e32 v227, v227
	v_add_f32_e32 v226, 1.0, v226
	v_add_f32_e32 v227, 1.0, v227
	v_rcp_f32_e32 v226, v226
	v_rcp_f32_e32 v227, v227
	v_mul_f32_e32 v226, v57, v226
	v_mul_f32_e32 v227, v41, v227
	v_cvt_pk_bf16_f32 v226, v226, v227
	ds_write_b16 v211, v226 offset:2448
	ds_write_b16_d16_hi v211, v226 offset:2512
	v_mul_f32_e32 v224, 0xbfb8aa3b, v58
	v_mul_f32_e32 v225, 0xbfb8aa3b, v42
	v_exp_f32_e32 v224, v224
	v_exp_f32_e32 v225, v225
	v_add_f32_e32 v224, 1.0, v224
	v_add_f32_e32 v225, 1.0, v225
	v_rcp_f32_e32 v224, v224
	v_rcp_f32_e32 v225, v225
	v_mul_f32_e32 v224, v58, v224
	v_mul_f32_e32 v225, v42, v225
	v_cvt_pk_bf16_f32 v224, v224, v225
	ds_write_b16 v211, v224 offset:2592
	ds_write_b16_d16_hi v211, v224 offset:2656
	v_mul_f32_e32 v226, 0xbfb8aa3b, v59
	v_mul_f32_e32 v227, 0xbfb8aa3b, v43
	v_exp_f32_e32 v226, v226
	v_exp_f32_e32 v227, v227
	v_add_f32_e32 v226, 1.0, v226
	v_add_f32_e32 v227, 1.0, v227
	v_rcp_f32_e32 v226, v226
	v_rcp_f32_e32 v227, v227
	v_mul_f32_e32 v226, v59, v226
	v_mul_f32_e32 v227, v43, v227
	v_cvt_pk_bf16_f32 v226, v226, v227
	ds_write_b16 v211, v226 offset:2736
	ds_write_b16_d16_hi v211, v226 offset:2800
	v_mul_f32_e32 v224, 0xbfb8aa3b, v60
	v_mul_f32_e32 v225, 0xbfb8aa3b, v44
	v_exp_f32_e32 v224, v224
	v_exp_f32_e32 v225, v225
	v_add_f32_e32 v224, 1.0, v224
	v_add_f32_e32 v225, 1.0, v225
	v_rcp_f32_e32 v224, v224
	v_rcp_f32_e32 v225, v225
	v_mul_f32_e32 v224, v60, v224
	v_mul_f32_e32 v225, v44, v225
	v_cvt_pk_bf16_f32 v224, v224, v225
	ds_write_b16 v211, v224 offset:3456
	ds_write_b16_d16_hi v211, v224 offset:3520
	v_mul_f32_e32 v226, 0xbfb8aa3b, v61
	v_mul_f32_e32 v227, 0xbfb8aa3b, v45
	v_exp_f32_e32 v226, v226
	v_exp_f32_e32 v227, v227
	v_add_f32_e32 v226, 1.0, v226
	v_add_f32_e32 v227, 1.0, v227
	v_rcp_f32_e32 v226, v226
	v_rcp_f32_e32 v227, v227
	v_mul_f32_e32 v226, v61, v226
	v_mul_f32_e32 v227, v45, v227
	v_cvt_pk_bf16_f32 v226, v226, v227
	ds_write_b16 v211, v226 offset:3600
	ds_write_b16_d16_hi v211, v226 offset:3664
	v_mul_f32_e32 v224, 0xbfb8aa3b, v62
	v_mul_f32_e32 v225, 0xbfb8aa3b, v46
	v_exp_f32_e32 v224, v224
	v_exp_f32_e32 v225, v225
	v_add_f32_e32 v224, 1.0, v224
	v_add_f32_e32 v225, 1.0, v225
	v_rcp_f32_e32 v224, v224
	v_rcp_f32_e32 v225, v225
	v_mul_f32_e32 v224, v62, v224
	v_mul_f32_e32 v225, v46, v225
	v_cvt_pk_bf16_f32 v224, v224, v225
	ds_write_b16 v211, v224 offset:3744
	ds_write_b16_d16_hi v211, v224 offset:3808
	v_mul_f32_e32 v226, 0xbfb8aa3b, v63
	v_mul_f32_e32 v227, 0xbfb8aa3b, v47
	v_exp_f32_e32 v226, v226
	v_exp_f32_e32 v227, v227
	v_add_f32_e32 v226, 1.0, v226
	v_add_f32_e32 v227, 1.0, v227
	v_rcp_f32_e32 v226, v226
	v_rcp_f32_e32 v227, v227
	v_mul_f32_e32 v226, v63, v226
	v_mul_f32_e32 v227, v47, v227
	v_cvt_pk_bf16_f32 v226, v226, v227
	ds_write_b16 v211, v226 offset:3888
	ds_write_b16_d16_hi v211, v226 offset:3952
	s_branch .Lep11_10_st

.Lep11_11_mG:
	v_mul_f32_e32 v224, 0xbfb8aa3b, v16
	v_mul_f32_e32 v225, 0xbfb8aa3b, v0
	v_exp_f32_e32 v224, v224
	v_exp_f32_e32 v225, v225
	v_add_f32_e32 v224, 1.0, v224
	v_add_f32_e32 v225, 1.0, v225
	v_rcp_f32_e32 v224, v224
	v_rcp_f32_e32 v225, v225
	s_nop 0
	v_cvt_pk_bf16_f32 v224, v224, v225
	ds_write_b16 v211, v224
	ds_write_b16_d16_hi v211, v224 offset:64
	v_mul_f32_e32 v226, 0xbfb8aa3b, v17
	v_mul_f32_e32 v227, 0xbfb8aa3b, v1
	v_exp_f32_e32 v226, v226
	v_exp_f32_e32 v227, v227
	v_add_f32_e32 v226, 1.0, v226
	v_add_f32_e32 v227, 1.0, v227
	v_rcp_f32_e32 v226, v226
	v_rcp_f32_e32 v227, v227
	s_nop 0
	v_cvt_pk_bf16_f32 v226, v226, v227
	ds_write_b16 v211, v226 offset:144
	ds_write_b16_d16_hi v211, v226 offset:208
	v_mul_f32_e32 v224, 0xbfb8aa3b, v18
	v_mul_f32_e32 v225, 0xbfb8aa3b, v2
	v_exp_f32_e32 v224, v224
	v_exp_f32_e32 v225, v225
	v_add_f32_e32 v224, 1.0, v224
	v_add_f32_e32 v225, 1.0, v225
	v_rcp_f32_e32 v224, v224
	v_rcp_f32_e32 v225, v225
	s_nop 0
	v_cvt_pk_bf16_f32 v224, v224, v225
	ds_write_b16 v211, v224 offset:288
	ds_write_b16_d16_hi v211, v224 offset:352
	v_mul_f32_e32 v226, 0xbfb8aa3b, v19
	v_mul_f32_e32 v227, 0xbfb8aa3b, v3
	v_exp_f32_e32 v226, v226
	v_exp_f32_e32 v227, v227
	v_add_f32_e32 v226, 1.0, v226
	v_add_f32_e32 v227, 1.0, v227
	v_rcp_f32_e32 v226, v226
	v_rcp_f32_e32 v227, v227
	s_nop 0
	v_cvt_pk_bf16_f32 v226, v226, v227
	ds_write_b16 v211, v226 offset:432
	ds_write_b16_d16_hi v211, v226 offset:496
	v_mul_f32_e32 v224, 0xbfb8aa3b, v20
	v_mul_f32_e32 v225, 0xbfb8aa3b, v4
	v_exp_f32_e32 v224, v224
	v_exp_f32_e32 v225, v225
	v_add_f32_e32 v224, 1.0, v224
	v_add_f32_e32 v225, 1.0, v225
	v_rcp_f32_e32 v224, v224
	v_rcp_f32_e32 v225, v225
	s_nop 0
	v_cvt_pk_bf16_f32 v224, v224, v225
	ds_write_b16 v211, v224 offset:1152
	ds_write_b16_d16_hi v211, v224 offset:1216
	v_mul_f32_e32 v226, 0xbfb8aa3b, v21
	v_mul_f32_e32 v227, 0xbfb8aa3b, v5
	v_exp_f32_e32 v226, v226
	v_exp_f32_e32 v227, v227
	v_add_f32_e32 v226, 1.0, v226
	v_add_f32_e32 v227, 1.0, v227
	v_rcp_f32_e32 v226, v226
	v_rcp_f32_e32 v227, v227
	s_nop 0
	v_cvt_pk_bf16_f32 v226, v226, v227
	ds_write_b16 v211, v226 offset:1296
	ds_write_b16_d16_hi v211, v226 offset:1360
	v_mul_f32_e32 v224, 0xbfb8aa3b, v22
	v_mul_f32_e32 v225, 0xbfb8aa3b, v6
	v_exp_f32_e32 v224, v224
	v_exp_f32_e32 v225, v225
	v_add_f32_e32 v224, 1.0, v224
	v_add_f32_e32 v225, 1.0, v225
	v_rcp_f32_e32 v224, v224
	v_rcp_f32_e32 v225, v225
	s_nop 0
	v_cvt_pk_bf16_f32 v224, v224, v225
	ds_write_b16 v211, v224 offset:1440
	ds_write_b16_d16_hi v211, v224 offset:1504
	v_mul_f32_e32 v226, 0xbfb8aa3b, v23
	v_mul_f32_e32 v227, 0xbfb8aa3b, v7
	v_exp_f32_e32 v226, v226
	v_exp_f32_e32 v227, v227
	v_add_f32_e32 v226, 1.0, v226
	v_add_f32_e32 v227, 1.0, v227
	v_rcp_f32_e32 v226, v226
	v_rcp_f32_e32 v227, v227
	s_nop 0
	v_cvt_pk_bf16_f32 v226, v226, v227
	ds_write_b16 v211, v226 offset:1584
	ds_write_b16_d16_hi v211, v226 offset:1648
	v_mul_f32_e32 v224, 0xbfb8aa3b, v24
	v_mul_f32_e32 v225, 0xbfb8aa3b, v8
	v_exp_f32_e32 v224, v224
	v_exp_f32_e32 v225, v225
	v_add_f32_e32 v224, 1.0, v224
	v_add_f32_e32 v225, 1.0, v225
	v_rcp_f32_e32 v224, v224
	v_rcp_f32_e32 v225, v225
	s_nop 0
	v_cvt_pk_bf16_f32 v224, v224, v225
	ds_write_b16 v211, v224 offset:2304
	ds_write_b16_d16_hi v211, v224 offset:2368
	v_mul_f32_e32 v226, 0xbfb8aa3b, v25
	v_mul_f32_e32 v227, 0xbfb8aa3b, v9
	v_exp_f32_e32 v226, v226
	v_exp_f32_e32 v227, v227
	v_add_f32_e32 v226, 1.0, v226
	v_add_f32_e32 v227, 1.0, v227
	v_rcp_f32_e32 v226, v226
	v_rcp_f32_e32 v227, v227
	s_nop 0
	v_cvt_pk_bf16_f32 v226, v226, v227
	ds_write_b16 v211, v226 offset:2448
	ds_write_b16_d16_hi v211, v226 offset:2512
	v_mul_f32_e32 v224, 0xbfb8aa3b, v26
	v_mul_f32_e32 v225, 0xbfb8aa3b, v10
	v_exp_f32_e32 v224, v224
	v_exp_f32_e32 v225, v225
	v_add_f32_e32 v224, 1.0, v224
	v_add_f32_e32 v225, 1.0, v225
	v_rcp_f32_e32 v224, v224
	v_rcp_f32_e32 v225, v225
	s_nop 0
	v_cvt_pk_bf16_f32 v224, v224, v225
	ds_write_b16 v211, v224 offset:2592
	ds_write_b16_d16_hi v211, v224 offset:2656
	v_mul_f32_e32 v226, 0xbfb8aa3b, v27
	v_mul_f32_e32 v227, 0xbfb8aa3b, v11
	v_exp_f32_e32 v226, v226
	v_exp_f32_e32 v227, v227
	v_add_f32_e32 v226, 1.0, v226
	v_add_f32_e32 v227, 1.0, v227
	v_rcp_f32_e32 v226, v226
	v_rcp_f32_e32 v227, v227
	s_nop 0
	v_cvt_pk_bf16_f32 v226, v226, v227
	ds_write_b16 v211, v226 offset:2736
	ds_write_b16_d16_hi v211, v226 offset:2800
	v_mul_f32_e32 v224, 0xbfb8aa3b, v28
	v_mul_f32_e32 v225, 0xbfb8aa3b, v12
	v_exp_f32_e32 v224, v224
	v_exp_f32_e32 v225, v225
	v_add_f32_e32 v224, 1.0, v224
	v_add_f32_e32 v225, 1.0, v225
	v_rcp_f32_e32 v224, v224
	v_rcp_f32_e32 v225, v225
	s_nop 0
	v_cvt_pk_bf16_f32 v224, v224, v225
	ds_write_b16 v211, v224 offset:3456
	ds_write_b16_d16_hi v211, v224 offset:3520
	v_mul_f32_e32 v226, 0xbfb8aa3b, v29
	v_mul_f32_e32 v227, 0xbfb8aa3b, v13
	v_exp_f32_e32 v226, v226
	v_exp_f32_e32 v227, v227
	v_add_f32_e32 v226, 1.0, v226
	v_add_f32_e32 v227, 1.0, v227
	v_rcp_f32_e32 v226, v226
	v_rcp_f32_e32 v227, v227
	s_nop 0
	v_cvt_pk_bf16_f32 v226, v226, v227
	ds_write_b16 v211, v226 offset:3600
	ds_write_b16_d16_hi v211, v226 offset:3664
	v_mul_f32_e32 v224, 0xbfb8aa3b, v30
	v_mul_f32_e32 v225, 0xbfb8aa3b, v14
	v_exp_f32_e32 v224, v224
	v_exp_f32_e32 v225, v225
	v_add_f32_e32 v224, 1.0, v224
	v_add_f32_e32 v225, 1.0, v225
	v_rcp_f32_e32 v224, v224
	v_rcp_f32_e32 v225, v225
	s_nop 0
	v_cvt_pk_bf16_f32 v224, v224, v225
	ds_write_b16 v211, v224 offset:3744
	ds_write_b16_d16_hi v211, v224 offset:3808
	v_mul_f32_e32 v226, 0xbfb8aa3b, v31
	v_mul_f32_e32 v227, 0xbfb8aa3b, v15
	v_exp_f32_e32 v226, v226
	v_exp_f32_e32 v227, v227
	v_add_f32_e32 v226, 1.0, v226
	v_add_f32_e32 v227, 1.0, v227
	v_rcp_f32_e32 v226, v226
	v_rcp_f32_e32 v227, v227
	s_nop 0
	v_cvt_pk_bf16_f32 v226, v226, v227
	ds_write_b16 v211, v226 offset:3888
	ds_write_b16_d16_hi v211, v226 offset:3952
	s_branch .Lep11_11_st
.Lep11_11_mP:
	v_cvt_pk_bf16_f32 v224, v16, v0
	ds_write_b16 v211, v224
	ds_write_b16_d16_hi v211, v224 offset:64
	v_cvt_pk_bf16_f32 v225, v17, v1
	ds_write_b16 v211, v225 offset:144
	ds_write_b16_d16_hi v211, v225 offset:208
	v_cvt_pk_bf16_f32 v226, v18, v2
	ds_write_b16 v211, v226 offset:288
	ds_write_b16_d16_hi v211, v226 offset:352
	v_cvt_pk_bf16_f32 v227, v19, v3
	ds_write_b16 v211, v227 offset:432
	ds_write_b16_d16_hi v211, v227 offset:496
	v_cvt_pk_bf16_f32 v224, v20, v4
	ds_write_b16 v211, v224 offset:1152
	ds_write_b16_d16_hi v211, v224 offset:1216
	v_cvt_pk_bf16_f32 v225, v21, v5
	ds_write_b16 v211, v225 offset:1296
	ds_write_b16_d16_hi v211, v225 offset:1360
	v_cvt_pk_bf16_f32 v226, v22, v6
	ds_write_b16 v211, v226 offset:1440
	ds_write_b16_d16_hi v211, v226 offset:1504
	v_cvt_pk_bf16_f32 v227, v23, v7
	ds_write_b16 v211, v227 offset:1584
	ds_write_b16_d16_hi v211, v227 offset:1648
	v_cvt_pk_bf16_f32 v224, v24, v8
	ds_write_b16 v211, v224 offset:2304
	ds_write_b16_d16_hi v211, v224 offset:2368
	v_cvt_pk_bf16_f32 v225, v25, v9
	ds_write_b16 v211, v225 offset:2448
	ds_write_b16_d16_hi v211, v225 offset:2512
	v_cvt_pk_bf16_f32 v226, v26, v10
	ds_write_b16 v211, v226 offset:2592
	ds_write_b16_d16_hi v211, v226 offset:2656
	v_cvt_pk_bf16_f32 v227, v27, v11
	ds_write_b16 v211, v227 offset:2736
	ds_write_b16_d16_hi v211, v227 offset:2800
	v_cvt_pk_bf16_f32 v224, v28, v12
	ds_write_b16 v211, v224 offset:3456
	ds_write_b16_d16_hi v211, v224 offset:3520
	v_cvt_pk_bf16_f32 v225, v29, v13
	ds_write_b16 v211, v225 offset:3600
	ds_write_b16_d16_hi v211, v225 offset:3664
	v_cvt_pk_bf16_f32 v226, v30, v14
	ds_write_b16 v211, v226 offset:3744
	ds_write_b16_d16_hi v211, v226 offset:3808
	v_cvt_pk_bf16_f32 v227, v31, v15
	ds_write_b16 v211, v227 offset:3888
	ds_write_b16_d16_hi v211, v227 offset:3952
	s_branch .Lep11_11_st
.Lep11_11_mR:
	s_load_dwordx2 s[98:99], s[0:1], 0x148
	v_add_u32_e32 v224, s94, v221
	v_lshlrev_b32_e32 v224, 8, v224
	v_add_u32_e32 v230, v224, v201
	v_mov_b32_e32 v231, 0
	s_waitcnt lgkmcnt(0)
	v_lshl_add_u64 v[230:231], s[98:99], 0, v[230:231]
	global_load_dwordx2 v[128:129], v[230:231], off
	global_load_dwordx2 v[130:131], v[230:231], off offset:256
	global_load_dwordx2 v[132:133], v[230:231], off offset:512
	global_load_dwordx2 v[134:135], v[230:231], off offset:768
	global_load_dwordx2 v[136:137], v[230:231], off offset:2048
	global_load_dwordx2 v[138:139], v[230:231], off offset:2304
	global_load_dwordx2 v[140:141], v[230:231], off offset:2560
	global_load_dwordx2 v[142:143], v[230:231], off offset:2816
	v_add_co_u32_e32 v232, vcc, 0x1000, v230
	s_nop 1
	v_addc_co_u32_e32 v233, vcc, 0, v231, vcc
	global_load_dwordx2 v[144:145], v[232:233], off
	global_load_dwordx2 v[146:147], v[232:233], off offset:256
	global_load_dwordx2 v[148:149], v[232:233], off offset:512
	global_load_dwordx2 v[150:151], v[232:233], off offset:768
	global_load_dwordx2 v[152:153], v[232:233], off offset:2048
	global_load_dwordx2 v[154:155], v[232:233], off offset:2304
	global_load_dwordx2 v[156:157], v[232:233], off offset:2560
	global_load_dwordx2 v[158:159], v[232:233], off offset:2816
	s_waitcnt vmcnt(15)
	v_mul_f32_e32 v224, v0, v129
	v_mul_f32_e32 v225, v16, v129
	v_fma_f32 v224, v16, v128, -v224
	v_fma_f32 v225, v0, v128, v225
	v_mul_f32_e32 v224, s88, v224
	v_mul_f32_e32 v225, s88, v225
	v_cvt_pk_bf16_f32 v224, v224, v225
	ds_write_b16 v211, v224
	ds_write_b16_d16_hi v211, v224 offset:64
	s_waitcnt vmcnt(14)
	v_mul_f32_e32 v224, v1, v131
	v_mul_f32_e32 v225, v17, v131
	v_fma_f32 v224, v17, v130, -v224
	v_fma_f32 v225, v1, v130, v225
	v_mul_f32_e32 v224, s88, v224
	v_mul_f32_e32 v225, s88, v225
	v_cvt_pk_bf16_f32 v224, v224, v225
	ds_write_b16 v211, v224 offset:144
	ds_write_b16_d16_hi v211, v224 offset:208
	s_waitcnt vmcnt(13)
	v_mul_f32_e32 v224, v2, v133
	v_mul_f32_e32 v225, v18, v133
	v_fma_f32 v224, v18, v132, -v224
	v_fma_f32 v225, v2, v132, v225
	v_mul_f32_e32 v224, s88, v224
	v_mul_f32_e32 v225, s88, v225
	v_cvt_pk_bf16_f32 v224, v224, v225
	ds_write_b16 v211, v224 offset:288
	ds_write_b16_d16_hi v211, v224 offset:352
	s_waitcnt vmcnt(12)
	v_mul_f32_e32 v224, v3, v135
	v_mul_f32_e32 v225, v19, v135
	v_fma_f32 v224, v19, v134, -v224
	v_fma_f32 v225, v3, v134, v225
	v_mul_f32_e32 v224, s88, v224
	v_mul_f32_e32 v225, s88, v225
	v_cvt_pk_bf16_f32 v224, v224, v225
	ds_write_b16 v211, v224 offset:432
	ds_write_b16_d16_hi v211, v224 offset:496
	s_waitcnt vmcnt(11)
	v_mul_f32_e32 v224, v4, v137
	v_mul_f32_e32 v225, v20, v137
	v_fma_f32 v224, v20, v136, -v224
	v_fma_f32 v225, v4, v136, v225
	v_mul_f32_e32 v224, s88, v224
	v_mul_f32_e32 v225, s88, v225
	v_cvt_pk_bf16_f32 v224, v224, v225
	ds_write_b16 v211, v224 offset:1152
	ds_write_b16_d16_hi v211, v224 offset:1216
	s_waitcnt vmcnt(10)
	v_mul_f32_e32 v224, v5, v139
	v_mul_f32_e32 v225, v21, v139
	v_fma_f32 v224, v21, v138, -v224
	v_fma_f32 v225, v5, v138, v225
	v_mul_f32_e32 v224, s88, v224
	v_mul_f32_e32 v225, s88, v225
	v_cvt_pk_bf16_f32 v224, v224, v225
	ds_write_b16 v211, v224 offset:1296
	ds_write_b16_d16_hi v211, v224 offset:1360
	s_waitcnt vmcnt(9)
	v_mul_f32_e32 v224, v6, v141
	v_mul_f32_e32 v225, v22, v141
	v_fma_f32 v224, v22, v140, -v224
	v_fma_f32 v225, v6, v140, v225
	v_mul_f32_e32 v224, s88, v224
	v_mul_f32_e32 v225, s88, v225
	v_cvt_pk_bf16_f32 v224, v224, v225
	ds_write_b16 v211, v224 offset:1440
	ds_write_b16_d16_hi v211, v224 offset:1504
	s_waitcnt vmcnt(8)
	v_mul_f32_e32 v224, v7, v143
	v_mul_f32_e32 v225, v23, v143
	v_fma_f32 v224, v23, v142, -v224
	v_fma_f32 v225, v7, v142, v225
	v_mul_f32_e32 v224, s88, v224
	v_mul_f32_e32 v225, s88, v225
	v_cvt_pk_bf16_f32 v224, v224, v225
	ds_write_b16 v211, v224 offset:1584
	ds_write_b16_d16_hi v211, v224 offset:1648
	s_waitcnt vmcnt(7)
	v_mul_f32_e32 v224, v8, v145
	v_mul_f32_e32 v225, v24, v145
	v_fma_f32 v224, v24, v144, -v224
	v_fma_f32 v225, v8, v144, v225
	v_mul_f32_e32 v224, s88, v224
	v_mul_f32_e32 v225, s88, v225
	v_cvt_pk_bf16_f32 v224, v224, v225
	ds_write_b16 v211, v224 offset:2304
	ds_write_b16_d16_hi v211, v224 offset:2368
	s_waitcnt vmcnt(6)
	v_mul_f32_e32 v224, v9, v147
	v_mul_f32_e32 v225, v25, v147
	v_fma_f32 v224, v25, v146, -v224
	v_fma_f32 v225, v9, v146, v225
	v_mul_f32_e32 v224, s88, v224
	v_mul_f32_e32 v225, s88, v225
	v_cvt_pk_bf16_f32 v224, v224, v225
	ds_write_b16 v211, v224 offset:2448
	ds_write_b16_d16_hi v211, v224 offset:2512
	s_waitcnt vmcnt(5)
	v_mul_f32_e32 v224, v10, v149
	v_mul_f32_e32 v225, v26, v149
	v_fma_f32 v224, v26, v148, -v224
	v_fma_f32 v225, v10, v148, v225
	v_mul_f32_e32 v224, s88, v224
	v_mul_f32_e32 v225, s88, v225
	v_cvt_pk_bf16_f32 v224, v224, v225
	ds_write_b16 v211, v224 offset:2592
	ds_write_b16_d16_hi v211, v224 offset:2656
	s_waitcnt vmcnt(4)
	v_mul_f32_e32 v224, v11, v151
	v_mul_f32_e32 v225, v27, v151
	v_fma_f32 v224, v27, v150, -v224
	v_fma_f32 v225, v11, v150, v225
	v_mul_f32_e32 v224, s88, v224
	v_mul_f32_e32 v225, s88, v225
	v_cvt_pk_bf16_f32 v224, v224, v225
	ds_write_b16 v211, v224 offset:2736
	ds_write_b16_d16_hi v211, v224 offset:2800
	s_waitcnt vmcnt(3)
	v_mul_f32_e32 v224, v12, v153
	v_mul_f32_e32 v225, v28, v153
	v_fma_f32 v224, v28, v152, -v224
	v_fma_f32 v225, v12, v152, v225
	v_mul_f32_e32 v224, s88, v224
	v_mul_f32_e32 v225, s88, v225
	v_cvt_pk_bf16_f32 v224, v224, v225
	ds_write_b16 v211, v224 offset:3456
	ds_write_b16_d16_hi v211, v224 offset:3520
	s_waitcnt vmcnt(2)
	v_mul_f32_e32 v224, v13, v155
	v_mul_f32_e32 v225, v29, v155
	v_fma_f32 v224, v29, v154, -v224
	v_fma_f32 v225, v13, v154, v225
	v_mul_f32_e32 v224, s88, v224
	v_mul_f32_e32 v225, s88, v225
	v_cvt_pk_bf16_f32 v224, v224, v225
	ds_write_b16 v211, v224 offset:3600
	ds_write_b16_d16_hi v211, v224 offset:3664
	s_waitcnt vmcnt(1)
	v_mul_f32_e32 v224, v14, v157
	v_mul_f32_e32 v225, v30, v157
	v_fma_f32 v224, v30, v156, -v224
	v_fma_f32 v225, v14, v156, v225
	v_mul_f32_e32 v224, s88, v224
	v_mul_f32_e32 v225, s88, v225
	v_cvt_pk_bf16_f32 v224, v224, v225
	ds_write_b16 v211, v224 offset:3744
	ds_write_b16_d16_hi v211, v224 offset:3808
	s_waitcnt vmcnt(0)
	v_mul_f32_e32 v224, v15, v159
	v_mul_f32_e32 v225, v31, v159
	v_fma_f32 v224, v31, v158, -v224
	v_fma_f32 v225, v15, v158, v225
	v_mul_f32_e32 v224, s88, v224
	v_mul_f32_e32 v225, s88, v225
	v_cvt_pk_bf16_f32 v224, v224, v225
	ds_write_b16 v211, v224 offset:3888
	ds_write_b16_d16_hi v211, v224 offset:3952
	s_branch .Lep11_11_st
.Lep11_11_mS:
	v_mul_f32_e32 v224, 0xbfb8aa3b, v16
	v_mul_f32_e32 v225, 0xbfb8aa3b, v0
	v_exp_f32_e32 v224, v224
	v_exp_f32_e32 v225, v225
	v_add_f32_e32 v224, 1.0, v224
	v_add_f32_e32 v225, 1.0, v225
	v_rcp_f32_e32 v224, v224
	v_rcp_f32_e32 v225, v225
	v_mul_f32_e32 v224, v16, v224
	v_mul_f32_e32 v225, v0, v225
	v_cvt_pk_bf16_f32 v224, v224, v225
	ds_write_b16 v211, v224
	ds_write_b16_d16_hi v211, v224 offset:64
	v_mul_f32_e32 v226, 0xbfb8aa3b, v17
	v_mul_f32_e32 v227, 0xbfb8aa3b, v1
	v_exp_f32_e32 v226, v226
	v_exp_f32_e32 v227, v227
	v_add_f32_e32 v226, 1.0, v226
	v_add_f32_e32 v227, 1.0, v227
	v_rcp_f32_e32 v226, v226
	v_rcp_f32_e32 v227, v227
	v_mul_f32_e32 v226, v17, v226
	v_mul_f32_e32 v227, v1, v227
	v_cvt_pk_bf16_f32 v226, v226, v227
	ds_write_b16 v211, v226 offset:144
	ds_write_b16_d16_hi v211, v226 offset:208
	v_mul_f32_e32 v224, 0xbfb8aa3b, v18
	v_mul_f32_e32 v225, 0xbfb8aa3b, v2
	v_exp_f32_e32 v224, v224
	v_exp_f32_e32 v225, v225
	v_add_f32_e32 v224, 1.0, v224
	v_add_f32_e32 v225, 1.0, v225
	v_rcp_f32_e32 v224, v224
	v_rcp_f32_e32 v225, v225
	v_mul_f32_e32 v224, v18, v224
	v_mul_f32_e32 v225, v2, v225
	v_cvt_pk_bf16_f32 v224, v224, v225
	ds_write_b16 v211, v224 offset:288
	ds_write_b16_d16_hi v211, v224 offset:352
	v_mul_f32_e32 v226, 0xbfb8aa3b, v19
	v_mul_f32_e32 v227, 0xbfb8aa3b, v3
	v_exp_f32_e32 v226, v226
	v_exp_f32_e32 v227, v227
	v_add_f32_e32 v226, 1.0, v226
	v_add_f32_e32 v227, 1.0, v227
	v_rcp_f32_e32 v226, v226
	v_rcp_f32_e32 v227, v227
	v_mul_f32_e32 v226, v19, v226
	v_mul_f32_e32 v227, v3, v227
	v_cvt_pk_bf16_f32 v226, v226, v227
	ds_write_b16 v211, v226 offset:432
	ds_write_b16_d16_hi v211, v226 offset:496
	v_mul_f32_e32 v224, 0xbfb8aa3b, v20
	v_mul_f32_e32 v225, 0xbfb8aa3b, v4
	v_exp_f32_e32 v224, v224
	v_exp_f32_e32 v225, v225
	v_add_f32_e32 v224, 1.0, v224
	v_add_f32_e32 v225, 1.0, v225
	v_rcp_f32_e32 v224, v224
	v_rcp_f32_e32 v225, v225
	v_mul_f32_e32 v224, v20, v224
	v_mul_f32_e32 v225, v4, v225
	v_cvt_pk_bf16_f32 v224, v224, v225
	ds_write_b16 v211, v224 offset:1152
	ds_write_b16_d16_hi v211, v224 offset:1216
	v_mul_f32_e32 v226, 0xbfb8aa3b, v21
	v_mul_f32_e32 v227, 0xbfb8aa3b, v5
	v_exp_f32_e32 v226, v226
	v_exp_f32_e32 v227, v227
	v_add_f32_e32 v226, 1.0, v226
	v_add_f32_e32 v227, 1.0, v227
	v_rcp_f32_e32 v226, v226
	v_rcp_f32_e32 v227, v227
	v_mul_f32_e32 v226, v21, v226
	v_mul_f32_e32 v227, v5, v227
	v_cvt_pk_bf16_f32 v226, v226, v227
	ds_write_b16 v211, v226 offset:1296
	ds_write_b16_d16_hi v211, v226 offset:1360
	v_mul_f32_e32 v224, 0xbfb8aa3b, v22
	v_mul_f32_e32 v225, 0xbfb8aa3b, v6
	v_exp_f32_e32 v224, v224
	v_exp_f32_e32 v225, v225
	v_add_f32_e32 v224, 1.0, v224
	v_add_f32_e32 v225, 1.0, v225
	v_rcp_f32_e32 v224, v224
	v_rcp_f32_e32 v225, v225
	v_mul_f32_e32 v224, v22, v224
	v_mul_f32_e32 v225, v6, v225
	v_cvt_pk_bf16_f32 v224, v224, v225
	ds_write_b16 v211, v224 offset:1440
	ds_write_b16_d16_hi v211, v224 offset:1504
	v_mul_f32_e32 v226, 0xbfb8aa3b, v23
	v_mul_f32_e32 v227, 0xbfb8aa3b, v7
	v_exp_f32_e32 v226, v226
	v_exp_f32_e32 v227, v227
	v_add_f32_e32 v226, 1.0, v226
	v_add_f32_e32 v227, 1.0, v227
	v_rcp_f32_e32 v226, v226
	v_rcp_f32_e32 v227, v227
	v_mul_f32_e32 v226, v23, v226
	v_mul_f32_e32 v227, v7, v227
	v_cvt_pk_bf16_f32 v226, v226, v227
	ds_write_b16 v211, v226 offset:1584
	ds_write_b16_d16_hi v211, v226 offset:1648
	v_mul_f32_e32 v224, 0xbfb8aa3b, v24
	v_mul_f32_e32 v225, 0xbfb8aa3b, v8
	v_exp_f32_e32 v224, v224
	v_exp_f32_e32 v225, v225
	v_add_f32_e32 v224, 1.0, v224
	v_add_f32_e32 v225, 1.0, v225
	v_rcp_f32_e32 v224, v224
	v_rcp_f32_e32 v225, v225
	v_mul_f32_e32 v224, v24, v224
	v_mul_f32_e32 v225, v8, v225
	v_cvt_pk_bf16_f32 v224, v224, v225
	ds_write_b16 v211, v224 offset:2304
	ds_write_b16_d16_hi v211, v224 offset:2368
	v_mul_f32_e32 v226, 0xbfb8aa3b, v25
	v_mul_f32_e32 v227, 0xbfb8aa3b, v9
	v_exp_f32_e32 v226, v226
	v_exp_f32_e32 v227, v227
	v_add_f32_e32 v226, 1.0, v226
	v_add_f32_e32 v227, 1.0, v227
	v_rcp_f32_e32 v226, v226
	v_rcp_f32_e32 v227, v227
	v_mul_f32_e32 v226, v25, v226
	v_mul_f32_e32 v227, v9, v227
	v_cvt_pk_bf16_f32 v226, v226, v227
	ds_write_b16 v211, v226 offset:2448
	ds_write_b16_d16_hi v211, v226 offset:2512
	v_mul_f32_e32 v224, 0xbfb8aa3b, v26
	v_mul_f32_e32 v225, 0xbfb8aa3b, v10
	v_exp_f32_e32 v224, v224
	v_exp_f32_e32 v225, v225
	v_add_f32_e32 v224, 1.0, v224
	v_add_f32_e32 v225, 1.0, v225
	v_rcp_f32_e32 v224, v224
	v_rcp_f32_e32 v225, v225
	v_mul_f32_e32 v224, v26, v224
	v_mul_f32_e32 v225, v10, v225
	v_cvt_pk_bf16_f32 v224, v224, v225
	ds_write_b16 v211, v224 offset:2592
	ds_write_b16_d16_hi v211, v224 offset:2656
	v_mul_f32_e32 v226, 0xbfb8aa3b, v27
	v_mul_f32_e32 v227, 0xbfb8aa3b, v11
	v_exp_f32_e32 v226, v226
	v_exp_f32_e32 v227, v227
	v_add_f32_e32 v226, 1.0, v226
	v_add_f32_e32 v227, 1.0, v227
	v_rcp_f32_e32 v226, v226
	v_rcp_f32_e32 v227, v227
	v_mul_f32_e32 v226, v27, v226
	v_mul_f32_e32 v227, v11, v227
	v_cvt_pk_bf16_f32 v226, v226, v227
	ds_write_b16 v211, v226 offset:2736
	ds_write_b16_d16_hi v211, v226 offset:2800
	v_mul_f32_e32 v224, 0xbfb8aa3b, v28
	v_mul_f32_e32 v225, 0xbfb8aa3b, v12
	v_exp_f32_e32 v224, v224
	v_exp_f32_e32 v225, v225
	v_add_f32_e32 v224, 1.0, v224
	v_add_f32_e32 v225, 1.0, v225
	v_rcp_f32_e32 v224, v224
	v_rcp_f32_e32 v225, v225
	v_mul_f32_e32 v224, v28, v224
	v_mul_f32_e32 v225, v12, v225
	v_cvt_pk_bf16_f32 v224, v224, v225
	ds_write_b16 v211, v224 offset:3456
	ds_write_b16_d16_hi v211, v224 offset:3520
	v_mul_f32_e32 v226, 0xbfb8aa3b, v29
	v_mul_f32_e32 v227, 0xbfb8aa3b, v13
	v_exp_f32_e32 v226, v226
	v_exp_f32_e32 v227, v227
	v_add_f32_e32 v226, 1.0, v226
	v_add_f32_e32 v227, 1.0, v227
	v_rcp_f32_e32 v226, v226
	v_rcp_f32_e32 v227, v227
	v_mul_f32_e32 v226, v29, v226
	v_mul_f32_e32 v227, v13, v227
	v_cvt_pk_bf16_f32 v226, v226, v227
	ds_write_b16 v211, v226 offset:3600
	ds_write_b16_d16_hi v211, v226 offset:3664
	v_mul_f32_e32 v224, 0xbfb8aa3b, v30
	v_mul_f32_e32 v225, 0xbfb8aa3b, v14
	v_exp_f32_e32 v224, v224
	v_exp_f32_e32 v225, v225
	v_add_f32_e32 v224, 1.0, v224
	v_add_f32_e32 v225, 1.0, v225
	v_rcp_f32_e32 v224, v224
	v_rcp_f32_e32 v225, v225
	v_mul_f32_e32 v224, v30, v224
	v_mul_f32_e32 v225, v14, v225
	v_cvt_pk_bf16_f32 v224, v224, v225
	ds_write_b16 v211, v224 offset:3744
	ds_write_b16_d16_hi v211, v224 offset:3808
	v_mul_f32_e32 v226, 0xbfb8aa3b, v31
	v_mul_f32_e32 v227, 0xbfb8aa3b, v15
	v_exp_f32_e32 v226, v226
	v_exp_f32_e32 v227, v227
	v_add_f32_e32 v226, 1.0, v226
	v_add_f32_e32 v227, 1.0, v227
	v_rcp_f32_e32 v226, v226
	v_rcp_f32_e32 v227, v227
	v_mul_f32_e32 v226, v31, v226
	v_mul_f32_e32 v227, v15, v227
	v_cvt_pk_bf16_f32 v226, v226, v227
	ds_write_b16 v211, v226 offset:3888
	ds_write_b16_d16_hi v211, v226 offset:3952
	s_branch .Lep11_11_st

.Lip11_latch:
	s_add_u32 s30, s30, s42
	s_cmpk_lt_u32 s30, 0x780
	s_cbranch_scc1 .Lip11_tile
.Lip11_done:
.LBB0_3853:
	s_cmp_lt_i32 s45, 13
	s_cbranch_scc1 .LBB0_3907
	s_waitcnt vmcnt(0) lgkmcnt(0)
	s_barrier
	v_mbcnt_hi_u32_b32 v0, -1, v210
	v_cmp_eq_u32_e32 vcc, 0, v0
	s_and_b64 s[4:5], s[46:47], vcc
	s_and_saveexec_b64 s[2:3], s[4:5]
	s_cbranch_execz .Lfb11_join
	v_mov_b32_e32 v0, 0x24400
	ds_read_b32 v1, v0
	ds_read_b32 v2, v0 offset:4
	ds_read_b32 v3, v0 offset:8
	s_waitcnt lgkmcnt(0)
	v_readfirstlane_b32 s4, v1
	v_readfirstlane_b32 s5, v2
	v_readfirstlane_b32 s6, v3
	s_add_u32 s7, s6, 1
	v_mov_b32_e32 v4, s7
	ds_write_b32 v0, v4 offset:8
	s_mul_i32 s8, s7, s4
	s_mul_i32 s9, s7, s5
	s_lshl_b32 s10, s23, 7
	s_add_u32 s10, s10, 0x3600
	v_mov_b32_e32 v1, s10
	v_mov_b32_e32 v2, 1
	global_atomic_add v3, v1, v2, s[40:41] sc0
	s_waitcnt vmcnt(0)
	v_readfirstlane_b32 s11, v3
	s_add_u32 s11, s11, 1
	v_mov_b32_e32 v1, 0x3e00
	s_cmp_lg_u32 s11, s8
	s_cbranch_scc1 .Lfb11_spin
	buffer_wbl2 sc1
	s_waitcnt vmcnt(0)
	global_atomic_add v1, v2, s[40:41]
